# MLA loop: V-fragment LDS reads moved behind the per-tile barrier so the 6|4 counted DMA wait is valid (V needs to land one barrier later)
# speedup vs baseline: 1.0056x; 1.0044x over previous
.Lmy_A_entry:
	s_mov_b32 s30, 0x20000
	s_mov_b32 s31, 0
	s_mov_b32 s12, 0x1000
	s_mov_b32 s13, 0
	s_lshr_b32 s71, s24, 1
	s_lshr_b32 s79, s25, 2
	s_add_i32 s79, s79, -1
	s_barrier
	s_mov_b32 s0, 0x60000
	s_mov_b32 s1, 0
	v_lshl_add_u64 v[24:25], v[16:17], 0, s[0:1]
	s_add_u32 m0, s40, 0x9000
	s_mov_b32 s0, 0x3000
	global_load_lds_dwordx4 v[24:25], off
	v_lshl_add_u64 v[30:31], v[222:223], 0, s[0:1]
	s_add_u32 m0, s43, 0x9000
	s_nop 0
	global_load_lds_dwordx4 v[30:31], off
	s_mov_b32 s0, 0x80000
	s_mov_b32 s1, 0
	v_lshl_add_u64 v[24:25], v[16:17], 0, s[0:1]
	s_mov_b32 s0, 0x60000
	v_lshl_add_u64 v[28:29], v[224:225], 0, s[0:1]
	s_mov_b32 s0, 0x4000
	v_lshl_add_u64 v[30:31], v[222:223], 0, s[0:1]
	s_waitcnt lgkmcnt(0)
	v_mfma_f32_32x32x16_bf16 v[82:97], v[218:221], v[4:7], v[66:81]
	v_mfma_f32_32x32x16_bf16 v[98:113], v[214:217], v[4:7], v[66:81]
	v_mfma_f32_32x32x16_bf16 v[82:97], v[210:213], v[8:11], v[82:97]
	v_mfma_f32_32x32x16_bf16 v[98:113], v[206:209], v[8:11], v[98:113]
	v_mfma_f32_32x32x16_bf16 v[82:97], v[202:205], v[12:15], v[82:97]
	v_mfma_f32_32x32x16_bf16 v[98:113], v[198:201], v[12:15], v[98:113]
	v_mfma_f32_32x32x16_bf16 v[82:97], v[194:197], v[130:133], v[82:97]
	v_mfma_f32_32x32x16_bf16 v[98:113], v[190:193], v[130:133], v[98:113]
	v_mfma_f32_32x32x16_bf16 v[82:97], v[186:189], v[134:137], v[82:97]
	v_mfma_f32_32x32x16_bf16 v[98:113], v[182:185], v[134:137], v[98:113]
	v_mfma_f32_32x32x16_bf16 v[82:97], v[178:181], v[138:141], v[82:97]
	v_mfma_f32_32x32x16_bf16 v[98:113], v[174:177], v[138:141], v[98:113]
	v_add_u32_e32 v2, 0x3000, v238
	ds_read_b128 v[218:221], v2
	ds_read_b128 v[214:217], v2 offset:512
	ds_read_b128 v[210:213], v2 offset:2048
	ds_read_b128 v[206:209], v2 offset:2560
	ds_read_b128 v[202:205], v2 offset:4096
	ds_read_b128 v[198:201], v2 offset:4608
	ds_read_b128 v[194:197], v2 offset:6144
	ds_read_b128 v[190:193], v2 offset:6656
	ds_read_b128 v[186:189], v2 offset:8192
	ds_read_b128 v[182:185], v2 offset:8704
	ds_read_b128 v[178:181], v2 offset:10240
	ds_read_b128 v[174:177], v2 offset:10752
	s_nop 7
	v_max3_f32 v19, v82, v83, v84
	v_max3_f32 v26, v85, v86, v87
	v_max3_f32 v19, v19, v88, v89
	v_max3_f32 v26, v26, v90, v91
	v_max3_f32 v19, v19, v92, v93
	v_max3_f32 v26, v26, v94, v95
	v_max3_f32 v19, v19, v96, v97
	v_max3_f32 v26, v26, v98, v99
	v_max3_f32 v19, v19, v100, v101
	v_max3_f32 v26, v26, v102, v103
	v_max3_f32 v19, v19, v104, v105
	v_max3_f32 v26, v26, v106, v107
	v_max3_f32 v19, v19, v108, v109
	v_max3_f32 v26, v26, v110, v111
	v_max3_f32 v19, v19, v112, v113
	v_max_f32_e32 v19, v19, v26
	v_mov_b32_e32 v26, v19
	s_nop 1
	v_permlane32_swap_b32_e32 v19, v26
	v_max_f32_e32 v19, v19, v26
	v_max_f32_e32 v19, v19, v19
	v_mov_b32_e32 v239, v19
	v_xor_b32_e32 v66, 0x80000000, v19
	v_mov_b32_e32 v67, v66
	v_mov_b32_e32 v68, v66
	v_mov_b32_e32 v69, v66
	v_mov_b32_e32 v70, v66
	v_mov_b32_e32 v71, v66
	v_mov_b32_e32 v72, v66
	v_mov_b32_e32 v73, v66
	v_mov_b32_e32 v74, v66
	v_mov_b32_e32 v75, v66
	v_mov_b32_e32 v76, v66
	v_mov_b32_e32 v77, v66
	v_mov_b32_e32 v78, v66
	v_mov_b32_e32 v79, v66
	v_mov_b32_e32 v80, v66
	v_mov_b32_e32 v81, v66
	v_sub_f32_e32 v82, v82, v19
	v_sub_f32_e32 v83, v83, v19
	v_sub_f32_e32 v84, v84, v19
	v_sub_f32_e32 v85, v85, v19
	v_sub_f32_e32 v86, v86, v19
	v_sub_f32_e32 v87, v87, v19
	v_sub_f32_e32 v88, v88, v19
	v_sub_f32_e32 v89, v89, v19
	v_sub_f32_e32 v90, v90, v19
	v_sub_f32_e32 v91, v91, v19
	v_sub_f32_e32 v92, v92, v19
	v_sub_f32_e32 v93, v93, v19
	v_sub_f32_e32 v94, v94, v19
	v_sub_f32_e32 v95, v95, v19
	v_sub_f32_e32 v96, v96, v19
	v_sub_f32_e32 v97, v97, v19
	v_sub_f32_e32 v98, v98, v19
	v_sub_f32_e32 v99, v99, v19
	v_sub_f32_e32 v100, v100, v19
	v_sub_f32_e32 v101, v101, v19
	v_sub_f32_e32 v102, v102, v19
	v_sub_f32_e32 v103, v103, v19
	v_sub_f32_e32 v104, v104, v19
	v_sub_f32_e32 v105, v105, v19
	v_sub_f32_e32 v106, v106, v19
	v_sub_f32_e32 v107, v107, v19
	v_sub_f32_e32 v108, v108, v19
	v_sub_f32_e32 v109, v109, v19
	v_sub_f32_e32 v110, v110, v19
	v_sub_f32_e32 v111, v111, v19
	v_sub_f32_e32 v112, v112, v19
	v_sub_f32_e32 v113, v113, v19
	s_cmp_lt_i32 s79, 1
	s_cbranch_scc1 .Lmy_A_tail
	s_waitcnt lgkmcnt(0)
	v_mov_b32_e32 v2, v237
	v_mfma_f32_32x32x16_bf16 v[142:157], v[218:221], v[4:7], v[66:81]
	v_exp_f32_e32 v82, v82
	v_exp_f32_e32 v83, v83
	v_exp_f32_e32 v84, v84
	v_add_f32_e32 v27, v82, v83
	v_exp_f32_e32 v85, v85
	v_mfma_f32_32x32x16_bf16 v[158:173], v[214:217], v[4:7], v[66:81]
	v_exp_f32_e32 v86, v86
	v_add_f32_e32 v27, v27, v84
	v_exp_f32_e32 v87, v87
	v_add_f32_e32 v27, v27, v85
	v_exp_f32_e32 v88, v88
	v_mfma_f32_32x32x16_bf16 v[142:157], v[210:213], v[8:11], v[142:157]
	v_add_f32_e32 v27, v27, v86
	v_exp_f32_e32 v89, v89
	v_add_f32_e32 v27, v27, v87
	v_add_f32_e32 v27, v27, v88
	v_add_f32_e32 v27, v27, v89
	v_mfma_f32_32x32x16_bf16 v[158:173], v[206:209], v[8:11], v[158:173]
	v_cvt_pk_bf16_f32 v82, v82, v83
	v_cvt_pk_bf16_f32 v83, v84, v85
	v_cvt_pk_bf16_f32 v84, v86, v87
	v_cvt_pk_bf16_f32 v85, v88, v89
	v_mfma_f32_32x32x16_bf16 v[142:157], v[202:205], v[12:15], v[142:157]
	v_exp_f32_e32 v90, v90
	v_exp_f32_e32 v91, v91
	v_exp_f32_e32 v92, v92
	v_add_f32_e32 v27, v27, v90
	v_exp_f32_e32 v93, v93
	v_mfma_f32_32x32x16_bf16 v[158:173], v[198:201], v[12:15], v[158:173]
	v_add_f32_e32 v27, v27, v91
	v_exp_f32_e32 v94, v94
	v_add_f32_e32 v27, v27, v92
	v_exp_f32_e32 v95, v95
	v_add_f32_e32 v27, v27, v93
	s_waitcnt vmcnt(3)
	s_barrier
	v_mfma_f32_32x32x16_bf16 v[142:157], v[194:197], v[130:133], v[142:157]
	s_add_u32 m0, s57, 0x6000
	v_exp_f32_e32 v96, v96
	v_add_f32_e32 v27, v27, v94
	global_load_lds_dwordx4 v[28:29], off
	v_lshl_add_u64 v[28:29], v[28:29], 0, s[30:31]
	v_exp_f32_e32 v97, v97
	v_add_f32_e32 v27, v27, v95
	v_add_f32_e32 v27, v27, v96
	ds_read_b64_tr_b16 v[114:115], v2 offset:49152
	ds_read_b64_tr_b16 v[116:117], v2 offset:49664
	ds_read_b64_tr_b16 v[118:119], v2 offset:50176
	ds_read_b64_tr_b16 v[120:121], v2 offset:50688
	v_mfma_f32_32x32x16_bf16 v[158:173], v[190:193], v[130:133], v[158:173]
	s_add_u32 m0, s40, 0x0
	v_add_f32_e32 v27, v27, v97
	v_cvt_pk_bf16_f32 v90, v90, v91
	global_load_lds_dwordx4 v[24:25], off
	v_lshl_add_u64 v[24:25], v[24:25], 0, s[30:31]
	v_cvt_pk_bf16_f32 v91, v92, v93
	v_cvt_pk_bf16_f32 v92, v94, v95
	v_cvt_pk_bf16_f32 v93, v96, v97
	ds_read_b64_tr_b16 v[122:123], v2 offset:51200
	ds_read_b64_tr_b16 v[124:125], v2 offset:51712
	ds_read_b64_tr_b16 v[126:127], v2 offset:52224
	ds_read_b64_tr_b16 v[128:129], v2 offset:52736
	v_mfma_f32_32x32x16_bf16 v[142:157], v[186:189], v[134:137], v[142:157]
	s_add_u32 m0, s43, 0x0
	v_exp_f32_e32 v98, v98
	v_exp_f32_e32 v99, v99
	global_load_lds_dwordx4 v[30:31], off
	v_lshl_add_u64 v[30:31], v[30:31], 0, s[12:13]
	v_exp_f32_e32 v100, v100
	v_add_f32_e32 v27, v27, v98
	v_exp_f32_e32 v101, v101
	ds_read_b64_tr_b16 v[240:241], v2 offset:53248
	ds_read_b64_tr_b16 v[242:243], v2 offset:53760
	ds_read_b64_tr_b16 v[244:245], v2 offset:54272
	ds_read_b64_tr_b16 v[246:247], v2 offset:54784
	v_mfma_f32_32x32x16_bf16 v[158:173], v[182:185], v[134:137], v[158:173]
	s_add_u32 m0, s40, 0x3000
	v_add_f32_e32 v27, v27, v99
	v_exp_f32_e32 v102, v102
	global_load_lds_dwordx4 v[24:25], off
	v_lshl_add_u64 v[24:25], v[24:25], 0, s[30:31]
	v_add_f32_e32 v27, v27, v100
	v_exp_f32_e32 v103, v103
	v_add_f32_e32 v27, v27, v101
	ds_read_b64_tr_b16 v[248:249], v2 offset:55296
	ds_read_b64_tr_b16 v[250:251], v2 offset:55808
	ds_read_b64_tr_b16 v[20:21], v2 offset:56320
	ds_read_b64_tr_b16 v[22:23], v2 offset:56832
	v_mfma_f32_32x32x16_bf16 v[142:157], v[178:181], v[138:141], v[142:157]
	s_add_u32 m0, s43, 0x3000
	v_exp_f32_e32 v104, v104
	v_add_f32_e32 v27, v27, v102
	global_load_lds_dwordx4 v[30:31], off
	v_lshl_add_u64 v[30:31], v[30:31], 0, s[12:13]
	v_exp_f32_e32 v105, v105
	v_add_f32_e32 v27, v27, v103
	v_add_f32_e32 v27, v27, v104
	v_mfma_f32_32x32x16_bf16 v[158:173], v[174:177], v[138:141], v[158:173]
	v_add_f32_e32 v27, v27, v105
	v_cvt_pk_bf16_f32 v98, v98, v99
	v_cvt_pk_bf16_f32 v99, v100, v101
	v_cvt_pk_bf16_f32 v100, v102, v103
	v_cvt_pk_bf16_f32 v101, v104, v105
	s_waitcnt lgkmcnt(0)
	v_add_u32_e32 v2, 0x6000, v238
	v_mfma_f32_32x32x16_bf16 v[34:49], v[82:85], v[114:117], v[34:49]
	v_exp_f32_e32 v106, v106
	v_exp_f32_e32 v107, v107
	v_exp_f32_e32 v108, v108
	v_add_f32_e32 v27, v27, v106
	v_exp_f32_e32 v109, v109
	ds_read_b128 v[218:221], v2
	ds_read_b128 v[214:217], v2 offset:512
	ds_read_b128 v[210:213], v2 offset:2048
	v_mfma_f32_32x32x16_bf16 v[50:65], v[82:85], v[240:243], v[50:65]
	v_add_f32_e32 v27, v27, v107
	v_exp_f32_e32 v110, v110
	v_add_f32_e32 v27, v27, v108
	v_exp_f32_e32 v111, v111
	v_add_f32_e32 v27, v27, v109
	ds_read_b128 v[206:209], v2 offset:2560
	ds_read_b128 v[202:205], v2 offset:4096
	ds_read_b128 v[198:201], v2 offset:4608
	v_mfma_f32_32x32x16_bf16 v[34:49], v[90:93], v[118:121], v[34:49]
	v_exp_f32_e32 v112, v112
	v_add_f32_e32 v27, v27, v110
	v_exp_f32_e32 v113, v113
	v_add_f32_e32 v27, v27, v111
	v_add_f32_e32 v27, v27, v112
	ds_read_b128 v[194:197], v2 offset:6144
	ds_read_b128 v[190:193], v2 offset:6656
	ds_read_b128 v[186:189], v2 offset:8192
	v_mfma_f32_32x32x16_bf16 v[50:65], v[90:93], v[244:247], v[50:65]
	v_add_f32_e32 v27, v27, v113
	v_cvt_pk_bf16_f32 v106, v106, v107
	v_cvt_pk_bf16_f32 v107, v108, v109
	v_cvt_pk_bf16_f32 v108, v110, v111
	v_cvt_pk_bf16_f32 v109, v112, v113
	v_add_f32_e32 v236, v236, v27
	ds_read_b128 v[182:185], v2 offset:8704
	ds_read_b128 v[178:181], v2 offset:10240
	ds_read_b128 v[174:177], v2 offset:10752
	v_mfma_f32_32x32x16_bf16 v[34:49], v[98:101], v[122:125], v[34:49]
	v_max3_f32 v19, v142, v143, v144
	v_max3_f32 v26, v145, v146, v147
	v_max3_f32 v19, v19, v148, v149
	v_max3_f32 v26, v26, v150, v151
	v_mfma_f32_32x32x16_bf16 v[50:65], v[98:101], v[248:251], v[50:65]
	v_max3_f32 v19, v19, v152, v153
	v_max3_f32 v26, v26, v154, v155
	v_max3_f32 v19, v19, v156, v157
	v_max3_f32 v26, v26, v158, v159
	v_mfma_f32_32x32x16_bf16 v[34:49], v[106:109], v[126:129], v[34:49]
	v_max3_f32 v19, v19, v160, v161
	v_max3_f32 v26, v26, v162, v163
	v_max3_f32 v19, v19, v164, v165
	v_max3_f32 v26, v26, v166, v167
	v_mfma_f32_32x32x16_bf16 v[50:65], v[106:109], v[20:23], v[50:65]
	v_max3_f32 v19, v19, v168, v169
	v_max3_f32 v26, v26, v170, v171
	v_max3_f32 v19, v19, v172, v173
	v_max_f32_e32 v19, v19, v26
	v_cmp_lt_f32_e32 vcc, s41, v19
	s_cbranch_vccz .Lmy_nors_1
	s_nop 15
	s_nop 15
	v_mov_b32_e32 v26, v19
	s_nop 1
	v_permlane32_swap_b32_e32 v19, v26
	v_max_f32_e32 v19, v19, v26
	v_max_f32_e32 v19, v19, v19
	v_max_f32_e32 v90, 0, v19
	v_exp_f32_e64 v91, -v90
	v_add_f32_e32 v239, v239, v90
	v_xor_b32_e32 v66, 0x80000000, v239
	v_mov_b32_e32 v67, v66
	v_mov_b32_e32 v68, v66
	v_mov_b32_e32 v69, v66
	v_mov_b32_e32 v70, v66
	v_mov_b32_e32 v71, v66
	v_mov_b32_e32 v72, v66
	v_mov_b32_e32 v73, v66
	v_mov_b32_e32 v74, v66
	v_mov_b32_e32 v75, v66
	v_mov_b32_e32 v76, v66
	v_mov_b32_e32 v77, v66
	v_mov_b32_e32 v78, v66
	v_mov_b32_e32 v79, v66
	v_mov_b32_e32 v80, v66
	v_mov_b32_e32 v81, v66
	v_sub_f32_e32 v142, v142, v90
	v_sub_f32_e32 v143, v143, v90
	v_sub_f32_e32 v144, v144, v90
	v_sub_f32_e32 v145, v145, v90
	v_sub_f32_e32 v146, v146, v90
	v_sub_f32_e32 v147, v147, v90
	v_sub_f32_e32 v148, v148, v90
	v_sub_f32_e32 v149, v149, v90
	v_sub_f32_e32 v150, v150, v90
	v_sub_f32_e32 v151, v151, v90
	v_sub_f32_e32 v152, v152, v90
	v_sub_f32_e32 v153, v153, v90
	v_sub_f32_e32 v154, v154, v90
	v_sub_f32_e32 v155, v155, v90
	v_sub_f32_e32 v156, v156, v90
	v_sub_f32_e32 v157, v157, v90
	v_sub_f32_e32 v158, v158, v90
	v_sub_f32_e32 v159, v159, v90
	v_sub_f32_e32 v160, v160, v90
	v_sub_f32_e32 v161, v161, v90
	v_sub_f32_e32 v162, v162, v90
	v_sub_f32_e32 v163, v163, v90
	v_sub_f32_e32 v164, v164, v90
	v_sub_f32_e32 v165, v165, v90
	v_sub_f32_e32 v166, v166, v90
	v_sub_f32_e32 v167, v167, v90
	v_sub_f32_e32 v168, v168, v90
	v_sub_f32_e32 v169, v169, v90
	v_sub_f32_e32 v170, v170, v90
	v_sub_f32_e32 v171, v171, v90
	v_sub_f32_e32 v172, v172, v90
	v_sub_f32_e32 v173, v173, v90
	v_mul_f32_e32 v236, v236, v91
	s_mov_b64 s[96:97], exec
	s_and_b64 exec, exec, s[8:9]
	ds_write_b32 v235, v91
	s_mov_b64 exec, s[96:97]
	v_lshl_add_u32 v2, v228, 4, s47
	ds_read_b128 v[94:97], v2 offset:0
	s_waitcnt lgkmcnt(0)
	v_mul_f32_e32 v34, v34, v94
	v_mul_f32_e32 v50, v50, v94
	v_mul_f32_e32 v35, v35, v95
	v_mul_f32_e32 v51, v51, v95
	v_mul_f32_e32 v36, v36, v96
	v_mul_f32_e32 v52, v52, v96
	v_mul_f32_e32 v37, v37, v97
	v_mul_f32_e32 v53, v53, v97
	ds_read_b128 v[94:97], v2 offset:32
	s_waitcnt lgkmcnt(0)
	v_mul_f32_e32 v38, v38, v94
	v_mul_f32_e32 v54, v54, v94
	v_mul_f32_e32 v39, v39, v95
	v_mul_f32_e32 v55, v55, v95
	v_mul_f32_e32 v40, v40, v96
	v_mul_f32_e32 v56, v56, v96
	v_mul_f32_e32 v41, v41, v97
	v_mul_f32_e32 v57, v57, v97
	ds_read_b128 v[94:97], v2 offset:64
	s_waitcnt lgkmcnt(0)
	v_mul_f32_e32 v42, v42, v94
	v_mul_f32_e32 v58, v58, v94
	v_mul_f32_e32 v43, v43, v95
	v_mul_f32_e32 v59, v59, v95
	v_mul_f32_e32 v44, v44, v96
	v_mul_f32_e32 v60, v60, v96
	v_mul_f32_e32 v45, v45, v97
	v_mul_f32_e32 v61, v61, v97
	ds_read_b128 v[94:97], v2 offset:96
	s_waitcnt lgkmcnt(0)
	v_mul_f32_e32 v46, v46, v94
	v_mul_f32_e32 v62, v62, v94
	v_mul_f32_e32 v47, v47, v95
	v_mul_f32_e32 v63, v63, v95
	v_mul_f32_e32 v48, v48, v96
	v_mul_f32_e32 v64, v64, v96
	v_mul_f32_e32 v49, v49, v97
	v_mul_f32_e32 v65, v65, v97
.Lmy_nors_1:
	s_waitcnt lgkmcnt(0)
	v_add_u32_e32 v2, 0x2000, v237
	v_mfma_f32_32x32x16_bf16 v[82:97], v[218:221], v[4:7], v[66:81]
	v_exp_f32_e32 v142, v142
	v_exp_f32_e32 v143, v143
	v_exp_f32_e32 v144, v144
	v_add_f32_e32 v27, v142, v143
	v_exp_f32_e32 v145, v145
	v_mfma_f32_32x32x16_bf16 v[98:113], v[214:217], v[4:7], v[66:81]
	v_exp_f32_e32 v146, v146
	v_add_f32_e32 v27, v27, v144
	v_exp_f32_e32 v147, v147
	v_add_f32_e32 v27, v27, v145
	v_exp_f32_e32 v148, v148
	v_mfma_f32_32x32x16_bf16 v[82:97], v[210:213], v[8:11], v[82:97]
	v_add_f32_e32 v27, v27, v146
	v_exp_f32_e32 v149, v149
	v_add_f32_e32 v27, v27, v147
	v_add_f32_e32 v27, v27, v148
	v_add_f32_e32 v27, v27, v149
	v_mfma_f32_32x32x16_bf16 v[98:113], v[206:209], v[8:11], v[98:113]
	v_cvt_pk_bf16_f32 v142, v142, v143
	v_cvt_pk_bf16_f32 v143, v144, v145
	v_cvt_pk_bf16_f32 v144, v146, v147
	v_cvt_pk_bf16_f32 v145, v148, v149
	v_mfma_f32_32x32x16_bf16 v[82:97], v[202:205], v[12:15], v[82:97]
	v_exp_f32_e32 v150, v150
	v_exp_f32_e32 v151, v151
	v_exp_f32_e32 v152, v152
	v_add_f32_e32 v27, v27, v150
	v_exp_f32_e32 v153, v153
	v_mfma_f32_32x32x16_bf16 v[98:113], v[198:201], v[12:15], v[98:113]
	v_add_f32_e32 v27, v27, v151
	v_exp_f32_e32 v154, v154
	v_add_f32_e32 v27, v27, v152
	v_exp_f32_e32 v155, v155
	v_add_f32_e32 v27, v27, v153
	s_waitcnt vmcnt(5)
	s_barrier
	v_mfma_f32_32x32x16_bf16 v[82:97], v[194:197], v[130:133], v[82:97]
	s_add_u32 m0, s57, 0x0
	v_exp_f32_e32 v156, v156
	v_add_f32_e32 v27, v27, v154
	global_load_lds_dwordx4 v[28:29], off
	v_lshl_add_u64 v[28:29], v[28:29], 0, s[30:31]
	v_exp_f32_e32 v157, v157
	v_add_f32_e32 v27, v27, v155
	v_add_f32_e32 v27, v27, v156
	ds_read_b64_tr_b16 v[114:115], v2 offset:49152
	ds_read_b64_tr_b16 v[116:117], v2 offset:49664
	ds_read_b64_tr_b16 v[118:119], v2 offset:50176
	ds_read_b64_tr_b16 v[120:121], v2 offset:50688
	v_mfma_f32_32x32x16_bf16 v[98:113], v[190:193], v[130:133], v[98:113]
	s_add_u32 m0, s40, 0x6000
	v_add_f32_e32 v27, v27, v157
	v_cvt_pk_bf16_f32 v150, v150, v151
	global_load_lds_dwordx4 v[24:25], off
	v_lshl_add_u64 v[24:25], v[24:25], 0, s[30:31]
	v_cvt_pk_bf16_f32 v151, v152, v153
	v_cvt_pk_bf16_f32 v152, v154, v155
	v_cvt_pk_bf16_f32 v153, v156, v157
	ds_read_b64_tr_b16 v[122:123], v2 offset:51200
	ds_read_b64_tr_b16 v[124:125], v2 offset:51712
	ds_read_b64_tr_b16 v[126:127], v2 offset:52224
	ds_read_b64_tr_b16 v[128:129], v2 offset:52736
	v_mfma_f32_32x32x16_bf16 v[82:97], v[186:189], v[134:137], v[82:97]
	s_add_u32 m0, s43, 0x6000
	v_exp_f32_e32 v158, v158
	v_exp_f32_e32 v159, v159
	global_load_lds_dwordx4 v[30:31], off
	v_lshl_add_u64 v[30:31], v[30:31], 0, s[12:13]
	v_exp_f32_e32 v160, v160
	v_add_f32_e32 v27, v27, v158
	v_exp_f32_e32 v161, v161
	ds_read_b64_tr_b16 v[240:241], v2 offset:53248
	ds_read_b64_tr_b16 v[242:243], v2 offset:53760
	ds_read_b64_tr_b16 v[244:245], v2 offset:54272
	ds_read_b64_tr_b16 v[246:247], v2 offset:54784
	v_mfma_f32_32x32x16_bf16 v[98:113], v[182:185], v[134:137], v[98:113]
	v_add_f32_e32 v27, v27, v159
	v_exp_f32_e32 v162, v162
	v_add_f32_e32 v27, v27, v160
	v_exp_f32_e32 v163, v163
	v_add_f32_e32 v27, v27, v161
	ds_read_b64_tr_b16 v[248:249], v2 offset:55296
	ds_read_b64_tr_b16 v[250:251], v2 offset:55808
	ds_read_b64_tr_b16 v[20:21], v2 offset:56320
	ds_read_b64_tr_b16 v[22:23], v2 offset:56832
	v_mfma_f32_32x32x16_bf16 v[82:97], v[178:181], v[138:141], v[82:97]
	v_exp_f32_e32 v164, v164
	v_add_f32_e32 v27, v27, v162
	v_exp_f32_e32 v165, v165
	v_add_f32_e32 v27, v27, v163
	v_add_f32_e32 v27, v27, v164
	v_mfma_f32_32x32x16_bf16 v[98:113], v[174:177], v[138:141], v[98:113]
	v_add_f32_e32 v27, v27, v165
	v_cvt_pk_bf16_f32 v158, v158, v159
	v_cvt_pk_bf16_f32 v159, v160, v161
	v_cvt_pk_bf16_f32 v160, v162, v163
	v_cvt_pk_bf16_f32 v161, v164, v165
	s_waitcnt lgkmcnt(0)
	v_add_u32_e32 v2, 0x9000, v238
	v_mfma_f32_32x32x16_bf16 v[34:49], v[142:145], v[114:117], v[34:49]
	v_exp_f32_e32 v166, v166
	v_exp_f32_e32 v167, v167
	v_exp_f32_e32 v168, v168
	v_add_f32_e32 v27, v27, v166
	v_exp_f32_e32 v169, v169
	ds_read_b128 v[218:221], v2
	ds_read_b128 v[214:217], v2 offset:512
	ds_read_b128 v[210:213], v2 offset:2048
	v_mfma_f32_32x32x16_bf16 v[50:65], v[142:145], v[240:243], v[50:65]
	v_add_f32_e32 v27, v27, v167
	v_exp_f32_e32 v170, v170
	v_add_f32_e32 v27, v27, v168
	v_exp_f32_e32 v171, v171
	v_add_f32_e32 v27, v27, v169
	ds_read_b128 v[206:209], v2 offset:2560
	ds_read_b128 v[202:205], v2 offset:4096
	ds_read_b128 v[198:201], v2 offset:4608
	v_mfma_f32_32x32x16_bf16 v[34:49], v[150:153], v[118:121], v[34:49]
	v_exp_f32_e32 v172, v172
	v_add_f32_e32 v27, v27, v170
	v_exp_f32_e32 v173, v173
	v_add_f32_e32 v27, v27, v171
	v_add_f32_e32 v27, v27, v172
	ds_read_b128 v[194:197], v2 offset:6144
	ds_read_b128 v[190:193], v2 offset:6656
	ds_read_b128 v[186:189], v2 offset:8192
	v_mfma_f32_32x32x16_bf16 v[50:65], v[150:153], v[244:247], v[50:65]
	v_add_f32_e32 v27, v27, v173
	v_cvt_pk_bf16_f32 v166, v166, v167
	v_cvt_pk_bf16_f32 v167, v168, v169
	v_cvt_pk_bf16_f32 v168, v170, v171
	v_cvt_pk_bf16_f32 v169, v172, v173
	v_add_f32_e32 v236, v236, v27
	ds_read_b128 v[182:185], v2 offset:8704
	ds_read_b128 v[178:181], v2 offset:10240
	ds_read_b128 v[174:177], v2 offset:10752
	v_mfma_f32_32x32x16_bf16 v[34:49], v[158:161], v[122:125], v[34:49]
	v_max3_f32 v19, v82, v83, v84
	v_max3_f32 v26, v85, v86, v87
	v_max3_f32 v19, v19, v88, v89
	v_max3_f32 v26, v26, v90, v91
	v_mfma_f32_32x32x16_bf16 v[50:65], v[158:161], v[248:251], v[50:65]
	v_max3_f32 v19, v19, v92, v93
	v_max3_f32 v26, v26, v94, v95
	v_max3_f32 v19, v19, v96, v97
	v_max3_f32 v26, v26, v98, v99
	v_mfma_f32_32x32x16_bf16 v[34:49], v[166:169], v[126:129], v[34:49]
	v_max3_f32 v19, v19, v100, v101
	v_max3_f32 v26, v26, v102, v103
	v_max3_f32 v19, v19, v104, v105
	v_max3_f32 v26, v26, v106, v107
	v_mfma_f32_32x32x16_bf16 v[50:65], v[166:169], v[20:23], v[50:65]
	v_max3_f32 v19, v19, v108, v109
	v_max3_f32 v26, v26, v110, v111
	v_max3_f32 v19, v19, v112, v113
	v_max_f32_e32 v19, v19, v26
	v_cmp_lt_f32_e32 vcc, s41, v19
	s_cbranch_vccz .Lmy_nors_2
	s_nop 15
	s_nop 15
	v_mov_b32_e32 v26, v19
	s_nop 1
	v_permlane32_swap_b32_e32 v19, v26
	v_max_f32_e32 v19, v19, v26
	v_max_f32_e32 v19, v19, v19
	v_max_f32_e32 v150, 0, v19
	v_exp_f32_e64 v151, -v150
	v_add_f32_e32 v239, v239, v150
	v_xor_b32_e32 v66, 0x80000000, v239
	v_mov_b32_e32 v67, v66
	v_mov_b32_e32 v68, v66
	v_mov_b32_e32 v69, v66
	v_mov_b32_e32 v70, v66
	v_mov_b32_e32 v71, v66
	v_mov_b32_e32 v72, v66
	v_mov_b32_e32 v73, v66
	v_mov_b32_e32 v74, v66
	v_mov_b32_e32 v75, v66
	v_mov_b32_e32 v76, v66
	v_mov_b32_e32 v77, v66
	v_mov_b32_e32 v78, v66
	v_mov_b32_e32 v79, v66
	v_mov_b32_e32 v80, v66
	v_mov_b32_e32 v81, v66
	v_sub_f32_e32 v82, v82, v150
	v_sub_f32_e32 v83, v83, v150
	v_sub_f32_e32 v84, v84, v150
	v_sub_f32_e32 v85, v85, v150
	v_sub_f32_e32 v86, v86, v150
	v_sub_f32_e32 v87, v87, v150
	v_sub_f32_e32 v88, v88, v150
	v_sub_f32_e32 v89, v89, v150
	v_sub_f32_e32 v90, v90, v150
	v_sub_f32_e32 v91, v91, v150
	v_sub_f32_e32 v92, v92, v150
	v_sub_f32_e32 v93, v93, v150
	v_sub_f32_e32 v94, v94, v150
	v_sub_f32_e32 v95, v95, v150
	v_sub_f32_e32 v96, v96, v150
	v_sub_f32_e32 v97, v97, v150
	v_sub_f32_e32 v98, v98, v150
	v_sub_f32_e32 v99, v99, v150
	v_sub_f32_e32 v100, v100, v150
	v_sub_f32_e32 v101, v101, v150
	v_sub_f32_e32 v102, v102, v150
	v_sub_f32_e32 v103, v103, v150
	v_sub_f32_e32 v104, v104, v150
	v_sub_f32_e32 v105, v105, v150
	v_sub_f32_e32 v106, v106, v150
	v_sub_f32_e32 v107, v107, v150
	v_sub_f32_e32 v108, v108, v150
	v_sub_f32_e32 v109, v109, v150
	v_sub_f32_e32 v110, v110, v150
	v_sub_f32_e32 v111, v111, v150
	v_sub_f32_e32 v112, v112, v150
	v_sub_f32_e32 v113, v113, v150
	v_mul_f32_e32 v236, v236, v151
	s_mov_b64 s[96:97], exec
	s_and_b64 exec, exec, s[8:9]
	ds_write_b32 v235, v151
	s_mov_b64 exec, s[96:97]
	v_lshl_add_u32 v2, v228, 4, s47
	ds_read_b128 v[154:157], v2 offset:0
	s_waitcnt lgkmcnt(0)
	v_mul_f32_e32 v34, v34, v154
	v_mul_f32_e32 v50, v50, v154
	v_mul_f32_e32 v35, v35, v155
	v_mul_f32_e32 v51, v51, v155
	v_mul_f32_e32 v36, v36, v156
	v_mul_f32_e32 v52, v52, v156
	v_mul_f32_e32 v37, v37, v157
	v_mul_f32_e32 v53, v53, v157
	ds_read_b128 v[154:157], v2 offset:32
	s_waitcnt lgkmcnt(0)
	v_mul_f32_e32 v38, v38, v154
	v_mul_f32_e32 v54, v54, v154
	v_mul_f32_e32 v39, v39, v155
	v_mul_f32_e32 v55, v55, v155
	v_mul_f32_e32 v40, v40, v156
	v_mul_f32_e32 v56, v56, v156
	v_mul_f32_e32 v41, v41, v157
	v_mul_f32_e32 v57, v57, v157
	ds_read_b128 v[154:157], v2 offset:64
	s_waitcnt lgkmcnt(0)
	v_mul_f32_e32 v42, v42, v154
	v_mul_f32_e32 v58, v58, v154
	v_mul_f32_e32 v43, v43, v155
	v_mul_f32_e32 v59, v59, v155
	v_mul_f32_e32 v44, v44, v156
	v_mul_f32_e32 v60, v60, v156
	v_mul_f32_e32 v45, v45, v157
	v_mul_f32_e32 v61, v61, v157
	ds_read_b128 v[154:157], v2 offset:96
	s_waitcnt lgkmcnt(0)
	v_mul_f32_e32 v46, v46, v154
	v_mul_f32_e32 v62, v62, v154
	v_mul_f32_e32 v47, v47, v155
	v_mul_f32_e32 v63, v63, v155
	v_mul_f32_e32 v48, v48, v156
	v_mul_f32_e32 v64, v64, v156
	v_mul_f32_e32 v49, v49, v157
	v_mul_f32_e32 v65, v65, v157
.Lmy_nors_2:
	s_waitcnt lgkmcnt(0)
	v_add_u32_e32 v2, 0x4000, v237
	v_mfma_f32_32x32x16_bf16 v[142:157], v[218:221], v[4:7], v[66:81]
	v_exp_f32_e32 v82, v82
	v_exp_f32_e32 v83, v83
	v_exp_f32_e32 v84, v84
	v_add_f32_e32 v27, v82, v83
	v_exp_f32_e32 v85, v85
	v_mfma_f32_32x32x16_bf16 v[158:173], v[214:217], v[4:7], v[66:81]
	v_exp_f32_e32 v86, v86
	v_add_f32_e32 v27, v27, v84
	v_exp_f32_e32 v87, v87
	v_add_f32_e32 v27, v27, v85
	v_exp_f32_e32 v88, v88
	v_mfma_f32_32x32x16_bf16 v[142:157], v[210:213], v[8:11], v[142:157]
	v_add_f32_e32 v27, v27, v86
	v_exp_f32_e32 v89, v89
	v_add_f32_e32 v27, v27, v87
	v_add_f32_e32 v27, v27, v88
	v_add_f32_e32 v27, v27, v89
	v_mfma_f32_32x32x16_bf16 v[158:173], v[206:209], v[8:11], v[158:173]
	v_cvt_pk_bf16_f32 v82, v82, v83
	v_cvt_pk_bf16_f32 v83, v84, v85
	v_cvt_pk_bf16_f32 v84, v86, v87
	v_cvt_pk_bf16_f32 v85, v88, v89
	v_mfma_f32_32x32x16_bf16 v[142:157], v[202:205], v[12:15], v[142:157]
	v_exp_f32_e32 v90, v90
	v_exp_f32_e32 v91, v91
	v_exp_f32_e32 v92, v92
	v_add_f32_e32 v27, v27, v90
	v_exp_f32_e32 v93, v93
	v_mfma_f32_32x32x16_bf16 v[158:173], v[198:201], v[12:15], v[158:173]
	v_add_f32_e32 v27, v27, v91
	v_exp_f32_e32 v94, v94
	v_add_f32_e32 v27, v27, v92
	v_exp_f32_e32 v95, v95
	v_add_f32_e32 v27, v27, v93
	s_waitcnt vmcnt(5)
	s_barrier
	v_mfma_f32_32x32x16_bf16 v[142:157], v[194:197], v[130:133], v[142:157]
	s_add_u32 m0, s57, 0x2000
	v_exp_f32_e32 v96, v96
	v_add_f32_e32 v27, v27, v94
	global_load_lds_dwordx4 v[28:29], off
	v_lshl_add_u64 v[28:29], v[28:29], 0, s[30:31]
	v_exp_f32_e32 v97, v97
	v_add_f32_e32 v27, v27, v95
	v_add_f32_e32 v27, v27, v96
	ds_read_b64_tr_b16 v[114:115], v2 offset:49152
	ds_read_b64_tr_b16 v[116:117], v2 offset:49664
	ds_read_b64_tr_b16 v[118:119], v2 offset:50176
	ds_read_b64_tr_b16 v[120:121], v2 offset:50688
	v_mfma_f32_32x32x16_bf16 v[158:173], v[190:193], v[130:133], v[158:173]
	s_add_u32 m0, s40, 0x9000
	v_add_f32_e32 v27, v27, v97
	v_cvt_pk_bf16_f32 v90, v90, v91
	global_load_lds_dwordx4 v[24:25], off
	v_lshl_add_u64 v[24:25], v[24:25], 0, s[30:31]
	v_cvt_pk_bf16_f32 v91, v92, v93
	v_cvt_pk_bf16_f32 v92, v94, v95
	v_cvt_pk_bf16_f32 v93, v96, v97
	ds_read_b64_tr_b16 v[122:123], v2 offset:51200
	ds_read_b64_tr_b16 v[124:125], v2 offset:51712
	ds_read_b64_tr_b16 v[126:127], v2 offset:52224
	ds_read_b64_tr_b16 v[128:129], v2 offset:52736
	v_mfma_f32_32x32x16_bf16 v[142:157], v[186:189], v[134:137], v[142:157]
	s_add_u32 m0, s43, 0x9000
	v_exp_f32_e32 v98, v98
	v_exp_f32_e32 v99, v99
	global_load_lds_dwordx4 v[30:31], off
	v_lshl_add_u64 v[30:31], v[30:31], 0, s[12:13]
	v_exp_f32_e32 v100, v100
	v_add_f32_e32 v27, v27, v98
	v_exp_f32_e32 v101, v101
	ds_read_b64_tr_b16 v[240:241], v2 offset:53248
	ds_read_b64_tr_b16 v[242:243], v2 offset:53760
	ds_read_b64_tr_b16 v[244:245], v2 offset:54272
	ds_read_b64_tr_b16 v[246:247], v2 offset:54784
	v_mfma_f32_32x32x16_bf16 v[158:173], v[182:185], v[134:137], v[158:173]
	v_add_f32_e32 v27, v27, v99
	v_exp_f32_e32 v102, v102
	v_add_f32_e32 v27, v27, v100
	v_exp_f32_e32 v103, v103
	v_add_f32_e32 v27, v27, v101
	ds_read_b64_tr_b16 v[248:249], v2 offset:55296
	ds_read_b64_tr_b16 v[250:251], v2 offset:55808
	ds_read_b64_tr_b16 v[20:21], v2 offset:56320
	ds_read_b64_tr_b16 v[22:23], v2 offset:56832
	v_mfma_f32_32x32x16_bf16 v[142:157], v[178:181], v[138:141], v[142:157]
	v_exp_f32_e32 v104, v104
	v_add_f32_e32 v27, v27, v102
	v_exp_f32_e32 v105, v105
	v_add_f32_e32 v27, v27, v103
	v_add_f32_e32 v27, v27, v104
	v_mfma_f32_32x32x16_bf16 v[158:173], v[174:177], v[138:141], v[158:173]
	v_add_f32_e32 v27, v27, v105
	v_cvt_pk_bf16_f32 v98, v98, v99
	v_cvt_pk_bf16_f32 v99, v100, v101
	v_cvt_pk_bf16_f32 v100, v102, v103
	v_cvt_pk_bf16_f32 v101, v104, v105
	s_waitcnt lgkmcnt(0)
	v_mov_b32_e32 v2, v238
	v_mfma_f32_32x32x16_bf16 v[34:49], v[82:85], v[114:117], v[34:49]
	v_exp_f32_e32 v106, v106
	v_exp_f32_e32 v107, v107
	v_exp_f32_e32 v108, v108
	v_add_f32_e32 v27, v27, v106
	v_exp_f32_e32 v109, v109
	ds_read_b128 v[218:221], v2
	ds_read_b128 v[214:217], v2 offset:512
	ds_read_b128 v[210:213], v2 offset:2048
	v_mfma_f32_32x32x16_bf16 v[50:65], v[82:85], v[240:243], v[50:65]
	v_add_f32_e32 v27, v27, v107
	v_exp_f32_e32 v110, v110
	v_add_f32_e32 v27, v27, v108
	v_exp_f32_e32 v111, v111
	v_add_f32_e32 v27, v27, v109
	ds_read_b128 v[206:209], v2 offset:2560
	ds_read_b128 v[202:205], v2 offset:4096
	ds_read_b128 v[198:201], v2 offset:4608
	v_mfma_f32_32x32x16_bf16 v[34:49], v[90:93], v[118:121], v[34:49]
	v_exp_f32_e32 v112, v112
	v_add_f32_e32 v27, v27, v110
	v_exp_f32_e32 v113, v113
	v_add_f32_e32 v27, v27, v111
	v_add_f32_e32 v27, v27, v112
	ds_read_b128 v[194:197], v2 offset:6144
	ds_read_b128 v[190:193], v2 offset:6656
	ds_read_b128 v[186:189], v2 offset:8192
	v_mfma_f32_32x32x16_bf16 v[50:65], v[90:93], v[244:247], v[50:65]
	v_add_f32_e32 v27, v27, v113
	v_cvt_pk_bf16_f32 v106, v106, v107
	v_cvt_pk_bf16_f32 v107, v108, v109
	v_cvt_pk_bf16_f32 v108, v110, v111
	v_cvt_pk_bf16_f32 v109, v112, v113
	v_add_f32_e32 v236, v236, v27
	ds_read_b128 v[182:185], v2 offset:8704
	ds_read_b128 v[178:181], v2 offset:10240
	ds_read_b128 v[174:177], v2 offset:10752
	v_mfma_f32_32x32x16_bf16 v[34:49], v[98:101], v[122:125], v[34:49]
	v_max3_f32 v19, v142, v143, v144
	v_max3_f32 v26, v145, v146, v147
	v_max3_f32 v19, v19, v148, v149
	v_max3_f32 v26, v26, v150, v151
	v_mfma_f32_32x32x16_bf16 v[50:65], v[98:101], v[248:251], v[50:65]
	v_max3_f32 v19, v19, v152, v153
	v_max3_f32 v26, v26, v154, v155
	v_max3_f32 v19, v19, v156, v157
	v_max3_f32 v26, v26, v158, v159
	v_mfma_f32_32x32x16_bf16 v[34:49], v[106:109], v[126:129], v[34:49]
	v_max3_f32 v19, v19, v160, v161
	v_max3_f32 v26, v26, v162, v163
	v_max3_f32 v19, v19, v164, v165
	v_max3_f32 v26, v26, v166, v167
	v_mfma_f32_32x32x16_bf16 v[50:65], v[106:109], v[20:23], v[50:65]
	v_max3_f32 v19, v19, v168, v169
	v_max3_f32 v26, v26, v170, v171
	v_max3_f32 v19, v19, v172, v173
	v_max_f32_e32 v19, v19, v26
	v_cmp_lt_f32_e32 vcc, s41, v19
	s_cbranch_vccz .Lmy_nors_3
	s_nop 15
	s_nop 15
	v_mov_b32_e32 v26, v19
	s_nop 1
	v_permlane32_swap_b32_e32 v19, v26
	v_max_f32_e32 v19, v19, v26
	v_max_f32_e32 v19, v19, v19
	v_max_f32_e32 v90, 0, v19
	v_exp_f32_e64 v91, -v90
	v_add_f32_e32 v239, v239, v90
	v_xor_b32_e32 v66, 0x80000000, v239
	v_mov_b32_e32 v67, v66
	v_mov_b32_e32 v68, v66
	v_mov_b32_e32 v69, v66
	v_mov_b32_e32 v70, v66
	v_mov_b32_e32 v71, v66
	v_mov_b32_e32 v72, v66
	v_mov_b32_e32 v73, v66
	v_mov_b32_e32 v74, v66
	v_mov_b32_e32 v75, v66
	v_mov_b32_e32 v76, v66
	v_mov_b32_e32 v77, v66
	v_mov_b32_e32 v78, v66
	v_mov_b32_e32 v79, v66
	v_mov_b32_e32 v80, v66
	v_mov_b32_e32 v81, v66
	v_sub_f32_e32 v142, v142, v90
	v_sub_f32_e32 v143, v143, v90
	v_sub_f32_e32 v144, v144, v90
	v_sub_f32_e32 v145, v145, v90
	v_sub_f32_e32 v146, v146, v90
	v_sub_f32_e32 v147, v147, v90
	v_sub_f32_e32 v148, v148, v90
	v_sub_f32_e32 v149, v149, v90
	v_sub_f32_e32 v150, v150, v90
	v_sub_f32_e32 v151, v151, v90
	v_sub_f32_e32 v152, v152, v90
	v_sub_f32_e32 v153, v153, v90
	v_sub_f32_e32 v154, v154, v90
	v_sub_f32_e32 v155, v155, v90
	v_sub_f32_e32 v156, v156, v90
	v_sub_f32_e32 v157, v157, v90
	v_sub_f32_e32 v158, v158, v90
	v_sub_f32_e32 v159, v159, v90
	v_sub_f32_e32 v160, v160, v90
	v_sub_f32_e32 v161, v161, v90
	v_sub_f32_e32 v162, v162, v90
	v_sub_f32_e32 v163, v163, v90
	v_sub_f32_e32 v164, v164, v90
	v_sub_f32_e32 v165, v165, v90
	v_sub_f32_e32 v166, v166, v90
	v_sub_f32_e32 v167, v167, v90
	v_sub_f32_e32 v168, v168, v90
	v_sub_f32_e32 v169, v169, v90
	v_sub_f32_e32 v170, v170, v90
	v_sub_f32_e32 v171, v171, v90
	v_sub_f32_e32 v172, v172, v90
	v_sub_f32_e32 v173, v173, v90
	v_mul_f32_e32 v236, v236, v91
	s_mov_b64 s[96:97], exec
	s_and_b64 exec, exec, s[8:9]
	ds_write_b32 v235, v91
	s_mov_b64 exec, s[96:97]
	v_lshl_add_u32 v2, v228, 4, s47
	ds_read_b128 v[94:97], v2 offset:0
	s_waitcnt lgkmcnt(0)
	v_mul_f32_e32 v34, v34, v94
	v_mul_f32_e32 v50, v50, v94
	v_mul_f32_e32 v35, v35, v95
	v_mul_f32_e32 v51, v51, v95
	v_mul_f32_e32 v36, v36, v96
	v_mul_f32_e32 v52, v52, v96
	v_mul_f32_e32 v37, v37, v97
	v_mul_f32_e32 v53, v53, v97
	ds_read_b128 v[94:97], v2 offset:32
	s_waitcnt lgkmcnt(0)
	v_mul_f32_e32 v38, v38, v94
	v_mul_f32_e32 v54, v54, v94
	v_mul_f32_e32 v39, v39, v95
	v_mul_f32_e32 v55, v55, v95
	v_mul_f32_e32 v40, v40, v96
	v_mul_f32_e32 v56, v56, v96
	v_mul_f32_e32 v41, v41, v97
	v_mul_f32_e32 v57, v57, v97
	ds_read_b128 v[94:97], v2 offset:64
	s_waitcnt lgkmcnt(0)
	v_mul_f32_e32 v42, v42, v94
	v_mul_f32_e32 v58, v58, v94
	v_mul_f32_e32 v43, v43, v95
	v_mul_f32_e32 v59, v59, v95
	v_mul_f32_e32 v44, v44, v96
	v_mul_f32_e32 v60, v60, v96
	v_mul_f32_e32 v45, v45, v97
	v_mul_f32_e32 v61, v61, v97
	ds_read_b128 v[94:97], v2 offset:96
	s_waitcnt lgkmcnt(0)
	v_mul_f32_e32 v46, v46, v94
	v_mul_f32_e32 v62, v62, v94
	v_mul_f32_e32 v47, v47, v95
	v_mul_f32_e32 v63, v63, v95
	v_mul_f32_e32 v48, v48, v96
	v_mul_f32_e32 v64, v64, v96
	v_mul_f32_e32 v49, v49, v97
	v_mul_f32_e32 v65, v65, v97
.Lmy_nors_3:
	s_waitcnt lgkmcnt(0)
	v_add_u32_e32 v2, 0x6000, v237
	v_mfma_f32_32x32x16_bf16 v[82:97], v[218:221], v[4:7], v[66:81]
	v_exp_f32_e32 v142, v142
	v_exp_f32_e32 v143, v143
	v_exp_f32_e32 v144, v144
	v_add_f32_e32 v27, v142, v143
	v_exp_f32_e32 v145, v145
	v_mfma_f32_32x32x16_bf16 v[98:113], v[214:217], v[4:7], v[66:81]
	v_exp_f32_e32 v146, v146
	v_add_f32_e32 v27, v27, v144
	v_exp_f32_e32 v147, v147
	v_add_f32_e32 v27, v27, v145
	v_exp_f32_e32 v148, v148
	v_mfma_f32_32x32x16_bf16 v[82:97], v[210:213], v[8:11], v[82:97]
	v_add_f32_e32 v27, v27, v146
	v_exp_f32_e32 v149, v149
	v_add_f32_e32 v27, v27, v147
	v_add_f32_e32 v27, v27, v148
	v_add_f32_e32 v27, v27, v149
	v_mfma_f32_32x32x16_bf16 v[98:113], v[206:209], v[8:11], v[98:113]
	v_cvt_pk_bf16_f32 v142, v142, v143
	v_cvt_pk_bf16_f32 v143, v144, v145
	v_cvt_pk_bf16_f32 v144, v146, v147
	v_cvt_pk_bf16_f32 v145, v148, v149
	v_mfma_f32_32x32x16_bf16 v[82:97], v[202:205], v[12:15], v[82:97]
	v_exp_f32_e32 v150, v150
	v_exp_f32_e32 v151, v151
	v_exp_f32_e32 v152, v152
	v_add_f32_e32 v27, v27, v150
	v_exp_f32_e32 v153, v153
	v_mfma_f32_32x32x16_bf16 v[98:113], v[198:201], v[12:15], v[98:113]
	v_add_f32_e32 v27, v27, v151
	v_exp_f32_e32 v154, v154
	v_add_f32_e32 v27, v27, v152
	v_exp_f32_e32 v155, v155
	v_add_f32_e32 v27, v27, v153
	s_waitcnt vmcnt(6)
	s_barrier
	v_mfma_f32_32x32x16_bf16 v[82:97], v[194:197], v[130:133], v[82:97]
	s_add_u32 m0, s57, 0x4000
	v_exp_f32_e32 v156, v156
	v_add_f32_e32 v27, v27, v154
	global_load_lds_dwordx4 v[28:29], off
	v_lshl_add_u64 v[28:29], v[28:29], 0, s[30:31]
	v_exp_f32_e32 v157, v157
	v_add_f32_e32 v27, v27, v155
	v_add_f32_e32 v27, v27, v156
	ds_read_b64_tr_b16 v[114:115], v2 offset:49152
	ds_read_b64_tr_b16 v[116:117], v2 offset:49664
	ds_read_b64_tr_b16 v[118:119], v2 offset:50176
	ds_read_b64_tr_b16 v[120:121], v2 offset:50688
	v_mfma_f32_32x32x16_bf16 v[98:113], v[190:193], v[130:133], v[98:113]
	s_cmp_eq_u32 s79, 1
	s_cbranch_scc1 .Lmy_gl_4
	s_add_u32 m0, s40, 0x0
	s_nop 0
	global_load_lds_dwordx4 v[24:25], off
	v_lshl_add_u64 v[24:25], v[24:25], 0, s[30:31]
.Lmy_gl_4:
	v_add_f32_e32 v27, v27, v157
	v_cvt_pk_bf16_f32 v150, v150, v151
	v_cvt_pk_bf16_f32 v151, v152, v153
	v_cvt_pk_bf16_f32 v152, v154, v155
	v_cvt_pk_bf16_f32 v153, v156, v157
	ds_read_b64_tr_b16 v[122:123], v2 offset:51200
	ds_read_b64_tr_b16 v[124:125], v2 offset:51712
	ds_read_b64_tr_b16 v[126:127], v2 offset:52224
	ds_read_b64_tr_b16 v[128:129], v2 offset:52736
	v_mfma_f32_32x32x16_bf16 v[82:97], v[186:189], v[134:137], v[82:97]
	s_cmp_eq_u32 s79, 1
	s_cbranch_scc1 .Lmy_gl_5
	s_add_u32 m0, s43, 0x0
	s_nop 0
	global_load_lds_dwordx4 v[30:31], off
	v_lshl_add_u64 v[30:31], v[30:31], 0, s[12:13]
.Lmy_gl_5:
	v_exp_f32_e32 v158, v158
	v_exp_f32_e32 v159, v159
	v_exp_f32_e32 v160, v160
	v_add_f32_e32 v27, v27, v158
	v_exp_f32_e32 v161, v161
	ds_read_b64_tr_b16 v[240:241], v2 offset:53248
	ds_read_b64_tr_b16 v[242:243], v2 offset:53760
	ds_read_b64_tr_b16 v[244:245], v2 offset:54272
	ds_read_b64_tr_b16 v[246:247], v2 offset:54784
	v_mfma_f32_32x32x16_bf16 v[98:113], v[182:185], v[134:137], v[98:113]
	v_add_f32_e32 v27, v27, v159
	v_exp_f32_e32 v162, v162
	v_add_f32_e32 v27, v27, v160
	v_exp_f32_e32 v163, v163
	v_add_f32_e32 v27, v27, v161
	ds_read_b64_tr_b16 v[248:249], v2 offset:55296
	ds_read_b64_tr_b16 v[250:251], v2 offset:55808
	ds_read_b64_tr_b16 v[20:21], v2 offset:56320
	ds_read_b64_tr_b16 v[22:23], v2 offset:56832
	v_mfma_f32_32x32x16_bf16 v[82:97], v[178:181], v[138:141], v[82:97]
	v_exp_f32_e32 v164, v164
	v_add_f32_e32 v27, v27, v162
	v_exp_f32_e32 v165, v165
	v_add_f32_e32 v27, v27, v163
	v_add_f32_e32 v27, v27, v164
	v_mfma_f32_32x32x16_bf16 v[98:113], v[174:177], v[138:141], v[98:113]
	v_add_f32_e32 v27, v27, v165
	v_cvt_pk_bf16_f32 v158, v158, v159
	v_cvt_pk_bf16_f32 v159, v160, v161
	v_cvt_pk_bf16_f32 v160, v162, v163
	v_cvt_pk_bf16_f32 v161, v164, v165
	s_waitcnt lgkmcnt(0)
	v_add_u32_e32 v2, 0x3000, v238
	v_mfma_f32_32x32x16_bf16 v[34:49], v[142:145], v[114:117], v[34:49]
	v_exp_f32_e32 v166, v166
	v_exp_f32_e32 v167, v167
	v_exp_f32_e32 v168, v168
	v_add_f32_e32 v27, v27, v166
	v_exp_f32_e32 v169, v169
	ds_read_b128 v[218:221], v2
	ds_read_b128 v[214:217], v2 offset:512
	ds_read_b128 v[210:213], v2 offset:2048
	v_mfma_f32_32x32x16_bf16 v[50:65], v[142:145], v[240:243], v[50:65]
	v_add_f32_e32 v27, v27, v167
	v_exp_f32_e32 v170, v170
	v_add_f32_e32 v27, v27, v168
	v_exp_f32_e32 v171, v171
	v_add_f32_e32 v27, v27, v169
	ds_read_b128 v[206:209], v2 offset:2560
	ds_read_b128 v[202:205], v2 offset:4096
	ds_read_b128 v[198:201], v2 offset:4608
	v_mfma_f32_32x32x16_bf16 v[34:49], v[150:153], v[118:121], v[34:49]
	v_exp_f32_e32 v172, v172
	v_add_f32_e32 v27, v27, v170
	v_exp_f32_e32 v173, v173
	v_add_f32_e32 v27, v27, v171
	v_add_f32_e32 v27, v27, v172
	ds_read_b128 v[194:197], v2 offset:6144
	ds_read_b128 v[190:193], v2 offset:6656
	ds_read_b128 v[186:189], v2 offset:8192
	v_mfma_f32_32x32x16_bf16 v[50:65], v[150:153], v[244:247], v[50:65]
	v_add_f32_e32 v27, v27, v173
	v_cvt_pk_bf16_f32 v166, v166, v167
	v_cvt_pk_bf16_f32 v167, v168, v169
	v_cvt_pk_bf16_f32 v168, v170, v171
	v_cvt_pk_bf16_f32 v169, v172, v173
	v_add_f32_e32 v236, v236, v27
	ds_read_b128 v[182:185], v2 offset:8704
	ds_read_b128 v[178:181], v2 offset:10240
	ds_read_b128 v[174:177], v2 offset:10752
	v_mfma_f32_32x32x16_bf16 v[34:49], v[158:161], v[122:125], v[34:49]
	v_max3_f32 v19, v82, v83, v84
	v_max3_f32 v26, v85, v86, v87
	v_max3_f32 v19, v19, v88, v89
	v_max3_f32 v26, v26, v90, v91
	v_mfma_f32_32x32x16_bf16 v[50:65], v[158:161], v[248:251], v[50:65]
	v_max3_f32 v19, v19, v92, v93
	v_max3_f32 v26, v26, v94, v95
	v_max3_f32 v19, v19, v96, v97
	v_max3_f32 v26, v26, v98, v99
	v_mfma_f32_32x32x16_bf16 v[34:49], v[166:169], v[126:129], v[34:49]
	v_max3_f32 v19, v19, v100, v101
	v_max3_f32 v26, v26, v102, v103
	v_max3_f32 v19, v19, v104, v105
	v_max3_f32 v26, v26, v106, v107
	v_mfma_f32_32x32x16_bf16 v[50:65], v[166:169], v[20:23], v[50:65]
	v_max3_f32 v19, v19, v108, v109
	v_max3_f32 v26, v26, v110, v111
	v_max3_f32 v19, v19, v112, v113
	v_max_f32_e32 v19, v19, v26
	v_cmp_lt_f32_e32 vcc, s41, v19
	s_cbranch_vccz .Lmy_nors_6
	s_nop 15
	s_nop 15
	v_mov_b32_e32 v26, v19
	s_nop 1
	v_permlane32_swap_b32_e32 v19, v26
	v_max_f32_e32 v19, v19, v26
	v_max_f32_e32 v19, v19, v19
	v_max_f32_e32 v150, 0, v19
	v_exp_f32_e64 v151, -v150
	v_add_f32_e32 v239, v239, v150
	v_xor_b32_e32 v66, 0x80000000, v239
	v_mov_b32_e32 v67, v66
	v_mov_b32_e32 v68, v66
	v_mov_b32_e32 v69, v66
	v_mov_b32_e32 v70, v66
	v_mov_b32_e32 v71, v66
	v_mov_b32_e32 v72, v66
	v_mov_b32_e32 v73, v66
	v_mov_b32_e32 v74, v66
	v_mov_b32_e32 v75, v66
	v_mov_b32_e32 v76, v66
	v_mov_b32_e32 v77, v66
	v_mov_b32_e32 v78, v66
	v_mov_b32_e32 v79, v66
	v_mov_b32_e32 v80, v66
	v_mov_b32_e32 v81, v66
	v_sub_f32_e32 v82, v82, v150
	v_sub_f32_e32 v83, v83, v150
	v_sub_f32_e32 v84, v84, v150
	v_sub_f32_e32 v85, v85, v150
	v_sub_f32_e32 v86, v86, v150
	v_sub_f32_e32 v87, v87, v150
	v_sub_f32_e32 v88, v88, v150
	v_sub_f32_e32 v89, v89, v150
	v_sub_f32_e32 v90, v90, v150
	v_sub_f32_e32 v91, v91, v150
	v_sub_f32_e32 v92, v92, v150
	v_sub_f32_e32 v93, v93, v150
	v_sub_f32_e32 v94, v94, v150
	v_sub_f32_e32 v95, v95, v150
	v_sub_f32_e32 v96, v96, v150
	v_sub_f32_e32 v97, v97, v150
	v_sub_f32_e32 v98, v98, v150
	v_sub_f32_e32 v99, v99, v150
	v_sub_f32_e32 v100, v100, v150
	v_sub_f32_e32 v101, v101, v150
	v_sub_f32_e32 v102, v102, v150
	v_sub_f32_e32 v103, v103, v150
	v_sub_f32_e32 v104, v104, v150
	v_sub_f32_e32 v105, v105, v150
	v_sub_f32_e32 v106, v106, v150
	v_sub_f32_e32 v107, v107, v150
	v_sub_f32_e32 v108, v108, v150
	v_sub_f32_e32 v109, v109, v150
	v_sub_f32_e32 v110, v110, v150
	v_sub_f32_e32 v111, v111, v150
	v_sub_f32_e32 v112, v112, v150
	v_sub_f32_e32 v113, v113, v150
	v_mul_f32_e32 v236, v236, v151
	s_mov_b64 s[96:97], exec
	s_and_b64 exec, exec, s[8:9]
	ds_write_b32 v235, v151
	s_mov_b64 exec, s[96:97]
	v_lshl_add_u32 v2, v228, 4, s47
	ds_read_b128 v[154:157], v2 offset:0
	s_waitcnt lgkmcnt(0)
	v_mul_f32_e32 v34, v34, v154
	v_mul_f32_e32 v50, v50, v154
	v_mul_f32_e32 v35, v35, v155
	v_mul_f32_e32 v51, v51, v155
	v_mul_f32_e32 v36, v36, v156
	v_mul_f32_e32 v52, v52, v156
	v_mul_f32_e32 v37, v37, v157
	v_mul_f32_e32 v53, v53, v157
	ds_read_b128 v[154:157], v2 offset:32
	s_waitcnt lgkmcnt(0)
	v_mul_f32_e32 v38, v38, v154
	v_mul_f32_e32 v54, v54, v154
	v_mul_f32_e32 v39, v39, v155
	v_mul_f32_e32 v55, v55, v155
	v_mul_f32_e32 v40, v40, v156
	v_mul_f32_e32 v56, v56, v156
	v_mul_f32_e32 v41, v41, v157
	v_mul_f32_e32 v57, v57, v157
	ds_read_b128 v[154:157], v2 offset:64
	s_waitcnt lgkmcnt(0)
	v_mul_f32_e32 v42, v42, v154
	v_mul_f32_e32 v58, v58, v154
	v_mul_f32_e32 v43, v43, v155
	v_mul_f32_e32 v59, v59, v155
	v_mul_f32_e32 v44, v44, v156
	v_mul_f32_e32 v60, v60, v156
	v_mul_f32_e32 v45, v45, v157
	v_mul_f32_e32 v61, v61, v157
	ds_read_b128 v[154:157], v2 offset:96
	s_waitcnt lgkmcnt(0)
	v_mul_f32_e32 v46, v46, v154
	v_mul_f32_e32 v62, v62, v154
	v_mul_f32_e32 v47, v47, v155
	v_mul_f32_e32 v63, v63, v155
	v_mul_f32_e32 v48, v48, v156
	v_mul_f32_e32 v64, v64, v156
	v_mul_f32_e32 v49, v49, v157
	v_mul_f32_e32 v65, v65, v157

.Lmy_A_loop:
	s_waitcnt lgkmcnt(0)
	v_mov_b32_e32 v2, v237
	v_mfma_f32_32x32x16_bf16 v[142:157], v[218:221], v[4:7], v[66:81]
	v_exp_f32_e32 v82, v82
	v_exp_f32_e32 v83, v83
	v_exp_f32_e32 v84, v84
	v_add_f32_e32 v27, v82, v83
	v_exp_f32_e32 v85, v85
	v_mfma_f32_32x32x16_bf16 v[158:173], v[214:217], v[4:7], v[66:81]
	v_exp_f32_e32 v86, v86
	v_add_f32_e32 v27, v27, v84
	v_exp_f32_e32 v87, v87
	v_add_f32_e32 v27, v27, v85
	v_exp_f32_e32 v88, v88
	v_mfma_f32_32x32x16_bf16 v[142:157], v[210:213], v[8:11], v[142:157]
	v_add_f32_e32 v27, v27, v86
	v_exp_f32_e32 v89, v89
	v_add_f32_e32 v27, v27, v87
	v_add_f32_e32 v27, v27, v88
	v_add_f32_e32 v27, v27, v89
	v_mfma_f32_32x32x16_bf16 v[158:173], v[206:209], v[8:11], v[158:173]
	v_cvt_pk_bf16_f32 v82, v82, v83
	v_cvt_pk_bf16_f32 v83, v84, v85
	v_cvt_pk_bf16_f32 v84, v86, v87
	v_cvt_pk_bf16_f32 v85, v88, v89
	v_mfma_f32_32x32x16_bf16 v[142:157], v[202:205], v[12:15], v[142:157]
	v_exp_f32_e32 v90, v90
	v_exp_f32_e32 v91, v91
	v_exp_f32_e32 v92, v92
	v_add_f32_e32 v27, v27, v90
	v_exp_f32_e32 v93, v93
	v_mfma_f32_32x32x16_bf16 v[158:173], v[198:201], v[12:15], v[158:173]
	v_add_f32_e32 v27, v27, v91
	v_exp_f32_e32 v94, v94
	v_add_f32_e32 v27, v27, v92
	v_exp_f32_e32 v95, v95
	v_add_f32_e32 v27, v27, v93
	s_waitcnt vmcnt(6)
	s_barrier
	v_mfma_f32_32x32x16_bf16 v[142:157], v[194:197], v[130:133], v[142:157]
	s_add_u32 m0, s57, 0x6000
	v_exp_f32_e32 v96, v96
	v_add_f32_e32 v27, v27, v94
	global_load_lds_dwordx4 v[28:29], off
	v_lshl_add_u64 v[28:29], v[28:29], 0, s[30:31]
	v_exp_f32_e32 v97, v97
	v_add_f32_e32 v27, v27, v95
	v_add_f32_e32 v27, v27, v96
	ds_read_b64_tr_b16 v[114:115], v2 offset:49152
	ds_read_b64_tr_b16 v[116:117], v2 offset:49664
	ds_read_b64_tr_b16 v[118:119], v2 offset:50176
	ds_read_b64_tr_b16 v[120:121], v2 offset:50688
	v_mfma_f32_32x32x16_bf16 v[158:173], v[190:193], v[130:133], v[158:173]
	s_add_u32 m0, s40, 0x3000
	v_add_f32_e32 v27, v27, v97
	v_cvt_pk_bf16_f32 v90, v90, v91
	global_load_lds_dwordx4 v[24:25], off
	v_lshl_add_u64 v[24:25], v[24:25], 0, s[30:31]
	v_cvt_pk_bf16_f32 v91, v92, v93
	v_cvt_pk_bf16_f32 v92, v94, v95
	v_cvt_pk_bf16_f32 v93, v96, v97
	ds_read_b64_tr_b16 v[122:123], v2 offset:51200
	ds_read_b64_tr_b16 v[124:125], v2 offset:51712
	ds_read_b64_tr_b16 v[126:127], v2 offset:52224
	ds_read_b64_tr_b16 v[128:129], v2 offset:52736
	v_mfma_f32_32x32x16_bf16 v[142:157], v[186:189], v[134:137], v[142:157]
	s_add_u32 m0, s43, 0x3000
	v_exp_f32_e32 v98, v98
	v_exp_f32_e32 v99, v99
	global_load_lds_dwordx4 v[30:31], off
	v_lshl_add_u64 v[30:31], v[30:31], 0, s[12:13]
	v_exp_f32_e32 v100, v100
	v_add_f32_e32 v27, v27, v98
	v_exp_f32_e32 v101, v101
	ds_read_b64_tr_b16 v[240:241], v2 offset:53248
	ds_read_b64_tr_b16 v[242:243], v2 offset:53760
	ds_read_b64_tr_b16 v[244:245], v2 offset:54272
	ds_read_b64_tr_b16 v[246:247], v2 offset:54784
	v_mfma_f32_32x32x16_bf16 v[158:173], v[182:185], v[134:137], v[158:173]
	v_add_f32_e32 v27, v27, v99
	v_exp_f32_e32 v102, v102
	v_add_f32_e32 v27, v27, v100
	v_exp_f32_e32 v103, v103
	v_add_f32_e32 v27, v27, v101
	ds_read_b64_tr_b16 v[248:249], v2 offset:55296
	ds_read_b64_tr_b16 v[250:251], v2 offset:55808
	ds_read_b64_tr_b16 v[20:21], v2 offset:56320
	ds_read_b64_tr_b16 v[22:23], v2 offset:56832
	v_mfma_f32_32x32x16_bf16 v[142:157], v[178:181], v[138:141], v[142:157]
	v_exp_f32_e32 v104, v104
	v_add_f32_e32 v27, v27, v102
	v_exp_f32_e32 v105, v105
	v_add_f32_e32 v27, v27, v103
	v_add_f32_e32 v27, v27, v104
	v_mfma_f32_32x32x16_bf16 v[158:173], v[174:177], v[138:141], v[158:173]
	v_add_f32_e32 v27, v27, v105
	v_cvt_pk_bf16_f32 v98, v98, v99
	v_cvt_pk_bf16_f32 v99, v100, v101
	v_cvt_pk_bf16_f32 v100, v102, v103
	v_cvt_pk_bf16_f32 v101, v104, v105
	s_waitcnt lgkmcnt(0)
	v_add_u32_e32 v2, 0x6000, v238
	v_mfma_f32_32x32x16_bf16 v[34:49], v[82:85], v[114:117], v[34:49]
	v_exp_f32_e32 v106, v106
	v_exp_f32_e32 v107, v107
	v_exp_f32_e32 v108, v108
	v_add_f32_e32 v27, v27, v106
	v_exp_f32_e32 v109, v109
	ds_read_b128 v[218:221], v2
	ds_read_b128 v[214:217], v2 offset:512
	ds_read_b128 v[210:213], v2 offset:2048
	v_mfma_f32_32x32x16_bf16 v[50:65], v[82:85], v[240:243], v[50:65]
	v_add_f32_e32 v27, v27, v107
	v_exp_f32_e32 v110, v110
	v_add_f32_e32 v27, v27, v108
	v_exp_f32_e32 v111, v111
	v_add_f32_e32 v27, v27, v109
	ds_read_b128 v[206:209], v2 offset:2560
	ds_read_b128 v[202:205], v2 offset:4096
	ds_read_b128 v[198:201], v2 offset:4608
	v_mfma_f32_32x32x16_bf16 v[34:49], v[90:93], v[118:121], v[34:49]
	v_exp_f32_e32 v112, v112
	v_add_f32_e32 v27, v27, v110
	v_exp_f32_e32 v113, v113
	v_add_f32_e32 v27, v27, v111
	v_add_f32_e32 v27, v27, v112
	ds_read_b128 v[194:197], v2 offset:6144
	ds_read_b128 v[190:193], v2 offset:6656
	ds_read_b128 v[186:189], v2 offset:8192
	v_mfma_f32_32x32x16_bf16 v[50:65], v[90:93], v[244:247], v[50:65]
	v_add_f32_e32 v27, v27, v113
	v_cvt_pk_bf16_f32 v106, v106, v107
	v_cvt_pk_bf16_f32 v107, v108, v109
	v_cvt_pk_bf16_f32 v108, v110, v111
	v_cvt_pk_bf16_f32 v109, v112, v113
	v_add_f32_e32 v236, v236, v27
	ds_read_b128 v[182:185], v2 offset:8704
	ds_read_b128 v[178:181], v2 offset:10240
	ds_read_b128 v[174:177], v2 offset:10752
	v_mfma_f32_32x32x16_bf16 v[34:49], v[98:101], v[122:125], v[34:49]
	v_max3_f32 v19, v142, v143, v144
	v_max3_f32 v26, v145, v146, v147
	v_max3_f32 v19, v19, v148, v149
	v_max3_f32 v26, v26, v150, v151
	v_mfma_f32_32x32x16_bf16 v[50:65], v[98:101], v[248:251], v[50:65]
	v_max3_f32 v19, v19, v152, v153
	v_max3_f32 v26, v26, v154, v155
	v_max3_f32 v19, v19, v156, v157
	v_max3_f32 v26, v26, v158, v159
	v_mfma_f32_32x32x16_bf16 v[34:49], v[106:109], v[126:129], v[34:49]
	v_max3_f32 v19, v19, v160, v161
	v_max3_f32 v26, v26, v162, v163
	v_max3_f32 v19, v19, v164, v165
	v_max3_f32 v26, v26, v166, v167
	v_mfma_f32_32x32x16_bf16 v[50:65], v[106:109], v[20:23], v[50:65]
	v_max3_f32 v19, v19, v168, v169
	v_max3_f32 v26, v26, v170, v171
	v_max3_f32 v19, v19, v172, v173
	v_max_f32_e32 v19, v19, v26
	v_cmp_lt_f32_e32 vcc, s41, v19
	s_cbranch_vccz .Lmy_nors_7
	s_nop 15
	s_nop 15
	v_mov_b32_e32 v26, v19
	s_nop 1
	v_permlane32_swap_b32_e32 v19, v26
	v_max_f32_e32 v19, v19, v26
	v_max_f32_e32 v19, v19, v19
	v_max_f32_e32 v90, 0, v19
	v_exp_f32_e64 v91, -v90
	v_add_f32_e32 v239, v239, v90
	v_xor_b32_e32 v66, 0x80000000, v239
	v_mov_b32_e32 v67, v66
	v_mov_b32_e32 v68, v66
	v_mov_b32_e32 v69, v66
	v_mov_b32_e32 v70, v66
	v_mov_b32_e32 v71, v66
	v_mov_b32_e32 v72, v66
	v_mov_b32_e32 v73, v66
	v_mov_b32_e32 v74, v66
	v_mov_b32_e32 v75, v66
	v_mov_b32_e32 v76, v66
	v_mov_b32_e32 v77, v66
	v_mov_b32_e32 v78, v66
	v_mov_b32_e32 v79, v66
	v_mov_b32_e32 v80, v66
	v_mov_b32_e32 v81, v66
	v_sub_f32_e32 v142, v142, v90
	v_sub_f32_e32 v143, v143, v90
	v_sub_f32_e32 v144, v144, v90
	v_sub_f32_e32 v145, v145, v90
	v_sub_f32_e32 v146, v146, v90
	v_sub_f32_e32 v147, v147, v90
	v_sub_f32_e32 v148, v148, v90
	v_sub_f32_e32 v149, v149, v90
	v_sub_f32_e32 v150, v150, v90
	v_sub_f32_e32 v151, v151, v90
	v_sub_f32_e32 v152, v152, v90
	v_sub_f32_e32 v153, v153, v90
	v_sub_f32_e32 v154, v154, v90
	v_sub_f32_e32 v155, v155, v90
	v_sub_f32_e32 v156, v156, v90
	v_sub_f32_e32 v157, v157, v90
	v_sub_f32_e32 v158, v158, v90
	v_sub_f32_e32 v159, v159, v90
	v_sub_f32_e32 v160, v160, v90
	v_sub_f32_e32 v161, v161, v90
	v_sub_f32_e32 v162, v162, v90
	v_sub_f32_e32 v163, v163, v90
	v_sub_f32_e32 v164, v164, v90
	v_sub_f32_e32 v165, v165, v90
	v_sub_f32_e32 v166, v166, v90
	v_sub_f32_e32 v167, v167, v90
	v_sub_f32_e32 v168, v168, v90
	v_sub_f32_e32 v169, v169, v90
	v_sub_f32_e32 v170, v170, v90
	v_sub_f32_e32 v171, v171, v90
	v_sub_f32_e32 v172, v172, v90
	v_sub_f32_e32 v173, v173, v90
	v_mul_f32_e32 v236, v236, v91
	s_mov_b64 s[96:97], exec
	s_and_b64 exec, exec, s[8:9]
	ds_write_b32 v235, v91
	s_mov_b64 exec, s[96:97]
	v_lshl_add_u32 v2, v228, 4, s47
	ds_read_b128 v[94:97], v2 offset:0
	s_waitcnt lgkmcnt(0)
	v_mul_f32_e32 v34, v34, v94
	v_mul_f32_e32 v50, v50, v94
	v_mul_f32_e32 v35, v35, v95
	v_mul_f32_e32 v51, v51, v95
	v_mul_f32_e32 v36, v36, v96
	v_mul_f32_e32 v52, v52, v96
	v_mul_f32_e32 v37, v37, v97
	v_mul_f32_e32 v53, v53, v97
	ds_read_b128 v[94:97], v2 offset:32
	s_waitcnt lgkmcnt(0)
	v_mul_f32_e32 v38, v38, v94
	v_mul_f32_e32 v54, v54, v94
	v_mul_f32_e32 v39, v39, v95
	v_mul_f32_e32 v55, v55, v95
	v_mul_f32_e32 v40, v40, v96
	v_mul_f32_e32 v56, v56, v96
	v_mul_f32_e32 v41, v41, v97
	v_mul_f32_e32 v57, v57, v97
	ds_read_b128 v[94:97], v2 offset:64
	s_waitcnt lgkmcnt(0)
	v_mul_f32_e32 v42, v42, v94
	v_mul_f32_e32 v58, v58, v94
	v_mul_f32_e32 v43, v43, v95
	v_mul_f32_e32 v59, v59, v95
	v_mul_f32_e32 v44, v44, v96
	v_mul_f32_e32 v60, v60, v96
	v_mul_f32_e32 v45, v45, v97
	v_mul_f32_e32 v61, v61, v97
	ds_read_b128 v[94:97], v2 offset:96
	s_waitcnt lgkmcnt(0)
	v_mul_f32_e32 v46, v46, v94
	v_mul_f32_e32 v62, v62, v94
	v_mul_f32_e32 v47, v47, v95
	v_mul_f32_e32 v63, v63, v95
	v_mul_f32_e32 v48, v48, v96
	v_mul_f32_e32 v64, v64, v96
	v_mul_f32_e32 v49, v49, v97
	v_mul_f32_e32 v65, v65, v97
.Lmy_nors_7:
	s_waitcnt lgkmcnt(0)
	v_add_u32_e32 v2, 0x2000, v237
	v_mfma_f32_32x32x16_bf16 v[82:97], v[218:221], v[4:7], v[66:81]
	v_exp_f32_e32 v142, v142
	v_exp_f32_e32 v143, v143
	v_exp_f32_e32 v144, v144
	v_add_f32_e32 v27, v142, v143
	v_exp_f32_e32 v145, v145
	v_mfma_f32_32x32x16_bf16 v[98:113], v[214:217], v[4:7], v[66:81]
	v_exp_f32_e32 v146, v146
	v_add_f32_e32 v27, v27, v144
	v_exp_f32_e32 v147, v147
	v_add_f32_e32 v27, v27, v145
	v_exp_f32_e32 v148, v148
	v_mfma_f32_32x32x16_bf16 v[82:97], v[210:213], v[8:11], v[82:97]
	v_add_f32_e32 v27, v27, v146
	v_exp_f32_e32 v149, v149
	v_add_f32_e32 v27, v27, v147
	v_add_f32_e32 v27, v27, v148
	v_add_f32_e32 v27, v27, v149
	v_mfma_f32_32x32x16_bf16 v[98:113], v[206:209], v[8:11], v[98:113]
	v_cvt_pk_bf16_f32 v142, v142, v143
	v_cvt_pk_bf16_f32 v143, v144, v145
	v_cvt_pk_bf16_f32 v144, v146, v147
	v_cvt_pk_bf16_f32 v145, v148, v149
	v_mfma_f32_32x32x16_bf16 v[82:97], v[202:205], v[12:15], v[82:97]
	v_exp_f32_e32 v150, v150
	v_exp_f32_e32 v151, v151
	v_exp_f32_e32 v152, v152
	v_add_f32_e32 v27, v27, v150
	v_exp_f32_e32 v153, v153
	v_mfma_f32_32x32x16_bf16 v[98:113], v[198:201], v[12:15], v[98:113]
	v_add_f32_e32 v27, v27, v151
	v_exp_f32_e32 v154, v154
	v_add_f32_e32 v27, v27, v152
	v_exp_f32_e32 v155, v155
	v_add_f32_e32 v27, v27, v153
	s_waitcnt vmcnt(6)
	s_barrier
	v_mfma_f32_32x32x16_bf16 v[82:97], v[194:197], v[130:133], v[82:97]
	s_add_u32 m0, s57, 0x0
	v_exp_f32_e32 v156, v156
	v_add_f32_e32 v27, v27, v154
	global_load_lds_dwordx4 v[28:29], off
	v_lshl_add_u64 v[28:29], v[28:29], 0, s[30:31]
	v_exp_f32_e32 v157, v157
	v_add_f32_e32 v27, v27, v155
	v_add_f32_e32 v27, v27, v156
	ds_read_b64_tr_b16 v[114:115], v2 offset:49152
	ds_read_b64_tr_b16 v[116:117], v2 offset:49664
	ds_read_b64_tr_b16 v[118:119], v2 offset:50176
	ds_read_b64_tr_b16 v[120:121], v2 offset:50688
	v_mfma_f32_32x32x16_bf16 v[98:113], v[190:193], v[130:133], v[98:113]
	s_add_u32 m0, s40, 0x6000
	v_add_f32_e32 v27, v27, v157
	v_cvt_pk_bf16_f32 v150, v150, v151
	global_load_lds_dwordx4 v[24:25], off
	v_lshl_add_u64 v[24:25], v[24:25], 0, s[30:31]
	v_cvt_pk_bf16_f32 v151, v152, v153
	v_cvt_pk_bf16_f32 v152, v154, v155
	v_cvt_pk_bf16_f32 v153, v156, v157
	ds_read_b64_tr_b16 v[122:123], v2 offset:51200
	ds_read_b64_tr_b16 v[124:125], v2 offset:51712
	ds_read_b64_tr_b16 v[126:127], v2 offset:52224
	ds_read_b64_tr_b16 v[128:129], v2 offset:52736
	v_mfma_f32_32x32x16_bf16 v[82:97], v[186:189], v[134:137], v[82:97]
	s_add_u32 m0, s43, 0x6000
	v_exp_f32_e32 v158, v158
	v_exp_f32_e32 v159, v159
	global_load_lds_dwordx4 v[30:31], off
	v_lshl_add_u64 v[30:31], v[30:31], 0, s[12:13]
	v_exp_f32_e32 v160, v160
	v_add_f32_e32 v27, v27, v158
	v_exp_f32_e32 v161, v161
	ds_read_b64_tr_b16 v[240:241], v2 offset:53248
	ds_read_b64_tr_b16 v[242:243], v2 offset:53760
	ds_read_b64_tr_b16 v[244:245], v2 offset:54272
	ds_read_b64_tr_b16 v[246:247], v2 offset:54784
	v_mfma_f32_32x32x16_bf16 v[98:113], v[182:185], v[134:137], v[98:113]
	v_add_f32_e32 v27, v27, v159
	v_exp_f32_e32 v162, v162
	v_add_f32_e32 v27, v27, v160
	v_exp_f32_e32 v163, v163
	v_add_f32_e32 v27, v27, v161
	ds_read_b64_tr_b16 v[248:249], v2 offset:55296
	ds_read_b64_tr_b16 v[250:251], v2 offset:55808
	ds_read_b64_tr_b16 v[20:21], v2 offset:56320
	ds_read_b64_tr_b16 v[22:23], v2 offset:56832
	v_mfma_f32_32x32x16_bf16 v[82:97], v[178:181], v[138:141], v[82:97]
	v_exp_f32_e32 v164, v164
	v_add_f32_e32 v27, v27, v162
	v_exp_f32_e32 v165, v165
	v_add_f32_e32 v27, v27, v163
	v_add_f32_e32 v27, v27, v164
	v_mfma_f32_32x32x16_bf16 v[98:113], v[174:177], v[138:141], v[98:113]
	v_add_f32_e32 v27, v27, v165
	v_cvt_pk_bf16_f32 v158, v158, v159
	v_cvt_pk_bf16_f32 v159, v160, v161
	v_cvt_pk_bf16_f32 v160, v162, v163
	v_cvt_pk_bf16_f32 v161, v164, v165
	s_waitcnt lgkmcnt(0)
	v_add_u32_e32 v2, 0x9000, v238
	v_mfma_f32_32x32x16_bf16 v[34:49], v[142:145], v[114:117], v[34:49]
	v_exp_f32_e32 v166, v166
	v_exp_f32_e32 v167, v167
	v_exp_f32_e32 v168, v168
	v_add_f32_e32 v27, v27, v166
	v_exp_f32_e32 v169, v169
	ds_read_b128 v[218:221], v2
	ds_read_b128 v[214:217], v2 offset:512
	ds_read_b128 v[210:213], v2 offset:2048
	v_mfma_f32_32x32x16_bf16 v[50:65], v[142:145], v[240:243], v[50:65]
	v_add_f32_e32 v27, v27, v167
	v_exp_f32_e32 v170, v170
	v_add_f32_e32 v27, v27, v168
	v_exp_f32_e32 v171, v171
	v_add_f32_e32 v27, v27, v169
	ds_read_b128 v[206:209], v2 offset:2560
	ds_read_b128 v[202:205], v2 offset:4096
	ds_read_b128 v[198:201], v2 offset:4608
	v_mfma_f32_32x32x16_bf16 v[34:49], v[150:153], v[118:121], v[34:49]
	v_exp_f32_e32 v172, v172
	v_add_f32_e32 v27, v27, v170
	v_exp_f32_e32 v173, v173
	v_add_f32_e32 v27, v27, v171
	v_add_f32_e32 v27, v27, v172
	ds_read_b128 v[194:197], v2 offset:6144
	ds_read_b128 v[190:193], v2 offset:6656
	ds_read_b128 v[186:189], v2 offset:8192
	v_mfma_f32_32x32x16_bf16 v[50:65], v[150:153], v[244:247], v[50:65]
	v_add_f32_e32 v27, v27, v173
	v_cvt_pk_bf16_f32 v166, v166, v167
	v_cvt_pk_bf16_f32 v167, v168, v169
	v_cvt_pk_bf16_f32 v168, v170, v171
	v_cvt_pk_bf16_f32 v169, v172, v173
	v_add_f32_e32 v236, v236, v27
	ds_read_b128 v[182:185], v2 offset:8704
	ds_read_b128 v[178:181], v2 offset:10240
	ds_read_b128 v[174:177], v2 offset:10752
	v_mfma_f32_32x32x16_bf16 v[34:49], v[158:161], v[122:125], v[34:49]
	v_max3_f32 v19, v82, v83, v84
	v_max3_f32 v26, v85, v86, v87
	v_max3_f32 v19, v19, v88, v89
	v_max3_f32 v26, v26, v90, v91
	v_mfma_f32_32x32x16_bf16 v[50:65], v[158:161], v[248:251], v[50:65]
	v_max3_f32 v19, v19, v92, v93
	v_max3_f32 v26, v26, v94, v95
	v_max3_f32 v19, v19, v96, v97
	v_max3_f32 v26, v26, v98, v99
	v_mfma_f32_32x32x16_bf16 v[34:49], v[166:169], v[126:129], v[34:49]
	v_max3_f32 v19, v19, v100, v101
	v_max3_f32 v26, v26, v102, v103
	v_max3_f32 v19, v19, v104, v105
	v_max3_f32 v26, v26, v106, v107
	v_mfma_f32_32x32x16_bf16 v[50:65], v[166:169], v[20:23], v[50:65]
	v_max3_f32 v19, v19, v108, v109
	v_max3_f32 v26, v26, v110, v111
	v_max3_f32 v19, v19, v112, v113
	v_max_f32_e32 v19, v19, v26
	v_cmp_lt_f32_e32 vcc, s41, v19
	s_cbranch_vccz .Lmy_nors_8
	s_nop 15
	s_nop 15
	v_mov_b32_e32 v26, v19
	s_nop 1
	v_permlane32_swap_b32_e32 v19, v26
	v_max_f32_e32 v19, v19, v26
	v_max_f32_e32 v19, v19, v19
	v_max_f32_e32 v150, 0, v19
	v_exp_f32_e64 v151, -v150
	v_add_f32_e32 v239, v239, v150
	v_xor_b32_e32 v66, 0x80000000, v239
	v_mov_b32_e32 v67, v66
	v_mov_b32_e32 v68, v66
	v_mov_b32_e32 v69, v66
	v_mov_b32_e32 v70, v66
	v_mov_b32_e32 v71, v66
	v_mov_b32_e32 v72, v66
	v_mov_b32_e32 v73, v66
	v_mov_b32_e32 v74, v66
	v_mov_b32_e32 v75, v66
	v_mov_b32_e32 v76, v66
	v_mov_b32_e32 v77, v66
	v_mov_b32_e32 v78, v66
	v_mov_b32_e32 v79, v66
	v_mov_b32_e32 v80, v66
	v_mov_b32_e32 v81, v66
	v_sub_f32_e32 v82, v82, v150
	v_sub_f32_e32 v83, v83, v150
	v_sub_f32_e32 v84, v84, v150
	v_sub_f32_e32 v85, v85, v150
	v_sub_f32_e32 v86, v86, v150
	v_sub_f32_e32 v87, v87, v150
	v_sub_f32_e32 v88, v88, v150
	v_sub_f32_e32 v89, v89, v150
	v_sub_f32_e32 v90, v90, v150
	v_sub_f32_e32 v91, v91, v150
	v_sub_f32_e32 v92, v92, v150
	v_sub_f32_e32 v93, v93, v150
	v_sub_f32_e32 v94, v94, v150
	v_sub_f32_e32 v95, v95, v150
	v_sub_f32_e32 v96, v96, v150
	v_sub_f32_e32 v97, v97, v150
	v_sub_f32_e32 v98, v98, v150
	v_sub_f32_e32 v99, v99, v150
	v_sub_f32_e32 v100, v100, v150
	v_sub_f32_e32 v101, v101, v150
	v_sub_f32_e32 v102, v102, v150
	v_sub_f32_e32 v103, v103, v150
	v_sub_f32_e32 v104, v104, v150
	v_sub_f32_e32 v105, v105, v150
	v_sub_f32_e32 v106, v106, v150
	v_sub_f32_e32 v107, v107, v150
	v_sub_f32_e32 v108, v108, v150
	v_sub_f32_e32 v109, v109, v150
	v_sub_f32_e32 v110, v110, v150
	v_sub_f32_e32 v111, v111, v150
	v_sub_f32_e32 v112, v112, v150
	v_sub_f32_e32 v113, v113, v150
	v_mul_f32_e32 v236, v236, v151
	s_mov_b64 s[96:97], exec
	s_and_b64 exec, exec, s[8:9]
	ds_write_b32 v235, v151
	s_mov_b64 exec, s[96:97]
	v_lshl_add_u32 v2, v228, 4, s47
	ds_read_b128 v[154:157], v2 offset:0
	s_waitcnt lgkmcnt(0)
	v_mul_f32_e32 v34, v34, v154
	v_mul_f32_e32 v50, v50, v154
	v_mul_f32_e32 v35, v35, v155
	v_mul_f32_e32 v51, v51, v155
	v_mul_f32_e32 v36, v36, v156
	v_mul_f32_e32 v52, v52, v156
	v_mul_f32_e32 v37, v37, v157
	v_mul_f32_e32 v53, v53, v157
	ds_read_b128 v[154:157], v2 offset:32
	s_waitcnt lgkmcnt(0)
	v_mul_f32_e32 v38, v38, v154
	v_mul_f32_e32 v54, v54, v154
	v_mul_f32_e32 v39, v39, v155
	v_mul_f32_e32 v55, v55, v155
	v_mul_f32_e32 v40, v40, v156
	v_mul_f32_e32 v56, v56, v156
	v_mul_f32_e32 v41, v41, v157
	v_mul_f32_e32 v57, v57, v157
	ds_read_b128 v[154:157], v2 offset:64
	s_waitcnt lgkmcnt(0)
	v_mul_f32_e32 v42, v42, v154
	v_mul_f32_e32 v58, v58, v154
	v_mul_f32_e32 v43, v43, v155
	v_mul_f32_e32 v59, v59, v155
	v_mul_f32_e32 v44, v44, v156
	v_mul_f32_e32 v60, v60, v156
	v_mul_f32_e32 v45, v45, v157
	v_mul_f32_e32 v61, v61, v157
	ds_read_b128 v[154:157], v2 offset:96
	s_waitcnt lgkmcnt(0)
	v_mul_f32_e32 v46, v46, v154
	v_mul_f32_e32 v62, v62, v154
	v_mul_f32_e32 v47, v47, v155
	v_mul_f32_e32 v63, v63, v155
	v_mul_f32_e32 v48, v48, v156
	v_mul_f32_e32 v64, v64, v156
	v_mul_f32_e32 v49, v49, v157
	v_mul_f32_e32 v65, v65, v157
.Lmy_nors_8:
	s_waitcnt lgkmcnt(0)
	v_add_u32_e32 v2, 0x4000, v237
	v_mfma_f32_32x32x16_bf16 v[142:157], v[218:221], v[4:7], v[66:81]
	v_exp_f32_e32 v82, v82
	v_exp_f32_e32 v83, v83
	v_exp_f32_e32 v84, v84
	v_add_f32_e32 v27, v82, v83
	v_exp_f32_e32 v85, v85
	v_mfma_f32_32x32x16_bf16 v[158:173], v[214:217], v[4:7], v[66:81]
	v_exp_f32_e32 v86, v86
	v_add_f32_e32 v27, v27, v84
	v_exp_f32_e32 v87, v87
	v_add_f32_e32 v27, v27, v85
	v_exp_f32_e32 v88, v88
	v_mfma_f32_32x32x16_bf16 v[142:157], v[210:213], v[8:11], v[142:157]
	v_add_f32_e32 v27, v27, v86
	v_exp_f32_e32 v89, v89
	v_add_f32_e32 v27, v27, v87
	v_add_f32_e32 v27, v27, v88
	v_add_f32_e32 v27, v27, v89
	v_mfma_f32_32x32x16_bf16 v[158:173], v[206:209], v[8:11], v[158:173]
	v_cvt_pk_bf16_f32 v82, v82, v83
	v_cvt_pk_bf16_f32 v83, v84, v85
	v_cvt_pk_bf16_f32 v84, v86, v87
	v_cvt_pk_bf16_f32 v85, v88, v89
	v_mfma_f32_32x32x16_bf16 v[142:157], v[202:205], v[12:15], v[142:157]
	v_exp_f32_e32 v90, v90
	v_exp_f32_e32 v91, v91
	v_exp_f32_e32 v92, v92
	v_add_f32_e32 v27, v27, v90
	v_exp_f32_e32 v93, v93
	v_mfma_f32_32x32x16_bf16 v[158:173], v[198:201], v[12:15], v[158:173]
	v_add_f32_e32 v27, v27, v91
	v_exp_f32_e32 v94, v94
	v_add_f32_e32 v27, v27, v92
	v_exp_f32_e32 v95, v95
	v_add_f32_e32 v27, v27, v93
	s_waitcnt vmcnt(6)
	s_barrier
	v_mfma_f32_32x32x16_bf16 v[142:157], v[194:197], v[130:133], v[142:157]
	s_add_u32 m0, s57, 0x2000
	v_exp_f32_e32 v96, v96
	v_add_f32_e32 v27, v27, v94
	global_load_lds_dwordx4 v[28:29], off
	v_lshl_add_u64 v[28:29], v[28:29], 0, s[30:31]
	v_exp_f32_e32 v97, v97
	v_add_f32_e32 v27, v27, v95
	v_add_f32_e32 v27, v27, v96
	ds_read_b64_tr_b16 v[114:115], v2 offset:49152
	ds_read_b64_tr_b16 v[116:117], v2 offset:49664
	ds_read_b64_tr_b16 v[118:119], v2 offset:50176
	ds_read_b64_tr_b16 v[120:121], v2 offset:50688
	v_mfma_f32_32x32x16_bf16 v[158:173], v[190:193], v[130:133], v[158:173]
	s_add_u32 m0, s40, 0x9000
	v_add_f32_e32 v27, v27, v97
	v_cvt_pk_bf16_f32 v90, v90, v91
	global_load_lds_dwordx4 v[24:25], off
	v_lshl_add_u64 v[24:25], v[24:25], 0, s[30:31]
	v_cvt_pk_bf16_f32 v91, v92, v93
	v_cvt_pk_bf16_f32 v92, v94, v95
	v_cvt_pk_bf16_f32 v93, v96, v97
	ds_read_b64_tr_b16 v[122:123], v2 offset:51200
	ds_read_b64_tr_b16 v[124:125], v2 offset:51712
	ds_read_b64_tr_b16 v[126:127], v2 offset:52224
	ds_read_b64_tr_b16 v[128:129], v2 offset:52736
	v_mfma_f32_32x32x16_bf16 v[142:157], v[186:189], v[134:137], v[142:157]
	s_add_u32 m0, s43, 0x9000
	v_exp_f32_e32 v98, v98
	v_exp_f32_e32 v99, v99
	global_load_lds_dwordx4 v[30:31], off
	v_lshl_add_u64 v[30:31], v[30:31], 0, s[12:13]
	v_exp_f32_e32 v100, v100
	v_add_f32_e32 v27, v27, v98
	v_exp_f32_e32 v101, v101
	ds_read_b64_tr_b16 v[240:241], v2 offset:53248
	ds_read_b64_tr_b16 v[242:243], v2 offset:53760
	ds_read_b64_tr_b16 v[244:245], v2 offset:54272
	ds_read_b64_tr_b16 v[246:247], v2 offset:54784
	v_mfma_f32_32x32x16_bf16 v[158:173], v[182:185], v[134:137], v[158:173]
	v_add_f32_e32 v27, v27, v99
	v_exp_f32_e32 v102, v102
	v_add_f32_e32 v27, v27, v100
	v_exp_f32_e32 v103, v103
	v_add_f32_e32 v27, v27, v101
	ds_read_b64_tr_b16 v[248:249], v2 offset:55296
	ds_read_b64_tr_b16 v[250:251], v2 offset:55808
	ds_read_b64_tr_b16 v[20:21], v2 offset:56320
	ds_read_b64_tr_b16 v[22:23], v2 offset:56832
	v_mfma_f32_32x32x16_bf16 v[142:157], v[178:181], v[138:141], v[142:157]
	v_exp_f32_e32 v104, v104
	v_add_f32_e32 v27, v27, v102
	v_exp_f32_e32 v105, v105
	v_add_f32_e32 v27, v27, v103
	v_add_f32_e32 v27, v27, v104
	v_mfma_f32_32x32x16_bf16 v[158:173], v[174:177], v[138:141], v[158:173]
	v_add_f32_e32 v27, v27, v105
	v_cvt_pk_bf16_f32 v98, v98, v99
	v_cvt_pk_bf16_f32 v99, v100, v101
	v_cvt_pk_bf16_f32 v100, v102, v103
	v_cvt_pk_bf16_f32 v101, v104, v105
	s_waitcnt lgkmcnt(0)
	v_mov_b32_e32 v2, v238
	v_mfma_f32_32x32x16_bf16 v[34:49], v[82:85], v[114:117], v[34:49]
	v_exp_f32_e32 v106, v106
	v_exp_f32_e32 v107, v107
	v_exp_f32_e32 v108, v108
	v_add_f32_e32 v27, v27, v106
	v_exp_f32_e32 v109, v109
	ds_read_b128 v[218:221], v2
	ds_read_b128 v[214:217], v2 offset:512
	ds_read_b128 v[210:213], v2 offset:2048
	v_mfma_f32_32x32x16_bf16 v[50:65], v[82:85], v[240:243], v[50:65]
	v_add_f32_e32 v27, v27, v107
	v_exp_f32_e32 v110, v110
	v_add_f32_e32 v27, v27, v108
	v_exp_f32_e32 v111, v111
	v_add_f32_e32 v27, v27, v109
	ds_read_b128 v[206:209], v2 offset:2560
	ds_read_b128 v[202:205], v2 offset:4096
	ds_read_b128 v[198:201], v2 offset:4608
	v_mfma_f32_32x32x16_bf16 v[34:49], v[90:93], v[118:121], v[34:49]
	v_exp_f32_e32 v112, v112
	v_add_f32_e32 v27, v27, v110
	v_exp_f32_e32 v113, v113
	v_add_f32_e32 v27, v27, v111
	v_add_f32_e32 v27, v27, v112
	ds_read_b128 v[194:197], v2 offset:6144
	ds_read_b128 v[190:193], v2 offset:6656
	ds_read_b128 v[186:189], v2 offset:8192
	v_mfma_f32_32x32x16_bf16 v[50:65], v[90:93], v[244:247], v[50:65]
	v_add_f32_e32 v27, v27, v113
	v_cvt_pk_bf16_f32 v106, v106, v107
	v_cvt_pk_bf16_f32 v107, v108, v109
	v_cvt_pk_bf16_f32 v108, v110, v111
	v_cvt_pk_bf16_f32 v109, v112, v113
	v_add_f32_e32 v236, v236, v27
	ds_read_b128 v[182:185], v2 offset:8704
	ds_read_b128 v[178:181], v2 offset:10240
	ds_read_b128 v[174:177], v2 offset:10752
	v_mfma_f32_32x32x16_bf16 v[34:49], v[98:101], v[122:125], v[34:49]
	v_max3_f32 v19, v142, v143, v144
	v_max3_f32 v26, v145, v146, v147
	v_max3_f32 v19, v19, v148, v149
	v_max3_f32 v26, v26, v150, v151
	v_mfma_f32_32x32x16_bf16 v[50:65], v[98:101], v[248:251], v[50:65]
	v_max3_f32 v19, v19, v152, v153
	v_max3_f32 v26, v26, v154, v155
	v_max3_f32 v19, v19, v156, v157
	v_max3_f32 v26, v26, v158, v159
	v_mfma_f32_32x32x16_bf16 v[34:49], v[106:109], v[126:129], v[34:49]
	v_max3_f32 v19, v19, v160, v161
	v_max3_f32 v26, v26, v162, v163
	v_max3_f32 v19, v19, v164, v165
	v_max3_f32 v26, v26, v166, v167
	v_mfma_f32_32x32x16_bf16 v[50:65], v[106:109], v[20:23], v[50:65]
	v_max3_f32 v19, v19, v168, v169
	v_max3_f32 v26, v26, v170, v171
	v_max3_f32 v19, v19, v172, v173
	v_max_f32_e32 v19, v19, v26
	v_cmp_lt_f32_e32 vcc, s41, v19
	s_cbranch_vccz .Lmy_nors_9
	s_nop 15
	s_nop 15
	v_mov_b32_e32 v26, v19
	s_nop 1
	v_permlane32_swap_b32_e32 v19, v26
	v_max_f32_e32 v19, v19, v26
	v_max_f32_e32 v19, v19, v19
	v_max_f32_e32 v90, 0, v19
	v_exp_f32_e64 v91, -v90
	v_add_f32_e32 v239, v239, v90
	v_xor_b32_e32 v66, 0x80000000, v239
	v_mov_b32_e32 v67, v66
	v_mov_b32_e32 v68, v66
	v_mov_b32_e32 v69, v66
	v_mov_b32_e32 v70, v66
	v_mov_b32_e32 v71, v66
	v_mov_b32_e32 v72, v66
	v_mov_b32_e32 v73, v66
	v_mov_b32_e32 v74, v66
	v_mov_b32_e32 v75, v66
	v_mov_b32_e32 v76, v66
	v_mov_b32_e32 v77, v66
	v_mov_b32_e32 v78, v66
	v_mov_b32_e32 v79, v66
	v_mov_b32_e32 v80, v66
	v_mov_b32_e32 v81, v66
	v_sub_f32_e32 v142, v142, v90
	v_sub_f32_e32 v143, v143, v90
	v_sub_f32_e32 v144, v144, v90
	v_sub_f32_e32 v145, v145, v90
	v_sub_f32_e32 v146, v146, v90
	v_sub_f32_e32 v147, v147, v90
	v_sub_f32_e32 v148, v148, v90
	v_sub_f32_e32 v149, v149, v90
	v_sub_f32_e32 v150, v150, v90
	v_sub_f32_e32 v151, v151, v90
	v_sub_f32_e32 v152, v152, v90
	v_sub_f32_e32 v153, v153, v90
	v_sub_f32_e32 v154, v154, v90
	v_sub_f32_e32 v155, v155, v90
	v_sub_f32_e32 v156, v156, v90
	v_sub_f32_e32 v157, v157, v90
	v_sub_f32_e32 v158, v158, v90
	v_sub_f32_e32 v159, v159, v90
	v_sub_f32_e32 v160, v160, v90
	v_sub_f32_e32 v161, v161, v90
	v_sub_f32_e32 v162, v162, v90
	v_sub_f32_e32 v163, v163, v90
	v_sub_f32_e32 v164, v164, v90
	v_sub_f32_e32 v165, v165, v90
	v_sub_f32_e32 v166, v166, v90
	v_sub_f32_e32 v167, v167, v90
	v_sub_f32_e32 v168, v168, v90
	v_sub_f32_e32 v169, v169, v90
	v_sub_f32_e32 v170, v170, v90
	v_sub_f32_e32 v171, v171, v90
	v_sub_f32_e32 v172, v172, v90
	v_sub_f32_e32 v173, v173, v90
	v_mul_f32_e32 v236, v236, v91
	s_mov_b64 s[96:97], exec
	s_and_b64 exec, exec, s[8:9]
	ds_write_b32 v235, v91
	s_mov_b64 exec, s[96:97]
	v_lshl_add_u32 v2, v228, 4, s47
	ds_read_b128 v[94:97], v2 offset:0
	s_waitcnt lgkmcnt(0)
	v_mul_f32_e32 v34, v34, v94
	v_mul_f32_e32 v50, v50, v94
	v_mul_f32_e32 v35, v35, v95
	v_mul_f32_e32 v51, v51, v95
	v_mul_f32_e32 v36, v36, v96
	v_mul_f32_e32 v52, v52, v96
	v_mul_f32_e32 v37, v37, v97
	v_mul_f32_e32 v53, v53, v97
	ds_read_b128 v[94:97], v2 offset:32
	s_waitcnt lgkmcnt(0)
	v_mul_f32_e32 v38, v38, v94
	v_mul_f32_e32 v54, v54, v94
	v_mul_f32_e32 v39, v39, v95
	v_mul_f32_e32 v55, v55, v95
	v_mul_f32_e32 v40, v40, v96
	v_mul_f32_e32 v56, v56, v96
	v_mul_f32_e32 v41, v41, v97
	v_mul_f32_e32 v57, v57, v97
	ds_read_b128 v[94:97], v2 offset:64
	s_waitcnt lgkmcnt(0)
	v_mul_f32_e32 v42, v42, v94
	v_mul_f32_e32 v58, v58, v94
	v_mul_f32_e32 v43, v43, v95
	v_mul_f32_e32 v59, v59, v95
	v_mul_f32_e32 v44, v44, v96
	v_mul_f32_e32 v60, v60, v96
	v_mul_f32_e32 v45, v45, v97
	v_mul_f32_e32 v61, v61, v97
	ds_read_b128 v[94:97], v2 offset:96
	s_waitcnt lgkmcnt(0)
	v_mul_f32_e32 v46, v46, v94
	v_mul_f32_e32 v62, v62, v94
	v_mul_f32_e32 v47, v47, v95
	v_mul_f32_e32 v63, v63, v95
	v_mul_f32_e32 v48, v48, v96
	v_mul_f32_e32 v64, v64, v96
	v_mul_f32_e32 v49, v49, v97
	v_mul_f32_e32 v65, v65, v97

.Lmy_ts_14:
	s_waitcnt lgkmcnt(0)
	s_waitcnt vmcnt(3)
	s_barrier
	s_add_u32 m0, s57, 0x6000
	s_nop 0
	global_load_lds_dwordx4 v[28:29], off
	v_lshl_add_u64 v[28:29], v[28:29], 0, s[30:31]
	v_mov_b32_e32 v2, v237
	ds_read_b64_tr_b16 v[114:115], v2 offset:49152
	ds_read_b64_tr_b16 v[116:117], v2 offset:49664
	ds_read_b64_tr_b16 v[118:119], v2 offset:50176
	ds_read_b64_tr_b16 v[120:121], v2 offset:50688
	ds_read_b64_tr_b16 v[122:123], v2 offset:51200
	ds_read_b64_tr_b16 v[124:125], v2 offset:51712
	ds_read_b64_tr_b16 v[126:127], v2 offset:52224
	ds_read_b64_tr_b16 v[128:129], v2 offset:52736
	ds_read_b64_tr_b16 v[240:241], v2 offset:53248
	ds_read_b64_tr_b16 v[242:243], v2 offset:53760
	ds_read_b64_tr_b16 v[244:245], v2 offset:54272
	ds_read_b64_tr_b16 v[246:247], v2 offset:54784
	ds_read_b64_tr_b16 v[248:249], v2 offset:55296
	ds_read_b64_tr_b16 v[250:251], v2 offset:55808
	ds_read_b64_tr_b16 v[20:21], v2 offset:56320
	ds_read_b64_tr_b16 v[22:23], v2 offset:56832
	v_exp_f32_e32 v82, v82
	v_exp_f32_e32 v83, v83
	v_exp_f32_e32 v84, v84
	v_add_f32_e32 v27, v82, v83
	v_exp_f32_e32 v85, v85
	v_exp_f32_e32 v86, v86
	v_add_f32_e32 v27, v27, v84
	v_exp_f32_e32 v87, v87
	v_add_f32_e32 v27, v27, v85
	v_exp_f32_e32 v88, v88
	v_add_f32_e32 v27, v27, v86
	v_exp_f32_e32 v89, v89
	v_add_f32_e32 v27, v27, v87
	v_add_f32_e32 v27, v27, v88
	v_add_f32_e32 v27, v27, v89
	v_cvt_pk_bf16_f32 v82, v82, v83
	v_cvt_pk_bf16_f32 v83, v84, v85
	v_cvt_pk_bf16_f32 v84, v86, v87
	v_cvt_pk_bf16_f32 v85, v88, v89
	v_exp_f32_e32 v90, v90
	v_exp_f32_e32 v91, v91
	v_exp_f32_e32 v92, v92
	v_add_f32_e32 v27, v27, v90
	v_exp_f32_e32 v93, v93
	v_add_f32_e32 v27, v27, v91
	v_exp_f32_e32 v94, v94
	v_add_f32_e32 v27, v27, v92
	v_exp_f32_e32 v95, v95
	v_add_f32_e32 v27, v27, v93
	v_exp_f32_e32 v96, v96
	v_add_f32_e32 v27, v27, v94
	v_exp_f32_e32 v97, v97
	v_add_f32_e32 v27, v27, v95
	v_add_f32_e32 v27, v27, v96
	v_add_f32_e32 v27, v27, v97
	v_cvt_pk_bf16_f32 v90, v90, v91
	v_cvt_pk_bf16_f32 v91, v92, v93
	v_cvt_pk_bf16_f32 v92, v94, v95
	v_cvt_pk_bf16_f32 v93, v96, v97
	s_waitcnt lgkmcnt(0)
	v_mfma_f32_32x32x16_bf16 v[34:49], v[82:85], v[114:117], v[34:49]
	v_mfma_f32_32x32x16_bf16 v[50:65], v[82:85], v[240:243], v[50:65]
	v_exp_f32_e32 v98, v98
	v_exp_f32_e32 v99, v99
	v_exp_f32_e32 v100, v100
	v_add_f32_e32 v27, v27, v98
	v_exp_f32_e32 v101, v101
	v_add_f32_e32 v27, v27, v99
	v_exp_f32_e32 v102, v102
	v_add_f32_e32 v27, v27, v100
	v_exp_f32_e32 v103, v103
	v_add_f32_e32 v27, v27, v101
	v_exp_f32_e32 v104, v104
	v_add_f32_e32 v27, v27, v102
	v_exp_f32_e32 v105, v105
	v_add_f32_e32 v27, v27, v103
	v_add_f32_e32 v27, v27, v104
	v_add_f32_e32 v27, v27, v105
	v_cvt_pk_bf16_f32 v98, v98, v99
	v_cvt_pk_bf16_f32 v99, v100, v101
	v_cvt_pk_bf16_f32 v100, v102, v103
	v_cvt_pk_bf16_f32 v101, v104, v105
	v_mfma_f32_32x32x16_bf16 v[34:49], v[90:93], v[118:121], v[34:49]
	v_mfma_f32_32x32x16_bf16 v[50:65], v[90:93], v[244:247], v[50:65]
	v_exp_f32_e32 v106, v106
	v_exp_f32_e32 v107, v107
	v_exp_f32_e32 v108, v108
	v_add_f32_e32 v27, v27, v106
	v_exp_f32_e32 v109, v109
	v_add_f32_e32 v27, v27, v107
	v_exp_f32_e32 v110, v110
	v_add_f32_e32 v27, v27, v108
	v_exp_f32_e32 v111, v111
	v_add_f32_e32 v27, v27, v109
	v_exp_f32_e32 v112, v112
	v_add_f32_e32 v27, v27, v110
	v_exp_f32_e32 v113, v113
	v_add_f32_e32 v27, v27, v111
	v_add_f32_e32 v27, v27, v112
	v_add_f32_e32 v27, v27, v113
	v_cvt_pk_bf16_f32 v106, v106, v107
	v_cvt_pk_bf16_f32 v107, v108, v109
	v_cvt_pk_bf16_f32 v108, v110, v111
	v_cvt_pk_bf16_f32 v109, v112, v113
	v_add_f32_e32 v236, v236, v27
	s_nop 1
	v_mfma_f32_32x32x16_bf16 v[34:49], v[98:101], v[122:125], v[34:49]
	v_mfma_f32_32x32x16_bf16 v[50:65], v[98:101], v[248:251], v[50:65]
	v_mfma_f32_32x32x16_bf16 v[34:49], v[106:109], v[126:129], v[34:49]
	v_mfma_f32_32x32x16_bf16 v[50:65], v[106:109], v[20:23], v[50:65]
	s_branch .Lmy_te_15
.Lmy_tf_13:
	s_waitcnt lgkmcnt(0)
	v_mov_b32_e32 v2, v237
	v_mfma_f32_32x32x16_bf16 v[142:157], v[218:221], v[4:7], v[66:81]
	v_exp_f32_e32 v82, v82
	v_exp_f32_e32 v83, v83
	v_exp_f32_e32 v84, v84
	v_add_f32_e32 v27, v82, v83
	v_exp_f32_e32 v85, v85
	v_mfma_f32_32x32x16_bf16 v[158:173], v[214:217], v[4:7], v[66:81]
	v_exp_f32_e32 v86, v86
	v_add_f32_e32 v27, v27, v84
	v_exp_f32_e32 v87, v87
	v_add_f32_e32 v27, v27, v85
	v_exp_f32_e32 v88, v88
	v_mfma_f32_32x32x16_bf16 v[142:157], v[210:213], v[8:11], v[142:157]
	v_add_f32_e32 v27, v27, v86
	v_exp_f32_e32 v89, v89
	v_add_f32_e32 v27, v27, v87
	v_add_f32_e32 v27, v27, v88
	v_add_f32_e32 v27, v27, v89
	v_mfma_f32_32x32x16_bf16 v[158:173], v[206:209], v[8:11], v[158:173]
	v_cvt_pk_bf16_f32 v82, v82, v83
	v_cvt_pk_bf16_f32 v83, v84, v85
	v_cvt_pk_bf16_f32 v84, v86, v87
	v_cvt_pk_bf16_f32 v85, v88, v89
	v_mfma_f32_32x32x16_bf16 v[142:157], v[202:205], v[12:15], v[142:157]
	v_exp_f32_e32 v90, v90
	v_exp_f32_e32 v91, v91
	v_exp_f32_e32 v92, v92
	v_add_f32_e32 v27, v27, v90
	v_exp_f32_e32 v93, v93
	v_mfma_f32_32x32x16_bf16 v[158:173], v[198:201], v[12:15], v[158:173]
	v_add_f32_e32 v27, v27, v91
	v_exp_f32_e32 v94, v94
	v_add_f32_e32 v27, v27, v92
	v_exp_f32_e32 v95, v95
	v_add_f32_e32 v27, v27, v93
	s_waitcnt vmcnt(3)
	s_barrier
	v_mfma_f32_32x32x16_bf16 v[142:157], v[194:197], v[130:133], v[142:157]
	s_add_u32 m0, s57, 0x6000
	v_exp_f32_e32 v96, v96
	v_add_f32_e32 v27, v27, v94
	global_load_lds_dwordx4 v[28:29], off
	v_lshl_add_u64 v[28:29], v[28:29], 0, s[30:31]
	v_exp_f32_e32 v97, v97
	v_add_f32_e32 v27, v27, v95
	v_add_f32_e32 v27, v27, v96
	ds_read_b64_tr_b16 v[114:115], v2 offset:49152
	ds_read_b64_tr_b16 v[116:117], v2 offset:49664
	ds_read_b64_tr_b16 v[118:119], v2 offset:50176
	ds_read_b64_tr_b16 v[120:121], v2 offset:50688
	v_mfma_f32_32x32x16_bf16 v[158:173], v[190:193], v[130:133], v[158:173]
	v_add_f32_e32 v27, v27, v97
	v_cvt_pk_bf16_f32 v90, v90, v91
	v_cvt_pk_bf16_f32 v91, v92, v93
	v_cvt_pk_bf16_f32 v92, v94, v95
	v_cvt_pk_bf16_f32 v93, v96, v97
	ds_read_b64_tr_b16 v[122:123], v2 offset:51200
	ds_read_b64_tr_b16 v[124:125], v2 offset:51712
	ds_read_b64_tr_b16 v[126:127], v2 offset:52224
	ds_read_b64_tr_b16 v[128:129], v2 offset:52736
	v_mfma_f32_32x32x16_bf16 v[142:157], v[186:189], v[134:137], v[142:157]
	v_exp_f32_e32 v98, v98
	v_exp_f32_e32 v99, v99
	v_exp_f32_e32 v100, v100
	v_add_f32_e32 v27, v27, v98
	v_exp_f32_e32 v101, v101
	ds_read_b64_tr_b16 v[240:241], v2 offset:53248
	ds_read_b64_tr_b16 v[242:243], v2 offset:53760
	ds_read_b64_tr_b16 v[244:245], v2 offset:54272
	ds_read_b64_tr_b16 v[246:247], v2 offset:54784
	v_mfma_f32_32x32x16_bf16 v[158:173], v[182:185], v[134:137], v[158:173]
	v_add_f32_e32 v27, v27, v99
	v_exp_f32_e32 v102, v102
	v_add_f32_e32 v27, v27, v100
	v_exp_f32_e32 v103, v103
	v_add_f32_e32 v27, v27, v101
	ds_read_b64_tr_b16 v[248:249], v2 offset:55296
	ds_read_b64_tr_b16 v[250:251], v2 offset:55808
	ds_read_b64_tr_b16 v[20:21], v2 offset:56320
	ds_read_b64_tr_b16 v[22:23], v2 offset:56832
	v_mfma_f32_32x32x16_bf16 v[142:157], v[178:181], v[138:141], v[142:157]
	v_exp_f32_e32 v104, v104
	v_add_f32_e32 v27, v27, v102
	v_exp_f32_e32 v105, v105
	v_add_f32_e32 v27, v27, v103
	v_add_f32_e32 v27, v27, v104
	v_mfma_f32_32x32x16_bf16 v[158:173], v[174:177], v[138:141], v[158:173]
	v_add_f32_e32 v27, v27, v105
	v_cvt_pk_bf16_f32 v98, v98, v99
	v_cvt_pk_bf16_f32 v99, v100, v101
	v_cvt_pk_bf16_f32 v100, v102, v103
	v_cvt_pk_bf16_f32 v101, v104, v105
	s_waitcnt lgkmcnt(0)
	v_add_u32_e32 v2, 0x6000, v238
	v_mfma_f32_32x32x16_bf16 v[34:49], v[82:85], v[114:117], v[34:49]
	v_exp_f32_e32 v106, v106
	v_exp_f32_e32 v107, v107
	v_exp_f32_e32 v108, v108
	v_add_f32_e32 v27, v27, v106
	v_exp_f32_e32 v109, v109
	s_cmp_gt_u32 s71, 1
	s_cbranch_scc0 .Lmy_nok_16
	ds_read_b128 v[218:221], v2
	ds_read_b128 v[214:217], v2 offset:512
	ds_read_b128 v[210:213], v2 offset:2048
	ds_read_b128 v[206:209], v2 offset:2560
	ds_read_b128 v[202:205], v2 offset:4096
	ds_read_b128 v[198:201], v2 offset:4608
	ds_read_b128 v[194:197], v2 offset:6144
	ds_read_b128 v[190:193], v2 offset:6656
	ds_read_b128 v[186:189], v2 offset:8192
	ds_read_b128 v[182:185], v2 offset:8704
	ds_read_b128 v[178:181], v2 offset:10240
	ds_read_b128 v[174:177], v2 offset:10752

.Lmy_ts_19:
	s_waitcnt lgkmcnt(0)
	s_waitcnt vmcnt(1)
	s_barrier
	v_add_u32_e32 v2, 0x2000, v237
	ds_read_b64_tr_b16 v[114:115], v2 offset:49152
	ds_read_b64_tr_b16 v[116:117], v2 offset:49664
	ds_read_b64_tr_b16 v[118:119], v2 offset:50176
	ds_read_b64_tr_b16 v[120:121], v2 offset:50688
	ds_read_b64_tr_b16 v[122:123], v2 offset:51200
	ds_read_b64_tr_b16 v[124:125], v2 offset:51712
	ds_read_b64_tr_b16 v[126:127], v2 offset:52224
	ds_read_b64_tr_b16 v[128:129], v2 offset:52736
	ds_read_b64_tr_b16 v[240:241], v2 offset:53248
	ds_read_b64_tr_b16 v[242:243], v2 offset:53760
	ds_read_b64_tr_b16 v[244:245], v2 offset:54272
	ds_read_b64_tr_b16 v[246:247], v2 offset:54784
	ds_read_b64_tr_b16 v[248:249], v2 offset:55296
	ds_read_b64_tr_b16 v[250:251], v2 offset:55808
	ds_read_b64_tr_b16 v[20:21], v2 offset:56320
	ds_read_b64_tr_b16 v[22:23], v2 offset:56832
	v_exp_f32_e32 v142, v142
	v_exp_f32_e32 v143, v143
	v_exp_f32_e32 v144, v144
	v_add_f32_e32 v27, v142, v143
	v_exp_f32_e32 v145, v145
	v_exp_f32_e32 v146, v146
	v_add_f32_e32 v27, v27, v144
	v_exp_f32_e32 v147, v147
	v_add_f32_e32 v27, v27, v145
	v_exp_f32_e32 v148, v148
	v_add_f32_e32 v27, v27, v146
	v_exp_f32_e32 v149, v149
	v_add_f32_e32 v27, v27, v147
	v_add_f32_e32 v27, v27, v148
	v_add_f32_e32 v27, v27, v149
	v_cvt_pk_bf16_f32 v142, v142, v143
	v_cvt_pk_bf16_f32 v143, v144, v145
	v_cvt_pk_bf16_f32 v144, v146, v147
	v_cvt_pk_bf16_f32 v145, v148, v149
	v_exp_f32_e32 v150, v150
	v_exp_f32_e32 v151, v151
	v_exp_f32_e32 v152, v152
	v_add_f32_e32 v27, v27, v150
	v_exp_f32_e32 v153, v153
	v_add_f32_e32 v27, v27, v151
	v_exp_f32_e32 v154, v154
	v_add_f32_e32 v27, v27, v152
	v_exp_f32_e32 v155, v155
	v_add_f32_e32 v27, v27, v153
	v_exp_f32_e32 v156, v156
	v_add_f32_e32 v27, v27, v154
	v_exp_f32_e32 v157, v157
	v_add_f32_e32 v27, v27, v155
	v_add_f32_e32 v27, v27, v156
	v_add_f32_e32 v27, v27, v157
	v_cvt_pk_bf16_f32 v150, v150, v151
	v_cvt_pk_bf16_f32 v151, v152, v153
	v_cvt_pk_bf16_f32 v152, v154, v155
	v_cvt_pk_bf16_f32 v153, v156, v157
	s_waitcnt lgkmcnt(0)
	v_mfma_f32_32x32x16_bf16 v[34:49], v[142:145], v[114:117], v[34:49]
	v_mfma_f32_32x32x16_bf16 v[50:65], v[142:145], v[240:243], v[50:65]
	v_exp_f32_e32 v158, v158
	v_exp_f32_e32 v159, v159
	v_exp_f32_e32 v160, v160
	v_add_f32_e32 v27, v27, v158
	v_exp_f32_e32 v161, v161
	v_add_f32_e32 v27, v27, v159
	v_exp_f32_e32 v162, v162
	v_add_f32_e32 v27, v27, v160
	v_exp_f32_e32 v163, v163
	v_add_f32_e32 v27, v27, v161
	v_exp_f32_e32 v164, v164
	v_add_f32_e32 v27, v27, v162
	v_exp_f32_e32 v165, v165
	v_add_f32_e32 v27, v27, v163
	v_add_f32_e32 v27, v27, v164
	v_add_f32_e32 v27, v27, v165
	v_cvt_pk_bf16_f32 v158, v158, v159
	v_cvt_pk_bf16_f32 v159, v160, v161
	v_cvt_pk_bf16_f32 v160, v162, v163
	v_cvt_pk_bf16_f32 v161, v164, v165
	v_mfma_f32_32x32x16_bf16 v[34:49], v[150:153], v[118:121], v[34:49]
	v_mfma_f32_32x32x16_bf16 v[50:65], v[150:153], v[244:247], v[50:65]
	v_exp_f32_e32 v166, v166
	v_exp_f32_e32 v167, v167
	v_exp_f32_e32 v168, v168
	v_add_f32_e32 v27, v27, v166
	v_exp_f32_e32 v169, v169
	v_add_f32_e32 v27, v27, v167
	v_exp_f32_e32 v170, v170
	v_add_f32_e32 v27, v27, v168
	v_exp_f32_e32 v171, v171
	v_add_f32_e32 v27, v27, v169
	v_exp_f32_e32 v172, v172
	v_add_f32_e32 v27, v27, v170
	v_exp_f32_e32 v173, v173
	v_add_f32_e32 v27, v27, v171
	v_add_f32_e32 v27, v27, v172
	v_add_f32_e32 v27, v27, v173
	v_cvt_pk_bf16_f32 v166, v166, v167
	v_cvt_pk_bf16_f32 v167, v168, v169
	v_cvt_pk_bf16_f32 v168, v170, v171
	v_cvt_pk_bf16_f32 v169, v172, v173
	v_add_f32_e32 v236, v236, v27
	s_nop 1
	v_mfma_f32_32x32x16_bf16 v[34:49], v[158:161], v[122:125], v[34:49]
	v_mfma_f32_32x32x16_bf16 v[50:65], v[158:161], v[248:251], v[50:65]
	v_mfma_f32_32x32x16_bf16 v[34:49], v[166:169], v[126:129], v[34:49]
	v_mfma_f32_32x32x16_bf16 v[50:65], v[166:169], v[20:23], v[50:65]
	s_branch .Lmy_te_20
.Lmy_tf_18:
	s_waitcnt lgkmcnt(0)
	v_add_u32_e32 v2, 0x2000, v237
	v_mfma_f32_32x32x16_bf16 v[82:97], v[218:221], v[4:7], v[66:81]
	v_exp_f32_e32 v142, v142
	v_exp_f32_e32 v143, v143
	v_exp_f32_e32 v144, v144
	v_add_f32_e32 v27, v142, v143
	v_exp_f32_e32 v145, v145
	v_mfma_f32_32x32x16_bf16 v[98:113], v[214:217], v[4:7], v[66:81]
	v_exp_f32_e32 v146, v146
	v_add_f32_e32 v27, v27, v144
	v_exp_f32_e32 v147, v147
	v_add_f32_e32 v27, v27, v145
	v_exp_f32_e32 v148, v148
	v_mfma_f32_32x32x16_bf16 v[82:97], v[210:213], v[8:11], v[82:97]
	v_add_f32_e32 v27, v27, v146
	v_exp_f32_e32 v149, v149
	v_add_f32_e32 v27, v27, v147
	v_add_f32_e32 v27, v27, v148
	v_add_f32_e32 v27, v27, v149
	v_mfma_f32_32x32x16_bf16 v[98:113], v[206:209], v[8:11], v[98:113]
	v_cvt_pk_bf16_f32 v142, v142, v143
	v_cvt_pk_bf16_f32 v143, v144, v145
	v_cvt_pk_bf16_f32 v144, v146, v147
	v_cvt_pk_bf16_f32 v145, v148, v149
	v_mfma_f32_32x32x16_bf16 v[82:97], v[202:205], v[12:15], v[82:97]
	v_exp_f32_e32 v150, v150
	v_exp_f32_e32 v151, v151
	v_exp_f32_e32 v152, v152
	v_add_f32_e32 v27, v27, v150
	v_exp_f32_e32 v153, v153
	v_mfma_f32_32x32x16_bf16 v[98:113], v[198:201], v[12:15], v[98:113]
	v_add_f32_e32 v27, v27, v151
	v_exp_f32_e32 v154, v154
	v_add_f32_e32 v27, v27, v152
	v_exp_f32_e32 v155, v155
	v_add_f32_e32 v27, v27, v153
	s_waitcnt vmcnt(1)
	s_barrier
	v_mfma_f32_32x32x16_bf16 v[82:97], v[194:197], v[130:133], v[82:97]
	v_exp_f32_e32 v156, v156
	v_add_f32_e32 v27, v27, v154
	v_exp_f32_e32 v157, v157
	v_add_f32_e32 v27, v27, v155
	v_add_f32_e32 v27, v27, v156
	ds_read_b64_tr_b16 v[114:115], v2 offset:49152
	ds_read_b64_tr_b16 v[116:117], v2 offset:49664
	ds_read_b64_tr_b16 v[118:119], v2 offset:50176
	ds_read_b64_tr_b16 v[120:121], v2 offset:50688
	v_mfma_f32_32x32x16_bf16 v[98:113], v[190:193], v[130:133], v[98:113]
	v_add_f32_e32 v27, v27, v157
	v_cvt_pk_bf16_f32 v150, v150, v151
	v_cvt_pk_bf16_f32 v151, v152, v153
	v_cvt_pk_bf16_f32 v152, v154, v155
	v_cvt_pk_bf16_f32 v153, v156, v157
	ds_read_b64_tr_b16 v[122:123], v2 offset:51200
	ds_read_b64_tr_b16 v[124:125], v2 offset:51712
	ds_read_b64_tr_b16 v[126:127], v2 offset:52224
	ds_read_b64_tr_b16 v[128:129], v2 offset:52736
	v_mfma_f32_32x32x16_bf16 v[82:97], v[186:189], v[134:137], v[82:97]
	v_exp_f32_e32 v158, v158
	v_exp_f32_e32 v159, v159
	v_exp_f32_e32 v160, v160
	v_add_f32_e32 v27, v27, v158
	v_exp_f32_e32 v161, v161
	ds_read_b64_tr_b16 v[240:241], v2 offset:53248
	ds_read_b64_tr_b16 v[242:243], v2 offset:53760
	ds_read_b64_tr_b16 v[244:245], v2 offset:54272
	ds_read_b64_tr_b16 v[246:247], v2 offset:54784
	v_mfma_f32_32x32x16_bf16 v[98:113], v[182:185], v[134:137], v[98:113]
	v_add_f32_e32 v27, v27, v159
	v_exp_f32_e32 v162, v162
	v_add_f32_e32 v27, v27, v160
	v_exp_f32_e32 v163, v163
	v_add_f32_e32 v27, v27, v161
	ds_read_b64_tr_b16 v[248:249], v2 offset:55296
	ds_read_b64_tr_b16 v[250:251], v2 offset:55808
	ds_read_b64_tr_b16 v[20:21], v2 offset:56320
	ds_read_b64_tr_b16 v[22:23], v2 offset:56832
	v_mfma_f32_32x32x16_bf16 v[82:97], v[178:181], v[138:141], v[82:97]
	v_exp_f32_e32 v164, v164
	v_add_f32_e32 v27, v27, v162
	v_exp_f32_e32 v165, v165
	v_add_f32_e32 v27, v27, v163
	v_add_f32_e32 v27, v27, v164
	v_mfma_f32_32x32x16_bf16 v[98:113], v[174:177], v[138:141], v[98:113]
	v_add_f32_e32 v27, v27, v165
	v_cvt_pk_bf16_f32 v158, v158, v159
	v_cvt_pk_bf16_f32 v159, v160, v161
	v_cvt_pk_bf16_f32 v160, v162, v163
	v_cvt_pk_bf16_f32 v161, v164, v165
	s_waitcnt lgkmcnt(0)
	v_add_u32_e32 v2, 0x9000, v238
	v_mfma_f32_32x32x16_bf16 v[34:49], v[142:145], v[114:117], v[34:49]
	v_exp_f32_e32 v166, v166
	v_exp_f32_e32 v167, v167
	v_exp_f32_e32 v168, v168
	v_add_f32_e32 v27, v27, v166
	v_exp_f32_e32 v169, v169
	s_cmp_gt_u32 s71, 2
	s_cbranch_scc0 .Lmy_nok_21
	ds_read_b128 v[218:221], v2
	ds_read_b128 v[214:217], v2 offset:512
	ds_read_b128 v[210:213], v2 offset:2048
	ds_read_b128 v[206:209], v2 offset:2560
	ds_read_b128 v[202:205], v2 offset:4096
	ds_read_b128 v[198:201], v2 offset:4608
	ds_read_b128 v[194:197], v2 offset:6144
	ds_read_b128 v[190:193], v2 offset:6656
	ds_read_b128 v[186:189], v2 offset:8192
	ds_read_b128 v[182:185], v2 offset:8704
	ds_read_b128 v[178:181], v2 offset:10240
	ds_read_b128 v[174:177], v2 offset:10752

.Lmy_ts_24:
	s_waitcnt lgkmcnt(0)
	s_waitcnt vmcnt(0)
	s_barrier
	v_add_u32_e32 v2, 0x4000, v237
	ds_read_b64_tr_b16 v[114:115], v2 offset:49152
	ds_read_b64_tr_b16 v[116:117], v2 offset:49664
	ds_read_b64_tr_b16 v[118:119], v2 offset:50176
	ds_read_b64_tr_b16 v[120:121], v2 offset:50688
	ds_read_b64_tr_b16 v[122:123], v2 offset:51200
	ds_read_b64_tr_b16 v[124:125], v2 offset:51712
	ds_read_b64_tr_b16 v[126:127], v2 offset:52224
	ds_read_b64_tr_b16 v[128:129], v2 offset:52736
	ds_read_b64_tr_b16 v[240:241], v2 offset:53248
	ds_read_b64_tr_b16 v[242:243], v2 offset:53760
	ds_read_b64_tr_b16 v[244:245], v2 offset:54272
	ds_read_b64_tr_b16 v[246:247], v2 offset:54784
	ds_read_b64_tr_b16 v[248:249], v2 offset:55296
	ds_read_b64_tr_b16 v[250:251], v2 offset:55808
	ds_read_b64_tr_b16 v[20:21], v2 offset:56320
	ds_read_b64_tr_b16 v[22:23], v2 offset:56832
	v_exp_f32_e32 v82, v82
	v_exp_f32_e32 v83, v83
	v_exp_f32_e32 v84, v84
	v_add_f32_e32 v27, v82, v83
	v_exp_f32_e32 v85, v85
	v_exp_f32_e32 v86, v86
	v_add_f32_e32 v27, v27, v84
	v_exp_f32_e32 v87, v87
	v_add_f32_e32 v27, v27, v85
	v_exp_f32_e32 v88, v88
	v_add_f32_e32 v27, v27, v86
	v_exp_f32_e32 v89, v89
	v_add_f32_e32 v27, v27, v87
	v_add_f32_e32 v27, v27, v88
	v_add_f32_e32 v27, v27, v89
	v_cvt_pk_bf16_f32 v82, v82, v83
	v_cvt_pk_bf16_f32 v83, v84, v85
	v_cvt_pk_bf16_f32 v84, v86, v87
	v_cvt_pk_bf16_f32 v85, v88, v89
	v_exp_f32_e32 v90, v90
	v_exp_f32_e32 v91, v91
	v_exp_f32_e32 v92, v92
	v_add_f32_e32 v27, v27, v90
	v_exp_f32_e32 v93, v93
	v_add_f32_e32 v27, v27, v91
	v_exp_f32_e32 v94, v94
	v_add_f32_e32 v27, v27, v92
	v_exp_f32_e32 v95, v95
	v_add_f32_e32 v27, v27, v93
	v_exp_f32_e32 v96, v96
	v_add_f32_e32 v27, v27, v94
	v_exp_f32_e32 v97, v97
	v_add_f32_e32 v27, v27, v95
	v_add_f32_e32 v27, v27, v96
	v_add_f32_e32 v27, v27, v97
	v_cvt_pk_bf16_f32 v90, v90, v91
	v_cvt_pk_bf16_f32 v91, v92, v93
	v_cvt_pk_bf16_f32 v92, v94, v95
	v_cvt_pk_bf16_f32 v93, v96, v97
	s_waitcnt lgkmcnt(0)
	v_mfma_f32_32x32x16_bf16 v[34:49], v[82:85], v[114:117], v[34:49]
	v_mfma_f32_32x32x16_bf16 v[50:65], v[82:85], v[240:243], v[50:65]
	v_exp_f32_e32 v98, v98
	v_exp_f32_e32 v99, v99
	v_exp_f32_e32 v100, v100
	v_add_f32_e32 v27, v27, v98
	v_exp_f32_e32 v101, v101
	v_add_f32_e32 v27, v27, v99
	v_exp_f32_e32 v102, v102
	v_add_f32_e32 v27, v27, v100
	v_exp_f32_e32 v103, v103
	v_add_f32_e32 v27, v27, v101
	v_exp_f32_e32 v104, v104
	v_add_f32_e32 v27, v27, v102
	v_exp_f32_e32 v105, v105
	v_add_f32_e32 v27, v27, v103
	v_add_f32_e32 v27, v27, v104
	v_add_f32_e32 v27, v27, v105
	v_cvt_pk_bf16_f32 v98, v98, v99
	v_cvt_pk_bf16_f32 v99, v100, v101
	v_cvt_pk_bf16_f32 v100, v102, v103
	v_cvt_pk_bf16_f32 v101, v104, v105
	v_mfma_f32_32x32x16_bf16 v[34:49], v[90:93], v[118:121], v[34:49]
	v_mfma_f32_32x32x16_bf16 v[50:65], v[90:93], v[244:247], v[50:65]
	v_exp_f32_e32 v106, v106
	v_exp_f32_e32 v107, v107
	v_exp_f32_e32 v108, v108
	v_add_f32_e32 v27, v27, v106
	v_exp_f32_e32 v109, v109
	v_add_f32_e32 v27, v27, v107
	v_exp_f32_e32 v110, v110
	v_add_f32_e32 v27, v27, v108
	v_exp_f32_e32 v111, v111
	v_add_f32_e32 v27, v27, v109
	v_exp_f32_e32 v112, v112
	v_add_f32_e32 v27, v27, v110
	v_exp_f32_e32 v113, v113
	v_add_f32_e32 v27, v27, v111
	v_add_f32_e32 v27, v27, v112
	v_add_f32_e32 v27, v27, v113
	v_cvt_pk_bf16_f32 v106, v106, v107
	v_cvt_pk_bf16_f32 v107, v108, v109
	v_cvt_pk_bf16_f32 v108, v110, v111
	v_cvt_pk_bf16_f32 v109, v112, v113
	v_add_f32_e32 v236, v236, v27
	s_nop 1
	v_mfma_f32_32x32x16_bf16 v[34:49], v[98:101], v[122:125], v[34:49]
	v_mfma_f32_32x32x16_bf16 v[50:65], v[98:101], v[248:251], v[50:65]
	v_mfma_f32_32x32x16_bf16 v[34:49], v[106:109], v[126:129], v[34:49]
	v_mfma_f32_32x32x16_bf16 v[50:65], v[106:109], v[20:23], v[50:65]
	s_branch .Lmy_te_25
.Lmy_tf_23:
	s_waitcnt lgkmcnt(0)
	v_add_u32_e32 v2, 0x4000, v237
	v_mfma_f32_32x32x16_bf16 v[142:157], v[218:221], v[4:7], v[66:81]
	v_exp_f32_e32 v82, v82
	v_exp_f32_e32 v83, v83
	v_exp_f32_e32 v84, v84
	v_add_f32_e32 v27, v82, v83
	v_exp_f32_e32 v85, v85
	v_mfma_f32_32x32x16_bf16 v[158:173], v[214:217], v[4:7], v[66:81]
	v_exp_f32_e32 v86, v86
	v_add_f32_e32 v27, v27, v84
	v_exp_f32_e32 v87, v87
	v_add_f32_e32 v27, v27, v85
	v_exp_f32_e32 v88, v88
	v_mfma_f32_32x32x16_bf16 v[142:157], v[210:213], v[8:11], v[142:157]
	v_add_f32_e32 v27, v27, v86
	v_exp_f32_e32 v89, v89
	v_add_f32_e32 v27, v27, v87
	v_add_f32_e32 v27, v27, v88
	v_add_f32_e32 v27, v27, v89
	v_mfma_f32_32x32x16_bf16 v[158:173], v[206:209], v[8:11], v[158:173]
	v_cvt_pk_bf16_f32 v82, v82, v83
	v_cvt_pk_bf16_f32 v83, v84, v85
	v_cvt_pk_bf16_f32 v84, v86, v87
	v_cvt_pk_bf16_f32 v85, v88, v89
	v_mfma_f32_32x32x16_bf16 v[142:157], v[202:205], v[12:15], v[142:157]
	v_exp_f32_e32 v90, v90
	v_exp_f32_e32 v91, v91
	v_exp_f32_e32 v92, v92
	v_add_f32_e32 v27, v27, v90
	v_exp_f32_e32 v93, v93
	v_mfma_f32_32x32x16_bf16 v[158:173], v[198:201], v[12:15], v[158:173]
	v_add_f32_e32 v27, v27, v91
	v_exp_f32_e32 v94, v94
	v_add_f32_e32 v27, v27, v92
	v_exp_f32_e32 v95, v95
	v_add_f32_e32 v27, v27, v93
	s_waitcnt vmcnt(0)
	s_barrier
	v_mfma_f32_32x32x16_bf16 v[142:157], v[194:197], v[130:133], v[142:157]
	v_exp_f32_e32 v96, v96
	v_add_f32_e32 v27, v27, v94
	v_exp_f32_e32 v97, v97
	v_add_f32_e32 v27, v27, v95
	v_add_f32_e32 v27, v27, v96
	ds_read_b64_tr_b16 v[114:115], v2 offset:49152
	ds_read_b64_tr_b16 v[116:117], v2 offset:49664
	ds_read_b64_tr_b16 v[118:119], v2 offset:50176
	ds_read_b64_tr_b16 v[120:121], v2 offset:50688
	v_mfma_f32_32x32x16_bf16 v[158:173], v[190:193], v[130:133], v[158:173]
	v_add_f32_e32 v27, v27, v97
	v_cvt_pk_bf16_f32 v90, v90, v91
	v_cvt_pk_bf16_f32 v91, v92, v93
	v_cvt_pk_bf16_f32 v92, v94, v95
	v_cvt_pk_bf16_f32 v93, v96, v97
	ds_read_b64_tr_b16 v[122:123], v2 offset:51200
	ds_read_b64_tr_b16 v[124:125], v2 offset:51712
	ds_read_b64_tr_b16 v[126:127], v2 offset:52224
	ds_read_b64_tr_b16 v[128:129], v2 offset:52736
	v_mfma_f32_32x32x16_bf16 v[142:157], v[186:189], v[134:137], v[142:157]
	v_exp_f32_e32 v98, v98
	v_exp_f32_e32 v99, v99
	v_exp_f32_e32 v100, v100
	v_add_f32_e32 v27, v27, v98
	v_exp_f32_e32 v101, v101
	ds_read_b64_tr_b16 v[240:241], v2 offset:53248
	ds_read_b64_tr_b16 v[242:243], v2 offset:53760
	ds_read_b64_tr_b16 v[244:245], v2 offset:54272
	ds_read_b64_tr_b16 v[246:247], v2 offset:54784
	v_mfma_f32_32x32x16_bf16 v[158:173], v[182:185], v[134:137], v[158:173]
	v_add_f32_e32 v27, v27, v99
	v_exp_f32_e32 v102, v102
	v_add_f32_e32 v27, v27, v100
	v_exp_f32_e32 v103, v103
	v_add_f32_e32 v27, v27, v101
	ds_read_b64_tr_b16 v[248:249], v2 offset:55296
	ds_read_b64_tr_b16 v[250:251], v2 offset:55808
	ds_read_b64_tr_b16 v[20:21], v2 offset:56320
	ds_read_b64_tr_b16 v[22:23], v2 offset:56832
	v_mfma_f32_32x32x16_bf16 v[142:157], v[178:181], v[138:141], v[142:157]
	v_exp_f32_e32 v104, v104
	v_add_f32_e32 v27, v27, v102
	v_exp_f32_e32 v105, v105
	v_add_f32_e32 v27, v27, v103
	v_add_f32_e32 v27, v27, v104
	v_mfma_f32_32x32x16_bf16 v[158:173], v[174:177], v[138:141], v[158:173]
	v_add_f32_e32 v27, v27, v105
	v_cvt_pk_bf16_f32 v98, v98, v99
	v_cvt_pk_bf16_f32 v99, v100, v101
	v_cvt_pk_bf16_f32 v100, v102, v103
	v_cvt_pk_bf16_f32 v101, v104, v105
	s_waitcnt lgkmcnt(0)
	v_mov_b32_e32 v2, v238
	v_mfma_f32_32x32x16_bf16 v[34:49], v[82:85], v[114:117], v[34:49]
	v_exp_f32_e32 v106, v106
	v_exp_f32_e32 v107, v107
	v_exp_f32_e32 v108, v108
	v_add_f32_e32 v27, v27, v106
	v_exp_f32_e32 v109, v109
	s_cmp_gt_u32 s71, 3
	s_cbranch_scc0 .Lmy_nok_26
	ds_read_b128 v[218:221], v2
	ds_read_b128 v[214:217], v2 offset:512
	ds_read_b128 v[210:213], v2 offset:2048
	ds_read_b128 v[206:209], v2 offset:2560
	ds_read_b128 v[202:205], v2 offset:4096
	ds_read_b128 v[198:201], v2 offset:4608
	ds_read_b128 v[194:197], v2 offset:6144
	ds_read_b128 v[190:193], v2 offset:6656
	ds_read_b128 v[186:189], v2 offset:8192
	ds_read_b128 v[182:185], v2 offset:8704
	ds_read_b128 v[178:181], v2 offset:10240
	ds_read_b128 v[174:177], v2 offset:10752

.Lmy_ts_29:
	s_waitcnt lgkmcnt(0)
	s_waitcnt vmcnt(0)
	s_barrier
	v_add_u32_e32 v2, 0x6000, v237
	ds_read_b64_tr_b16 v[114:115], v2 offset:49152
	ds_read_b64_tr_b16 v[116:117], v2 offset:49664
	ds_read_b64_tr_b16 v[118:119], v2 offset:50176
	ds_read_b64_tr_b16 v[120:121], v2 offset:50688
	ds_read_b64_tr_b16 v[122:123], v2 offset:51200
	ds_read_b64_tr_b16 v[124:125], v2 offset:51712
	ds_read_b64_tr_b16 v[126:127], v2 offset:52224
	ds_read_b64_tr_b16 v[128:129], v2 offset:52736
	ds_read_b64_tr_b16 v[240:241], v2 offset:53248
	ds_read_b64_tr_b16 v[242:243], v2 offset:53760
	ds_read_b64_tr_b16 v[244:245], v2 offset:54272
	ds_read_b64_tr_b16 v[246:247], v2 offset:54784
	ds_read_b64_tr_b16 v[248:249], v2 offset:55296
	ds_read_b64_tr_b16 v[250:251], v2 offset:55808
	ds_read_b64_tr_b16 v[20:21], v2 offset:56320
	ds_read_b64_tr_b16 v[22:23], v2 offset:56832
	v_exp_f32_e32 v142, v142
	v_exp_f32_e32 v143, v143
	v_exp_f32_e32 v144, v144
	v_add_f32_e32 v27, v142, v143
	v_exp_f32_e32 v145, v145
	v_exp_f32_e32 v146, v146
	v_add_f32_e32 v27, v27, v144
	v_exp_f32_e32 v147, v147
	v_add_f32_e32 v27, v27, v145
	v_exp_f32_e32 v148, v148
	v_add_f32_e32 v27, v27, v146
	v_exp_f32_e32 v149, v149
	v_add_f32_e32 v27, v27, v147
	v_add_f32_e32 v27, v27, v148
	v_add_f32_e32 v27, v27, v149
	v_cvt_pk_bf16_f32 v142, v142, v143
	v_cvt_pk_bf16_f32 v143, v144, v145
	v_cvt_pk_bf16_f32 v144, v146, v147
	v_cvt_pk_bf16_f32 v145, v148, v149
	v_exp_f32_e32 v150, v150
	v_exp_f32_e32 v151, v151
	v_exp_f32_e32 v152, v152
	v_add_f32_e32 v27, v27, v150
	v_exp_f32_e32 v153, v153
	v_add_f32_e32 v27, v27, v151
	v_exp_f32_e32 v154, v154
	v_add_f32_e32 v27, v27, v152
	v_exp_f32_e32 v155, v155
	v_add_f32_e32 v27, v27, v153
	v_exp_f32_e32 v156, v156
	v_add_f32_e32 v27, v27, v154
	v_exp_f32_e32 v157, v157
	v_add_f32_e32 v27, v27, v155
	v_add_f32_e32 v27, v27, v156
	v_add_f32_e32 v27, v27, v157
	v_cvt_pk_bf16_f32 v150, v150, v151
	v_cvt_pk_bf16_f32 v151, v152, v153
	v_cvt_pk_bf16_f32 v152, v154, v155
	v_cvt_pk_bf16_f32 v153, v156, v157
	s_waitcnt lgkmcnt(0)
	v_mfma_f32_32x32x16_bf16 v[34:49], v[142:145], v[114:117], v[34:49]
	v_mfma_f32_32x32x16_bf16 v[50:65], v[142:145], v[240:243], v[50:65]
	v_exp_f32_e32 v158, v158
	v_exp_f32_e32 v159, v159
	v_exp_f32_e32 v160, v160
	v_add_f32_e32 v27, v27, v158
	v_exp_f32_e32 v161, v161
	v_add_f32_e32 v27, v27, v159
	v_exp_f32_e32 v162, v162
	v_add_f32_e32 v27, v27, v160
	v_exp_f32_e32 v163, v163
	v_add_f32_e32 v27, v27, v161
	v_exp_f32_e32 v164, v164
	v_add_f32_e32 v27, v27, v162
	v_exp_f32_e32 v165, v165
	v_add_f32_e32 v27, v27, v163
	v_add_f32_e32 v27, v27, v164
	v_add_f32_e32 v27, v27, v165
	v_cvt_pk_bf16_f32 v158, v158, v159
	v_cvt_pk_bf16_f32 v159, v160, v161
	v_cvt_pk_bf16_f32 v160, v162, v163
	v_cvt_pk_bf16_f32 v161, v164, v165
	v_mfma_f32_32x32x16_bf16 v[34:49], v[150:153], v[118:121], v[34:49]
	v_mfma_f32_32x32x16_bf16 v[50:65], v[150:153], v[244:247], v[50:65]
	v_exp_f32_e32 v166, v166
	v_exp_f32_e32 v167, v167
	v_exp_f32_e32 v168, v168
	v_add_f32_e32 v27, v27, v166
	v_exp_f32_e32 v169, v169
	v_add_f32_e32 v27, v27, v167
	v_exp_f32_e32 v170, v170
	v_add_f32_e32 v27, v27, v168
	v_exp_f32_e32 v171, v171
	v_add_f32_e32 v27, v27, v169
	v_exp_f32_e32 v172, v172
	v_add_f32_e32 v27, v27, v170
	v_exp_f32_e32 v173, v173
	v_add_f32_e32 v27, v27, v171
	v_add_f32_e32 v27, v27, v172
	v_add_f32_e32 v27, v27, v173
	v_cvt_pk_bf16_f32 v166, v166, v167
	v_cvt_pk_bf16_f32 v167, v168, v169
	v_cvt_pk_bf16_f32 v168, v170, v171
	v_cvt_pk_bf16_f32 v169, v172, v173
	v_add_f32_e32 v236, v236, v27
	s_nop 1
	v_mfma_f32_32x32x16_bf16 v[34:49], v[158:161], v[122:125], v[34:49]
	v_mfma_f32_32x32x16_bf16 v[50:65], v[158:161], v[248:251], v[50:65]
	v_mfma_f32_32x32x16_bf16 v[34:49], v[166:169], v[126:129], v[34:49]
	v_mfma_f32_32x32x16_bf16 v[50:65], v[166:169], v[20:23], v[50:65]
	s_branch .Lmy_te_30

.Lmy_B_entry:
	s_mov_b32 s30, 0x20000
	s_mov_b32 s31, 0
	s_mov_b32 s12, 0x1000
	s_mov_b32 s13, 0
	s_lshr_b32 s71, s24, 1
	s_lshr_b32 s79, s25, 2
	s_add_i32 s79, s79, -1
	s_mov_b32 s0, 0x80000
	s_mov_b32 s1, 0
	v_lshl_add_u64 v[24:25], v[16:17], 0, s[0:1]
	s_mov_b32 s0, 0x60000
	v_lshl_add_u64 v[28:29], v[224:225], 0, s[0:1]
	s_mov_b32 s0, 0x4000
	v_lshl_add_u64 v[30:31], v[222:223], 0, s[0:1]
	s_waitcnt lgkmcnt(0)
	v_mfma_f32_32x32x16_bf16 v[82:97], v[218:221], v[4:7], v[66:81]
	v_mfma_f32_32x32x16_bf16 v[98:113], v[214:217], v[4:7], v[66:81]
	v_mfma_f32_32x32x16_bf16 v[82:97], v[210:213], v[8:11], v[82:97]
	v_mfma_f32_32x32x16_bf16 v[98:113], v[206:209], v[8:11], v[98:113]
	v_mfma_f32_32x32x16_bf16 v[82:97], v[202:205], v[12:15], v[82:97]
	v_mfma_f32_32x32x16_bf16 v[98:113], v[198:201], v[12:15], v[98:113]
	v_mfma_f32_32x32x16_bf16 v[82:97], v[194:197], v[130:133], v[82:97]
	v_mfma_f32_32x32x16_bf16 v[98:113], v[190:193], v[130:133], v[98:113]
	v_mfma_f32_32x32x16_bf16 v[82:97], v[186:189], v[134:137], v[82:97]
	v_mfma_f32_32x32x16_bf16 v[98:113], v[182:185], v[134:137], v[98:113]
	v_mfma_f32_32x32x16_bf16 v[82:97], v[178:181], v[138:141], v[82:97]
	v_mfma_f32_32x32x16_bf16 v[98:113], v[174:177], v[138:141], v[98:113]
	v_add_u32_e32 v2, 0x3000, v238
	ds_read_b128 v[218:221], v2
	ds_read_b128 v[214:217], v2 offset:512
	ds_read_b128 v[210:213], v2 offset:2048
	ds_read_b128 v[206:209], v2 offset:2560
	ds_read_b128 v[202:205], v2 offset:4096
	ds_read_b128 v[198:201], v2 offset:4608
	ds_read_b128 v[194:197], v2 offset:6144
	ds_read_b128 v[190:193], v2 offset:6656
	ds_read_b128 v[186:189], v2 offset:8192
	ds_read_b128 v[182:185], v2 offset:8704
	ds_read_b128 v[178:181], v2 offset:10240
	ds_read_b128 v[174:177], v2 offset:10752
	s_nop 7
	v_max3_f32 v19, v82, v83, v84
	v_max3_f32 v26, v85, v86, v87
	v_max3_f32 v19, v19, v88, v89
	v_max3_f32 v26, v26, v90, v91
	v_max3_f32 v19, v19, v92, v93
	v_max3_f32 v26, v26, v94, v95
	v_max3_f32 v19, v19, v96, v97
	v_max3_f32 v26, v26, v98, v99
	v_max3_f32 v19, v19, v100, v101
	v_max3_f32 v26, v26, v102, v103
	v_max3_f32 v19, v19, v104, v105
	v_max3_f32 v26, v26, v106, v107
	v_max3_f32 v19, v19, v108, v109
	v_max3_f32 v26, v26, v110, v111
	v_max3_f32 v19, v19, v112, v113
	v_max_f32_e32 v19, v19, v26
	v_mov_b32_e32 v26, v19
	s_nop 1
	v_permlane32_swap_b32_e32 v19, v26
	v_max_f32_e32 v19, v19, v26
	v_max_f32_e32 v19, v19, v19
	v_mov_b32_e32 v239, v19
	v_xor_b32_e32 v66, 0x80000000, v19
	v_mov_b32_e32 v67, v66
	v_mov_b32_e32 v68, v66
	v_mov_b32_e32 v69, v66
	v_mov_b32_e32 v70, v66
	v_mov_b32_e32 v71, v66
	v_mov_b32_e32 v72, v66
	v_mov_b32_e32 v73, v66
	v_mov_b32_e32 v74, v66
	v_mov_b32_e32 v75, v66
	v_mov_b32_e32 v76, v66
	v_mov_b32_e32 v77, v66
	v_mov_b32_e32 v78, v66
	v_mov_b32_e32 v79, v66
	v_mov_b32_e32 v80, v66
	v_mov_b32_e32 v81, v66
	v_sub_f32_e32 v82, v82, v19
	v_sub_f32_e32 v83, v83, v19
	v_sub_f32_e32 v84, v84, v19
	v_sub_f32_e32 v85, v85, v19
	v_sub_f32_e32 v86, v86, v19
	v_sub_f32_e32 v87, v87, v19
	v_sub_f32_e32 v88, v88, v19
	v_sub_f32_e32 v89, v89, v19
	v_sub_f32_e32 v90, v90, v19
	v_sub_f32_e32 v91, v91, v19
	v_sub_f32_e32 v92, v92, v19
	v_sub_f32_e32 v93, v93, v19
	v_sub_f32_e32 v94, v94, v19
	v_sub_f32_e32 v95, v95, v19
	v_sub_f32_e32 v96, v96, v19
	v_sub_f32_e32 v97, v97, v19
	v_sub_f32_e32 v98, v98, v19
	v_sub_f32_e32 v99, v99, v19
	v_sub_f32_e32 v100, v100, v19
	v_sub_f32_e32 v101, v101, v19
	v_sub_f32_e32 v102, v102, v19
	v_sub_f32_e32 v103, v103, v19
	v_sub_f32_e32 v104, v104, v19
	v_sub_f32_e32 v105, v105, v19
	v_sub_f32_e32 v106, v106, v19
	v_sub_f32_e32 v107, v107, v19
	v_sub_f32_e32 v108, v108, v19
	v_sub_f32_e32 v109, v109, v19
	v_sub_f32_e32 v110, v110, v19
	v_sub_f32_e32 v111, v111, v19
	v_sub_f32_e32 v112, v112, v19
	v_sub_f32_e32 v113, v113, v19
	s_cmp_lt_i32 s79, 1
	s_cbranch_scc1 .Lmy_B_tail
	s_waitcnt lgkmcnt(0)
	v_mov_b32_e32 v2, v237
	v_mfma_f32_32x32x16_bf16 v[142:157], v[218:221], v[4:7], v[66:81]
	v_exp_f32_e32 v82, v82
	v_exp_f32_e32 v83, v83
	v_exp_f32_e32 v84, v84
	v_add_f32_e32 v27, v82, v83
	v_exp_f32_e32 v85, v85
	v_mfma_f32_32x32x16_bf16 v[158:173], v[214:217], v[4:7], v[66:81]
	v_exp_f32_e32 v86, v86
	v_add_f32_e32 v27, v27, v84
	v_exp_f32_e32 v87, v87
	v_add_f32_e32 v27, v27, v85
	v_exp_f32_e32 v88, v88
	v_mfma_f32_32x32x16_bf16 v[142:157], v[210:213], v[8:11], v[142:157]
	v_add_f32_e32 v27, v27, v86
	v_exp_f32_e32 v89, v89
	v_add_f32_e32 v27, v27, v87
	v_add_f32_e32 v27, v27, v88
	v_add_f32_e32 v27, v27, v89
	v_mfma_f32_32x32x16_bf16 v[158:173], v[206:209], v[8:11], v[158:173]
	v_cvt_pk_bf16_f32 v82, v82, v83
	v_cvt_pk_bf16_f32 v83, v84, v85
	v_cvt_pk_bf16_f32 v84, v86, v87
	v_cvt_pk_bf16_f32 v85, v88, v89
	v_mfma_f32_32x32x16_bf16 v[142:157], v[202:205], v[12:15], v[142:157]
	v_exp_f32_e32 v90, v90
	v_exp_f32_e32 v91, v91
	v_exp_f32_e32 v92, v92
	v_add_f32_e32 v27, v27, v90
	v_exp_f32_e32 v93, v93
	v_mfma_f32_32x32x16_bf16 v[158:173], v[198:201], v[12:15], v[158:173]
	v_add_f32_e32 v27, v27, v91
	v_exp_f32_e32 v94, v94
	v_add_f32_e32 v27, v27, v92
	v_exp_f32_e32 v95, v95
	v_add_f32_e32 v27, v27, v93
	s_waitcnt vmcnt(2)
	s_barrier
	v_mfma_f32_32x32x16_bf16 v[142:157], v[194:197], v[130:133], v[142:157]
	s_add_u32 m0, s57, 0x6000
	v_exp_f32_e32 v96, v96
	v_add_f32_e32 v27, v27, v94
	global_load_lds_dwordx4 v[28:29], off
	v_lshl_add_u64 v[28:29], v[28:29], 0, s[30:31]
	v_exp_f32_e32 v97, v97
	v_add_f32_e32 v27, v27, v95
	v_add_f32_e32 v27, v27, v96
	ds_read_b64_tr_b16 v[114:115], v2 offset:49152
	ds_read_b64_tr_b16 v[116:117], v2 offset:49664
	ds_read_b64_tr_b16 v[118:119], v2 offset:50176
	ds_read_b64_tr_b16 v[120:121], v2 offset:50688
	v_mfma_f32_32x32x16_bf16 v[158:173], v[190:193], v[130:133], v[158:173]
	s_add_u32 m0, s40, 0x0
	v_add_f32_e32 v27, v27, v97
	v_cvt_pk_bf16_f32 v90, v90, v91
	global_load_lds_dwordx4 v[24:25], off
	v_lshl_add_u64 v[24:25], v[24:25], 0, s[30:31]
	v_cvt_pk_bf16_f32 v91, v92, v93
	v_cvt_pk_bf16_f32 v92, v94, v95
	v_cvt_pk_bf16_f32 v93, v96, v97
	ds_read_b64_tr_b16 v[122:123], v2 offset:51200
	ds_read_b64_tr_b16 v[124:125], v2 offset:51712
	ds_read_b64_tr_b16 v[126:127], v2 offset:52224
	ds_read_b64_tr_b16 v[128:129], v2 offset:52736
	v_mfma_f32_32x32x16_bf16 v[142:157], v[186:189], v[134:137], v[142:157]
	s_add_u32 m0, s40, 0x3000
	v_exp_f32_e32 v98, v98
	v_exp_f32_e32 v99, v99
	global_load_lds_dwordx4 v[24:25], off
	v_lshl_add_u64 v[24:25], v[24:25], 0, s[30:31]
	v_exp_f32_e32 v100, v100
	v_add_f32_e32 v27, v27, v98
	v_exp_f32_e32 v101, v101
	ds_read_b64_tr_b16 v[240:241], v2 offset:53248
	ds_read_b64_tr_b16 v[242:243], v2 offset:53760
	ds_read_b64_tr_b16 v[244:245], v2 offset:54272
	ds_read_b64_tr_b16 v[246:247], v2 offset:54784
	v_mfma_f32_32x32x16_bf16 v[158:173], v[182:185], v[134:137], v[158:173]
	v_add_f32_e32 v27, v27, v99
	v_exp_f32_e32 v102, v102
	v_add_f32_e32 v27, v27, v100
	v_exp_f32_e32 v103, v103
	v_add_f32_e32 v27, v27, v101
	ds_read_b64_tr_b16 v[248:249], v2 offset:55296
	ds_read_b64_tr_b16 v[250:251], v2 offset:55808
	ds_read_b64_tr_b16 v[20:21], v2 offset:56320
	ds_read_b64_tr_b16 v[22:23], v2 offset:56832
	v_mfma_f32_32x32x16_bf16 v[142:157], v[178:181], v[138:141], v[142:157]
	v_exp_f32_e32 v104, v104
	v_add_f32_e32 v27, v27, v102
	v_exp_f32_e32 v105, v105
	v_add_f32_e32 v27, v27, v103
	v_add_f32_e32 v27, v27, v104
	v_mfma_f32_32x32x16_bf16 v[158:173], v[174:177], v[138:141], v[158:173]
	v_add_f32_e32 v27, v27, v105
	v_cvt_pk_bf16_f32 v98, v98, v99
	v_cvt_pk_bf16_f32 v99, v100, v101
	v_cvt_pk_bf16_f32 v100, v102, v103
	v_cvt_pk_bf16_f32 v101, v104, v105
	s_waitcnt lgkmcnt(0)
	v_add_u32_e32 v2, 0x6000, v238
	v_mfma_f32_32x32x16_bf16 v[34:49], v[82:85], v[114:117], v[34:49]
	v_exp_f32_e32 v106, v106
	v_exp_f32_e32 v107, v107
	v_exp_f32_e32 v108, v108
	v_add_f32_e32 v27, v27, v106
	v_exp_f32_e32 v109, v109
	ds_read_b128 v[218:221], v2
	ds_read_b128 v[214:217], v2 offset:512
	ds_read_b128 v[210:213], v2 offset:2048
	v_mfma_f32_32x32x16_bf16 v[50:65], v[82:85], v[240:243], v[50:65]
	v_add_f32_e32 v27, v27, v107
	v_exp_f32_e32 v110, v110
	v_add_f32_e32 v27, v27, v108
	v_exp_f32_e32 v111, v111
	v_add_f32_e32 v27, v27, v109
	ds_read_b128 v[206:209], v2 offset:2560
	ds_read_b128 v[202:205], v2 offset:4096
	ds_read_b128 v[198:201], v2 offset:4608
	v_mfma_f32_32x32x16_bf16 v[34:49], v[90:93], v[118:121], v[34:49]
	v_exp_f32_e32 v112, v112
	v_add_f32_e32 v27, v27, v110
	v_exp_f32_e32 v113, v113
	v_add_f32_e32 v27, v27, v111
	v_add_f32_e32 v27, v27, v112
	ds_read_b128 v[194:197], v2 offset:6144
	ds_read_b128 v[190:193], v2 offset:6656
	ds_read_b128 v[186:189], v2 offset:8192
	v_mfma_f32_32x32x16_bf16 v[50:65], v[90:93], v[244:247], v[50:65]
	v_add_f32_e32 v27, v27, v113
	v_cvt_pk_bf16_f32 v106, v106, v107
	v_cvt_pk_bf16_f32 v107, v108, v109
	v_cvt_pk_bf16_f32 v108, v110, v111
	v_cvt_pk_bf16_f32 v109, v112, v113
	v_add_f32_e32 v236, v236, v27
	ds_read_b128 v[182:185], v2 offset:8704
	ds_read_b128 v[178:181], v2 offset:10240
	ds_read_b128 v[174:177], v2 offset:10752
	v_mfma_f32_32x32x16_bf16 v[34:49], v[98:101], v[122:125], v[34:49]
	v_max3_f32 v19, v142, v143, v144
	v_max3_f32 v26, v145, v146, v147
	v_max3_f32 v19, v19, v148, v149
	v_max3_f32 v26, v26, v150, v151
	v_mfma_f32_32x32x16_bf16 v[50:65], v[98:101], v[248:251], v[50:65]
	v_max3_f32 v19, v19, v152, v153
	v_max3_f32 v26, v26, v154, v155
	v_max3_f32 v19, v19, v156, v157
	v_max3_f32 v26, v26, v158, v159
	v_mfma_f32_32x32x16_bf16 v[34:49], v[106:109], v[126:129], v[34:49]
	v_max3_f32 v19, v19, v160, v161
	v_max3_f32 v26, v26, v162, v163
	v_max3_f32 v19, v19, v164, v165
	v_max3_f32 v26, v26, v166, v167
	v_mfma_f32_32x32x16_bf16 v[50:65], v[106:109], v[20:23], v[50:65]
	v_max3_f32 v19, v19, v168, v169
	v_max3_f32 v26, v26, v170, v171
	v_max3_f32 v19, v19, v172, v173
	v_max_f32_e32 v19, v19, v26
	v_cmp_lt_f32_e32 vcc, s41, v19
	s_cbranch_vccz .Lmy_nors_31
	s_nop 15
	s_nop 15
	v_mov_b32_e32 v26, v19
	s_nop 1
	v_permlane32_swap_b32_e32 v19, v26
	v_max_f32_e32 v19, v19, v26
	v_max_f32_e32 v19, v19, v19
	v_max_f32_e32 v90, 0, v19
	v_exp_f32_e64 v91, -v90
	v_add_f32_e32 v239, v239, v90
	v_xor_b32_e32 v66, 0x80000000, v239
	v_mov_b32_e32 v67, v66
	v_mov_b32_e32 v68, v66
	v_mov_b32_e32 v69, v66
	v_mov_b32_e32 v70, v66
	v_mov_b32_e32 v71, v66
	v_mov_b32_e32 v72, v66
	v_mov_b32_e32 v73, v66
	v_mov_b32_e32 v74, v66
	v_mov_b32_e32 v75, v66
	v_mov_b32_e32 v76, v66
	v_mov_b32_e32 v77, v66
	v_mov_b32_e32 v78, v66
	v_mov_b32_e32 v79, v66
	v_mov_b32_e32 v80, v66
	v_mov_b32_e32 v81, v66
	v_sub_f32_e32 v142, v142, v90
	v_sub_f32_e32 v143, v143, v90
	v_sub_f32_e32 v144, v144, v90
	v_sub_f32_e32 v145, v145, v90
	v_sub_f32_e32 v146, v146, v90
	v_sub_f32_e32 v147, v147, v90
	v_sub_f32_e32 v148, v148, v90
	v_sub_f32_e32 v149, v149, v90
	v_sub_f32_e32 v150, v150, v90
	v_sub_f32_e32 v151, v151, v90
	v_sub_f32_e32 v152, v152, v90
	v_sub_f32_e32 v153, v153, v90
	v_sub_f32_e32 v154, v154, v90
	v_sub_f32_e32 v155, v155, v90
	v_sub_f32_e32 v156, v156, v90
	v_sub_f32_e32 v157, v157, v90
	v_sub_f32_e32 v158, v158, v90
	v_sub_f32_e32 v159, v159, v90
	v_sub_f32_e32 v160, v160, v90
	v_sub_f32_e32 v161, v161, v90
	v_sub_f32_e32 v162, v162, v90
	v_sub_f32_e32 v163, v163, v90
	v_sub_f32_e32 v164, v164, v90
	v_sub_f32_e32 v165, v165, v90
	v_sub_f32_e32 v166, v166, v90
	v_sub_f32_e32 v167, v167, v90
	v_sub_f32_e32 v168, v168, v90
	v_sub_f32_e32 v169, v169, v90
	v_sub_f32_e32 v170, v170, v90
	v_sub_f32_e32 v171, v171, v90
	v_sub_f32_e32 v172, v172, v90
	v_sub_f32_e32 v173, v173, v90
	v_mul_f32_e32 v236, v236, v91
	s_mov_b64 s[96:97], exec
	s_and_b64 exec, exec, s[8:9]
	ds_write_b32 v235, v91
	s_mov_b64 exec, s[96:97]
	v_lshl_add_u32 v2, v228, 4, s47
	ds_read_b128 v[94:97], v2 offset:0
	s_waitcnt lgkmcnt(0)
	v_mul_f32_e32 v34, v34, v94
	v_mul_f32_e32 v50, v50, v94
	v_mul_f32_e32 v35, v35, v95
	v_mul_f32_e32 v51, v51, v95
	v_mul_f32_e32 v36, v36, v96
	v_mul_f32_e32 v52, v52, v96
	v_mul_f32_e32 v37, v37, v97
	v_mul_f32_e32 v53, v53, v97
	ds_read_b128 v[94:97], v2 offset:32
	s_waitcnt lgkmcnt(0)
	v_mul_f32_e32 v38, v38, v94
	v_mul_f32_e32 v54, v54, v94
	v_mul_f32_e32 v39, v39, v95
	v_mul_f32_e32 v55, v55, v95
	v_mul_f32_e32 v40, v40, v96
	v_mul_f32_e32 v56, v56, v96
	v_mul_f32_e32 v41, v41, v97
	v_mul_f32_e32 v57, v57, v97
	ds_read_b128 v[94:97], v2 offset:64
	s_waitcnt lgkmcnt(0)
	v_mul_f32_e32 v42, v42, v94
	v_mul_f32_e32 v58, v58, v94
	v_mul_f32_e32 v43, v43, v95
	v_mul_f32_e32 v59, v59, v95
	v_mul_f32_e32 v44, v44, v96
	v_mul_f32_e32 v60, v60, v96
	v_mul_f32_e32 v45, v45, v97
	v_mul_f32_e32 v61, v61, v97
	ds_read_b128 v[94:97], v2 offset:96
	s_waitcnt lgkmcnt(0)
	v_mul_f32_e32 v46, v46, v94
	v_mul_f32_e32 v62, v62, v94
	v_mul_f32_e32 v47, v47, v95
	v_mul_f32_e32 v63, v63, v95
	v_mul_f32_e32 v48, v48, v96
	v_mul_f32_e32 v64, v64, v96
	v_mul_f32_e32 v49, v49, v97
	v_mul_f32_e32 v65, v65, v97
.Lmy_nors_31:
	s_waitcnt lgkmcnt(0)
	v_add_u32_e32 v2, 0x2000, v237
	v_mfma_f32_32x32x16_bf16 v[82:97], v[218:221], v[4:7], v[66:81]
	v_exp_f32_e32 v142, v142
	v_exp_f32_e32 v143, v143
	v_exp_f32_e32 v144, v144
	v_add_f32_e32 v27, v142, v143
	v_exp_f32_e32 v145, v145
	v_mfma_f32_32x32x16_bf16 v[98:113], v[214:217], v[4:7], v[66:81]
	v_exp_f32_e32 v146, v146
	v_add_f32_e32 v27, v27, v144
	v_exp_f32_e32 v147, v147
	v_add_f32_e32 v27, v27, v145
	v_exp_f32_e32 v148, v148
	v_mfma_f32_32x32x16_bf16 v[82:97], v[210:213], v[8:11], v[82:97]
	v_add_f32_e32 v27, v27, v146
	v_exp_f32_e32 v149, v149
	v_add_f32_e32 v27, v27, v147
	v_add_f32_e32 v27, v27, v148
	v_add_f32_e32 v27, v27, v149
	v_mfma_f32_32x32x16_bf16 v[98:113], v[206:209], v[8:11], v[98:113]
	v_cvt_pk_bf16_f32 v142, v142, v143
	v_cvt_pk_bf16_f32 v143, v144, v145
	v_cvt_pk_bf16_f32 v144, v146, v147
	v_cvt_pk_bf16_f32 v145, v148, v149
	v_mfma_f32_32x32x16_bf16 v[82:97], v[202:205], v[12:15], v[82:97]
	v_exp_f32_e32 v150, v150
	v_exp_f32_e32 v151, v151
	v_exp_f32_e32 v152, v152
	v_add_f32_e32 v27, v27, v150
	v_exp_f32_e32 v153, v153
	v_mfma_f32_32x32x16_bf16 v[98:113], v[198:201], v[12:15], v[98:113]
	v_add_f32_e32 v27, v27, v151
	v_exp_f32_e32 v154, v154
	v_add_f32_e32 v27, v27, v152
	v_exp_f32_e32 v155, v155
	v_add_f32_e32 v27, v27, v153
	s_waitcnt vmcnt(3)
	s_barrier
	v_mfma_f32_32x32x16_bf16 v[82:97], v[194:197], v[130:133], v[82:97]
	s_add_u32 m0, s57, 0x0
	v_exp_f32_e32 v156, v156
	v_add_f32_e32 v27, v27, v154
	global_load_lds_dwordx4 v[28:29], off
	v_lshl_add_u64 v[28:29], v[28:29], 0, s[30:31]
	v_exp_f32_e32 v157, v157
	v_add_f32_e32 v27, v27, v155
	v_add_f32_e32 v27, v27, v156
	ds_read_b64_tr_b16 v[114:115], v2 offset:49152
	ds_read_b64_tr_b16 v[116:117], v2 offset:49664
	ds_read_b64_tr_b16 v[118:119], v2 offset:50176
	ds_read_b64_tr_b16 v[120:121], v2 offset:50688
	v_mfma_f32_32x32x16_bf16 v[98:113], v[190:193], v[130:133], v[98:113]
	s_add_u32 m0, s40, 0x6000
	v_add_f32_e32 v27, v27, v157
	v_cvt_pk_bf16_f32 v150, v150, v151
	global_load_lds_dwordx4 v[24:25], off
	v_lshl_add_u64 v[24:25], v[24:25], 0, s[30:31]
	v_cvt_pk_bf16_f32 v151, v152, v153
	v_cvt_pk_bf16_f32 v152, v154, v155
	v_cvt_pk_bf16_f32 v153, v156, v157
	ds_read_b64_tr_b16 v[122:123], v2 offset:51200
	ds_read_b64_tr_b16 v[124:125], v2 offset:51712
	ds_read_b64_tr_b16 v[126:127], v2 offset:52224
	ds_read_b64_tr_b16 v[128:129], v2 offset:52736
	v_mfma_f32_32x32x16_bf16 v[82:97], v[186:189], v[134:137], v[82:97]
	v_exp_f32_e32 v158, v158
	v_exp_f32_e32 v159, v159
	v_exp_f32_e32 v160, v160
	v_add_f32_e32 v27, v27, v158
	v_exp_f32_e32 v161, v161
	ds_read_b64_tr_b16 v[240:241], v2 offset:53248
	ds_read_b64_tr_b16 v[242:243], v2 offset:53760
	ds_read_b64_tr_b16 v[244:245], v2 offset:54272
	ds_read_b64_tr_b16 v[246:247], v2 offset:54784
	v_mfma_f32_32x32x16_bf16 v[98:113], v[182:185], v[134:137], v[98:113]
	v_add_f32_e32 v27, v27, v159
	v_exp_f32_e32 v162, v162
	v_add_f32_e32 v27, v27, v160
	v_exp_f32_e32 v163, v163
	v_add_f32_e32 v27, v27, v161
	ds_read_b64_tr_b16 v[248:249], v2 offset:55296
	ds_read_b64_tr_b16 v[250:251], v2 offset:55808
	ds_read_b64_tr_b16 v[20:21], v2 offset:56320
	ds_read_b64_tr_b16 v[22:23], v2 offset:56832
	v_mfma_f32_32x32x16_bf16 v[82:97], v[178:181], v[138:141], v[82:97]
	v_exp_f32_e32 v164, v164
	v_add_f32_e32 v27, v27, v162
	v_exp_f32_e32 v165, v165
	v_add_f32_e32 v27, v27, v163
	v_add_f32_e32 v27, v27, v164
	v_mfma_f32_32x32x16_bf16 v[98:113], v[174:177], v[138:141], v[98:113]
	v_add_f32_e32 v27, v27, v165
	v_cvt_pk_bf16_f32 v158, v158, v159
	v_cvt_pk_bf16_f32 v159, v160, v161
	v_cvt_pk_bf16_f32 v160, v162, v163
	v_cvt_pk_bf16_f32 v161, v164, v165
	s_waitcnt lgkmcnt(0)
	v_add_u32_e32 v2, 0x9000, v238
	v_mfma_f32_32x32x16_bf16 v[34:49], v[142:145], v[114:117], v[34:49]
	v_exp_f32_e32 v166, v166
	v_exp_f32_e32 v167, v167
	v_exp_f32_e32 v168, v168
	v_add_f32_e32 v27, v27, v166
	v_exp_f32_e32 v169, v169
	ds_read_b128 v[218:221], v2
	ds_read_b128 v[214:217], v2 offset:512
	ds_read_b128 v[210:213], v2 offset:2048
	v_mfma_f32_32x32x16_bf16 v[50:65], v[142:145], v[240:243], v[50:65]
	v_add_f32_e32 v27, v27, v167
	v_exp_f32_e32 v170, v170
	v_add_f32_e32 v27, v27, v168
	v_exp_f32_e32 v171, v171
	v_add_f32_e32 v27, v27, v169
	ds_read_b128 v[206:209], v2 offset:2560
	ds_read_b128 v[202:205], v2 offset:4096
	ds_read_b128 v[198:201], v2 offset:4608
	v_mfma_f32_32x32x16_bf16 v[34:49], v[150:153], v[118:121], v[34:49]
	v_exp_f32_e32 v172, v172
	v_add_f32_e32 v27, v27, v170
	v_exp_f32_e32 v173, v173
	v_add_f32_e32 v27, v27, v171
	v_add_f32_e32 v27, v27, v172
	ds_read_b128 v[194:197], v2 offset:6144
	ds_read_b128 v[190:193], v2 offset:6656
	ds_read_b128 v[186:189], v2 offset:8192
	v_mfma_f32_32x32x16_bf16 v[50:65], v[150:153], v[244:247], v[50:65]
	v_add_f32_e32 v27, v27, v173
	v_cvt_pk_bf16_f32 v166, v166, v167
	v_cvt_pk_bf16_f32 v167, v168, v169
	v_cvt_pk_bf16_f32 v168, v170, v171
	v_cvt_pk_bf16_f32 v169, v172, v173
	v_add_f32_e32 v236, v236, v27
	ds_read_b128 v[182:185], v2 offset:8704
	ds_read_b128 v[178:181], v2 offset:10240
	ds_read_b128 v[174:177], v2 offset:10752
	v_mfma_f32_32x32x16_bf16 v[34:49], v[158:161], v[122:125], v[34:49]
	v_max3_f32 v19, v82, v83, v84
	v_max3_f32 v26, v85, v86, v87
	v_max3_f32 v19, v19, v88, v89
	v_max3_f32 v26, v26, v90, v91
	v_mfma_f32_32x32x16_bf16 v[50:65], v[158:161], v[248:251], v[50:65]
	v_max3_f32 v19, v19, v92, v93
	v_max3_f32 v26, v26, v94, v95
	v_max3_f32 v19, v19, v96, v97
	v_max3_f32 v26, v26, v98, v99
	v_mfma_f32_32x32x16_bf16 v[34:49], v[166:169], v[126:129], v[34:49]
	v_max3_f32 v19, v19, v100, v101
	v_max3_f32 v26, v26, v102, v103
	v_max3_f32 v19, v19, v104, v105
	v_max3_f32 v26, v26, v106, v107
	v_mfma_f32_32x32x16_bf16 v[50:65], v[166:169], v[20:23], v[50:65]
	v_max3_f32 v19, v19, v108, v109
	v_max3_f32 v26, v26, v110, v111
	v_max3_f32 v19, v19, v112, v113
	v_max_f32_e32 v19, v19, v26
	v_cmp_lt_f32_e32 vcc, s41, v19
	s_cbranch_vccz .Lmy_nors_32
	s_nop 15
	s_nop 15
	v_mov_b32_e32 v26, v19
	s_nop 1
	v_permlane32_swap_b32_e32 v19, v26
	v_max_f32_e32 v19, v19, v26
	v_max_f32_e32 v19, v19, v19
	v_max_f32_e32 v150, 0, v19
	v_exp_f32_e64 v151, -v150
	v_add_f32_e32 v239, v239, v150
	v_xor_b32_e32 v66, 0x80000000, v239
	v_mov_b32_e32 v67, v66
	v_mov_b32_e32 v68, v66
	v_mov_b32_e32 v69, v66
	v_mov_b32_e32 v70, v66
	v_mov_b32_e32 v71, v66
	v_mov_b32_e32 v72, v66
	v_mov_b32_e32 v73, v66
	v_mov_b32_e32 v74, v66
	v_mov_b32_e32 v75, v66
	v_mov_b32_e32 v76, v66
	v_mov_b32_e32 v77, v66
	v_mov_b32_e32 v78, v66
	v_mov_b32_e32 v79, v66
	v_mov_b32_e32 v80, v66
	v_mov_b32_e32 v81, v66
	v_sub_f32_e32 v82, v82, v150
	v_sub_f32_e32 v83, v83, v150
	v_sub_f32_e32 v84, v84, v150
	v_sub_f32_e32 v85, v85, v150
	v_sub_f32_e32 v86, v86, v150
	v_sub_f32_e32 v87, v87, v150
	v_sub_f32_e32 v88, v88, v150
	v_sub_f32_e32 v89, v89, v150
	v_sub_f32_e32 v90, v90, v150
	v_sub_f32_e32 v91, v91, v150
	v_sub_f32_e32 v92, v92, v150
	v_sub_f32_e32 v93, v93, v150
	v_sub_f32_e32 v94, v94, v150
	v_sub_f32_e32 v95, v95, v150
	v_sub_f32_e32 v96, v96, v150
	v_sub_f32_e32 v97, v97, v150
	v_sub_f32_e32 v98, v98, v150
	v_sub_f32_e32 v99, v99, v150
	v_sub_f32_e32 v100, v100, v150
	v_sub_f32_e32 v101, v101, v150
	v_sub_f32_e32 v102, v102, v150
	v_sub_f32_e32 v103, v103, v150
	v_sub_f32_e32 v104, v104, v150
	v_sub_f32_e32 v105, v105, v150
	v_sub_f32_e32 v106, v106, v150
	v_sub_f32_e32 v107, v107, v150
	v_sub_f32_e32 v108, v108, v150
	v_sub_f32_e32 v109, v109, v150
	v_sub_f32_e32 v110, v110, v150
	v_sub_f32_e32 v111, v111, v150
	v_sub_f32_e32 v112, v112, v150
	v_sub_f32_e32 v113, v113, v150
	v_mul_f32_e32 v236, v236, v151
	s_mov_b64 s[96:97], exec
	s_and_b64 exec, exec, s[8:9]
	ds_write_b32 v235, v151
	s_mov_b64 exec, s[96:97]
	v_lshl_add_u32 v2, v228, 4, s47
	ds_read_b128 v[154:157], v2 offset:0
	s_waitcnt lgkmcnt(0)
	v_mul_f32_e32 v34, v34, v154
	v_mul_f32_e32 v50, v50, v154
	v_mul_f32_e32 v35, v35, v155
	v_mul_f32_e32 v51, v51, v155
	v_mul_f32_e32 v36, v36, v156
	v_mul_f32_e32 v52, v52, v156
	v_mul_f32_e32 v37, v37, v157
	v_mul_f32_e32 v53, v53, v157
	ds_read_b128 v[154:157], v2 offset:32
	s_waitcnt lgkmcnt(0)
	v_mul_f32_e32 v38, v38, v154
	v_mul_f32_e32 v54, v54, v154
	v_mul_f32_e32 v39, v39, v155
	v_mul_f32_e32 v55, v55, v155
	v_mul_f32_e32 v40, v40, v156
	v_mul_f32_e32 v56, v56, v156
	v_mul_f32_e32 v41, v41, v157
	v_mul_f32_e32 v57, v57, v157
	ds_read_b128 v[154:157], v2 offset:64
	s_waitcnt lgkmcnt(0)
	v_mul_f32_e32 v42, v42, v154
	v_mul_f32_e32 v58, v58, v154
	v_mul_f32_e32 v43, v43, v155
	v_mul_f32_e32 v59, v59, v155
	v_mul_f32_e32 v44, v44, v156
	v_mul_f32_e32 v60, v60, v156
	v_mul_f32_e32 v45, v45, v157
	v_mul_f32_e32 v61, v61, v157
	ds_read_b128 v[154:157], v2 offset:96
	s_waitcnt lgkmcnt(0)
	v_mul_f32_e32 v46, v46, v154
	v_mul_f32_e32 v62, v62, v154
	v_mul_f32_e32 v47, v47, v155
	v_mul_f32_e32 v63, v63, v155
	v_mul_f32_e32 v48, v48, v156
	v_mul_f32_e32 v64, v64, v156
	v_mul_f32_e32 v49, v49, v157
	v_mul_f32_e32 v65, v65, v157
.Lmy_nors_32:
	s_waitcnt lgkmcnt(0)
	v_add_u32_e32 v2, 0x4000, v237
	v_mfma_f32_32x32x16_bf16 v[142:157], v[218:221], v[4:7], v[66:81]
	v_exp_f32_e32 v82, v82
	v_exp_f32_e32 v83, v83
	v_exp_f32_e32 v84, v84
	v_add_f32_e32 v27, v82, v83
	v_exp_f32_e32 v85, v85
	v_mfma_f32_32x32x16_bf16 v[158:173], v[214:217], v[4:7], v[66:81]
	v_exp_f32_e32 v86, v86
	v_add_f32_e32 v27, v27, v84
	v_exp_f32_e32 v87, v87
	v_add_f32_e32 v27, v27, v85
	v_exp_f32_e32 v88, v88
	v_mfma_f32_32x32x16_bf16 v[142:157], v[210:213], v[8:11], v[142:157]
	v_add_f32_e32 v27, v27, v86
	v_exp_f32_e32 v89, v89
	v_add_f32_e32 v27, v27, v87
	v_add_f32_e32 v27, v27, v88
	v_add_f32_e32 v27, v27, v89
	v_mfma_f32_32x32x16_bf16 v[158:173], v[206:209], v[8:11], v[158:173]
	v_cvt_pk_bf16_f32 v82, v82, v83
	v_cvt_pk_bf16_f32 v83, v84, v85
	v_cvt_pk_bf16_f32 v84, v86, v87
	v_cvt_pk_bf16_f32 v85, v88, v89
	v_mfma_f32_32x32x16_bf16 v[142:157], v[202:205], v[12:15], v[142:157]
	v_exp_f32_e32 v90, v90
	v_exp_f32_e32 v91, v91
	v_exp_f32_e32 v92, v92
	v_add_f32_e32 v27, v27, v90
	v_exp_f32_e32 v93, v93
	v_mfma_f32_32x32x16_bf16 v[158:173], v[198:201], v[12:15], v[158:173]
	v_add_f32_e32 v27, v27, v91
	v_exp_f32_e32 v94, v94
	v_add_f32_e32 v27, v27, v92
	v_exp_f32_e32 v95, v95
	v_add_f32_e32 v27, v27, v93
	s_waitcnt vmcnt(3)
	s_barrier
	v_mfma_f32_32x32x16_bf16 v[142:157], v[194:197], v[130:133], v[142:157]
	s_add_u32 m0, s57, 0x2000
	v_exp_f32_e32 v96, v96
	v_add_f32_e32 v27, v27, v94
	global_load_lds_dwordx4 v[28:29], off
	v_lshl_add_u64 v[28:29], v[28:29], 0, s[30:31]
	v_exp_f32_e32 v97, v97
	v_add_f32_e32 v27, v27, v95
	v_add_f32_e32 v27, v27, v96
	ds_read_b64_tr_b16 v[114:115], v2 offset:49152
	ds_read_b64_tr_b16 v[116:117], v2 offset:49664
	ds_read_b64_tr_b16 v[118:119], v2 offset:50176
	ds_read_b64_tr_b16 v[120:121], v2 offset:50688
	v_mfma_f32_32x32x16_bf16 v[158:173], v[190:193], v[130:133], v[158:173]
	s_add_u32 m0, s40, 0x9000
	v_add_f32_e32 v27, v27, v97
	v_cvt_pk_bf16_f32 v90, v90, v91
	global_load_lds_dwordx4 v[24:25], off
	v_lshl_add_u64 v[24:25], v[24:25], 0, s[30:31]
	v_cvt_pk_bf16_f32 v91, v92, v93
	v_cvt_pk_bf16_f32 v92, v94, v95
	v_cvt_pk_bf16_f32 v93, v96, v97
	ds_read_b64_tr_b16 v[122:123], v2 offset:51200
	ds_read_b64_tr_b16 v[124:125], v2 offset:51712
	ds_read_b64_tr_b16 v[126:127], v2 offset:52224
	ds_read_b64_tr_b16 v[128:129], v2 offset:52736
	v_mfma_f32_32x32x16_bf16 v[142:157], v[186:189], v[134:137], v[142:157]
	v_exp_f32_e32 v98, v98
	v_exp_f32_e32 v99, v99
	v_exp_f32_e32 v100, v100
	v_add_f32_e32 v27, v27, v98
	v_exp_f32_e32 v101, v101
	ds_read_b64_tr_b16 v[240:241], v2 offset:53248
	ds_read_b64_tr_b16 v[242:243], v2 offset:53760
	ds_read_b64_tr_b16 v[244:245], v2 offset:54272
	ds_read_b64_tr_b16 v[246:247], v2 offset:54784
	v_mfma_f32_32x32x16_bf16 v[158:173], v[182:185], v[134:137], v[158:173]
	v_add_f32_e32 v27, v27, v99
	v_exp_f32_e32 v102, v102
	v_add_f32_e32 v27, v27, v100
	v_exp_f32_e32 v103, v103
	v_add_f32_e32 v27, v27, v101
	ds_read_b64_tr_b16 v[248:249], v2 offset:55296
	ds_read_b64_tr_b16 v[250:251], v2 offset:55808
	ds_read_b64_tr_b16 v[20:21], v2 offset:56320
	ds_read_b64_tr_b16 v[22:23], v2 offset:56832
	v_mfma_f32_32x32x16_bf16 v[142:157], v[178:181], v[138:141], v[142:157]
	v_exp_f32_e32 v104, v104
	v_add_f32_e32 v27, v27, v102
	v_exp_f32_e32 v105, v105
	v_add_f32_e32 v27, v27, v103
	v_add_f32_e32 v27, v27, v104
	v_mfma_f32_32x32x16_bf16 v[158:173], v[174:177], v[138:141], v[158:173]
	v_add_f32_e32 v27, v27, v105
	v_cvt_pk_bf16_f32 v98, v98, v99
	v_cvt_pk_bf16_f32 v99, v100, v101
	v_cvt_pk_bf16_f32 v100, v102, v103
	v_cvt_pk_bf16_f32 v101, v104, v105
	s_waitcnt lgkmcnt(0)
	v_mov_b32_e32 v2, v238
	v_mfma_f32_32x32x16_bf16 v[34:49], v[82:85], v[114:117], v[34:49]
	v_exp_f32_e32 v106, v106
	v_exp_f32_e32 v107, v107
	v_exp_f32_e32 v108, v108
	v_add_f32_e32 v27, v27, v106
	v_exp_f32_e32 v109, v109
	ds_read_b128 v[218:221], v2
	ds_read_b128 v[214:217], v2 offset:512
	ds_read_b128 v[210:213], v2 offset:2048
	v_mfma_f32_32x32x16_bf16 v[50:65], v[82:85], v[240:243], v[50:65]
	v_add_f32_e32 v27, v27, v107
	v_exp_f32_e32 v110, v110
	v_add_f32_e32 v27, v27, v108
	v_exp_f32_e32 v111, v111
	v_add_f32_e32 v27, v27, v109
	ds_read_b128 v[206:209], v2 offset:2560
	ds_read_b128 v[202:205], v2 offset:4096
	ds_read_b128 v[198:201], v2 offset:4608
	v_mfma_f32_32x32x16_bf16 v[34:49], v[90:93], v[118:121], v[34:49]
	v_exp_f32_e32 v112, v112
	v_add_f32_e32 v27, v27, v110
	v_exp_f32_e32 v113, v113
	v_add_f32_e32 v27, v27, v111
	v_add_f32_e32 v27, v27, v112
	ds_read_b128 v[194:197], v2 offset:6144
	ds_read_b128 v[190:193], v2 offset:6656
	ds_read_b128 v[186:189], v2 offset:8192
	v_mfma_f32_32x32x16_bf16 v[50:65], v[90:93], v[244:247], v[50:65]
	v_add_f32_e32 v27, v27, v113
	v_cvt_pk_bf16_f32 v106, v106, v107
	v_cvt_pk_bf16_f32 v107, v108, v109
	v_cvt_pk_bf16_f32 v108, v110, v111
	v_cvt_pk_bf16_f32 v109, v112, v113
	v_add_f32_e32 v236, v236, v27
	ds_read_b128 v[182:185], v2 offset:8704
	ds_read_b128 v[178:181], v2 offset:10240
	ds_read_b128 v[174:177], v2 offset:10752
	v_mfma_f32_32x32x16_bf16 v[34:49], v[98:101], v[122:125], v[34:49]
	v_max3_f32 v19, v142, v143, v144
	v_max3_f32 v26, v145, v146, v147
	v_max3_f32 v19, v19, v148, v149
	v_max3_f32 v26, v26, v150, v151
	v_mfma_f32_32x32x16_bf16 v[50:65], v[98:101], v[248:251], v[50:65]
	v_max3_f32 v19, v19, v152, v153
	v_max3_f32 v26, v26, v154, v155
	v_max3_f32 v19, v19, v156, v157
	v_max3_f32 v26, v26, v158, v159
	v_mfma_f32_32x32x16_bf16 v[34:49], v[106:109], v[126:129], v[34:49]
	v_max3_f32 v19, v19, v160, v161
	v_max3_f32 v26, v26, v162, v163
	v_max3_f32 v19, v19, v164, v165
	v_max3_f32 v26, v26, v166, v167
	v_mfma_f32_32x32x16_bf16 v[50:65], v[106:109], v[20:23], v[50:65]
	v_max3_f32 v19, v19, v168, v169
	v_max3_f32 v26, v26, v170, v171
	v_max3_f32 v19, v19, v172, v173
	v_max_f32_e32 v19, v19, v26
	v_cmp_lt_f32_e32 vcc, s41, v19
	s_cbranch_vccz .Lmy_nors_33
	s_nop 15
	s_nop 15
	v_mov_b32_e32 v26, v19
	s_nop 1
	v_permlane32_swap_b32_e32 v19, v26
	v_max_f32_e32 v19, v19, v26
	v_max_f32_e32 v19, v19, v19
	v_max_f32_e32 v90, 0, v19
	v_exp_f32_e64 v91, -v90
	v_add_f32_e32 v239, v239, v90
	v_xor_b32_e32 v66, 0x80000000, v239
	v_mov_b32_e32 v67, v66
	v_mov_b32_e32 v68, v66
	v_mov_b32_e32 v69, v66
	v_mov_b32_e32 v70, v66
	v_mov_b32_e32 v71, v66
	v_mov_b32_e32 v72, v66
	v_mov_b32_e32 v73, v66
	v_mov_b32_e32 v74, v66
	v_mov_b32_e32 v75, v66
	v_mov_b32_e32 v76, v66
	v_mov_b32_e32 v77, v66
	v_mov_b32_e32 v78, v66
	v_mov_b32_e32 v79, v66
	v_mov_b32_e32 v80, v66
	v_mov_b32_e32 v81, v66
	v_sub_f32_e32 v142, v142, v90
	v_sub_f32_e32 v143, v143, v90
	v_sub_f32_e32 v144, v144, v90
	v_sub_f32_e32 v145, v145, v90
	v_sub_f32_e32 v146, v146, v90
	v_sub_f32_e32 v147, v147, v90
	v_sub_f32_e32 v148, v148, v90
	v_sub_f32_e32 v149, v149, v90
	v_sub_f32_e32 v150, v150, v90
	v_sub_f32_e32 v151, v151, v90
	v_sub_f32_e32 v152, v152, v90
	v_sub_f32_e32 v153, v153, v90
	v_sub_f32_e32 v154, v154, v90
	v_sub_f32_e32 v155, v155, v90
	v_sub_f32_e32 v156, v156, v90
	v_sub_f32_e32 v157, v157, v90
	v_sub_f32_e32 v158, v158, v90
	v_sub_f32_e32 v159, v159, v90
	v_sub_f32_e32 v160, v160, v90
	v_sub_f32_e32 v161, v161, v90
	v_sub_f32_e32 v162, v162, v90
	v_sub_f32_e32 v163, v163, v90
	v_sub_f32_e32 v164, v164, v90
	v_sub_f32_e32 v165, v165, v90
	v_sub_f32_e32 v166, v166, v90
	v_sub_f32_e32 v167, v167, v90
	v_sub_f32_e32 v168, v168, v90
	v_sub_f32_e32 v169, v169, v90
	v_sub_f32_e32 v170, v170, v90
	v_sub_f32_e32 v171, v171, v90
	v_sub_f32_e32 v172, v172, v90
	v_sub_f32_e32 v173, v173, v90
	v_mul_f32_e32 v236, v236, v91
	s_mov_b64 s[96:97], exec
	s_and_b64 exec, exec, s[8:9]
	ds_write_b32 v235, v91
	s_mov_b64 exec, s[96:97]
	v_lshl_add_u32 v2, v228, 4, s47
	ds_read_b128 v[94:97], v2 offset:0
	s_waitcnt lgkmcnt(0)
	v_mul_f32_e32 v34, v34, v94
	v_mul_f32_e32 v50, v50, v94
	v_mul_f32_e32 v35, v35, v95
	v_mul_f32_e32 v51, v51, v95
	v_mul_f32_e32 v36, v36, v96
	v_mul_f32_e32 v52, v52, v96
	v_mul_f32_e32 v37, v37, v97
	v_mul_f32_e32 v53, v53, v97
	ds_read_b128 v[94:97], v2 offset:32
	s_waitcnt lgkmcnt(0)
	v_mul_f32_e32 v38, v38, v94
	v_mul_f32_e32 v54, v54, v94
	v_mul_f32_e32 v39, v39, v95
	v_mul_f32_e32 v55, v55, v95
	v_mul_f32_e32 v40, v40, v96
	v_mul_f32_e32 v56, v56, v96
	v_mul_f32_e32 v41, v41, v97
	v_mul_f32_e32 v57, v57, v97
	ds_read_b128 v[94:97], v2 offset:64
	s_waitcnt lgkmcnt(0)
	v_mul_f32_e32 v42, v42, v94
	v_mul_f32_e32 v58, v58, v94
	v_mul_f32_e32 v43, v43, v95
	v_mul_f32_e32 v59, v59, v95
	v_mul_f32_e32 v44, v44, v96
	v_mul_f32_e32 v60, v60, v96
	v_mul_f32_e32 v45, v45, v97
	v_mul_f32_e32 v61, v61, v97
	ds_read_b128 v[94:97], v2 offset:96
	s_waitcnt lgkmcnt(0)
	v_mul_f32_e32 v46, v46, v94
	v_mul_f32_e32 v62, v62, v94
	v_mul_f32_e32 v47, v47, v95
	v_mul_f32_e32 v63, v63, v95
	v_mul_f32_e32 v48, v48, v96
	v_mul_f32_e32 v64, v64, v96
	v_mul_f32_e32 v49, v49, v97
	v_mul_f32_e32 v65, v65, v97
.Lmy_nors_33:
	s_waitcnt lgkmcnt(0)
	v_add_u32_e32 v2, 0x6000, v237
	v_mfma_f32_32x32x16_bf16 v[82:97], v[218:221], v[4:7], v[66:81]
	v_exp_f32_e32 v142, v142
	v_exp_f32_e32 v143, v143
	v_exp_f32_e32 v144, v144
	v_add_f32_e32 v27, v142, v143
	v_exp_f32_e32 v145, v145
	v_mfma_f32_32x32x16_bf16 v[98:113], v[214:217], v[4:7], v[66:81]
	v_exp_f32_e32 v146, v146
	v_add_f32_e32 v27, v27, v144
	v_exp_f32_e32 v147, v147
	v_add_f32_e32 v27, v27, v145
	v_exp_f32_e32 v148, v148
	v_mfma_f32_32x32x16_bf16 v[82:97], v[210:213], v[8:11], v[82:97]
	v_add_f32_e32 v27, v27, v146
	v_exp_f32_e32 v149, v149
	v_add_f32_e32 v27, v27, v147
	v_add_f32_e32 v27, v27, v148
	v_add_f32_e32 v27, v27, v149
	v_mfma_f32_32x32x16_bf16 v[98:113], v[206:209], v[8:11], v[98:113]
	v_cvt_pk_bf16_f32 v142, v142, v143
	v_cvt_pk_bf16_f32 v143, v144, v145
	v_cvt_pk_bf16_f32 v144, v146, v147
	v_cvt_pk_bf16_f32 v145, v148, v149
	v_mfma_f32_32x32x16_bf16 v[82:97], v[202:205], v[12:15], v[82:97]
	v_exp_f32_e32 v150, v150
	v_exp_f32_e32 v151, v151
	v_exp_f32_e32 v152, v152
	v_add_f32_e32 v27, v27, v150
	v_exp_f32_e32 v153, v153
	v_mfma_f32_32x32x16_bf16 v[98:113], v[198:201], v[12:15], v[98:113]
	v_add_f32_e32 v27, v27, v151
	v_exp_f32_e32 v154, v154
	v_add_f32_e32 v27, v27, v152
	v_exp_f32_e32 v155, v155
	v_add_f32_e32 v27, v27, v153
	s_waitcnt vmcnt(4)
	s_barrier
	v_mfma_f32_32x32x16_bf16 v[82:97], v[194:197], v[130:133], v[82:97]
	s_add_u32 m0, s57, 0x4000
	v_exp_f32_e32 v156, v156
	v_add_f32_e32 v27, v27, v154
	global_load_lds_dwordx4 v[28:29], off
	v_lshl_add_u64 v[28:29], v[28:29], 0, s[30:31]
	v_exp_f32_e32 v157, v157
	v_add_f32_e32 v27, v27, v155
	v_add_f32_e32 v27, v27, v156
	ds_read_b64_tr_b16 v[114:115], v2 offset:49152
	ds_read_b64_tr_b16 v[116:117], v2 offset:49664
	ds_read_b64_tr_b16 v[118:119], v2 offset:50176
	ds_read_b64_tr_b16 v[120:121], v2 offset:50688
	v_mfma_f32_32x32x16_bf16 v[98:113], v[190:193], v[130:133], v[98:113]
	s_cmp_eq_u32 s79, 1
	s_cbranch_scc1 .Lmy_gl_34
	s_add_u32 m0, s40, 0x0
	s_nop 0
	global_load_lds_dwordx4 v[24:25], off
	v_lshl_add_u64 v[24:25], v[24:25], 0, s[30:31]
.Lmy_gl_34:
	v_add_f32_e32 v27, v27, v157
	v_cvt_pk_bf16_f32 v150, v150, v151
	v_cvt_pk_bf16_f32 v151, v152, v153
	v_cvt_pk_bf16_f32 v152, v154, v155
	v_cvt_pk_bf16_f32 v153, v156, v157
	ds_read_b64_tr_b16 v[122:123], v2 offset:51200
	ds_read_b64_tr_b16 v[124:125], v2 offset:51712
	ds_read_b64_tr_b16 v[126:127], v2 offset:52224
	ds_read_b64_tr_b16 v[128:129], v2 offset:52736
	v_mfma_f32_32x32x16_bf16 v[82:97], v[186:189], v[134:137], v[82:97]
	v_exp_f32_e32 v158, v158
	v_exp_f32_e32 v159, v159
	v_exp_f32_e32 v160, v160
	v_add_f32_e32 v27, v27, v158
	v_exp_f32_e32 v161, v161
	ds_read_b64_tr_b16 v[240:241], v2 offset:53248
	ds_read_b64_tr_b16 v[242:243], v2 offset:53760
	ds_read_b64_tr_b16 v[244:245], v2 offset:54272
	ds_read_b64_tr_b16 v[246:247], v2 offset:54784
	v_mfma_f32_32x32x16_bf16 v[98:113], v[182:185], v[134:137], v[98:113]
	v_add_f32_e32 v27, v27, v159
	v_exp_f32_e32 v162, v162
	v_add_f32_e32 v27, v27, v160
	v_exp_f32_e32 v163, v163
	v_add_f32_e32 v27, v27, v161
	ds_read_b64_tr_b16 v[248:249], v2 offset:55296
	ds_read_b64_tr_b16 v[250:251], v2 offset:55808
	ds_read_b64_tr_b16 v[20:21], v2 offset:56320
	ds_read_b64_tr_b16 v[22:23], v2 offset:56832
	v_mfma_f32_32x32x16_bf16 v[82:97], v[178:181], v[138:141], v[82:97]
	v_exp_f32_e32 v164, v164
	v_add_f32_e32 v27, v27, v162
	v_exp_f32_e32 v165, v165
	v_add_f32_e32 v27, v27, v163
	v_add_f32_e32 v27, v27, v164
	v_mfma_f32_32x32x16_bf16 v[98:113], v[174:177], v[138:141], v[98:113]
	v_add_f32_e32 v27, v27, v165
	v_cvt_pk_bf16_f32 v158, v158, v159
	v_cvt_pk_bf16_f32 v159, v160, v161
	v_cvt_pk_bf16_f32 v160, v162, v163
	v_cvt_pk_bf16_f32 v161, v164, v165
	s_waitcnt lgkmcnt(0)
	v_add_u32_e32 v2, 0x3000, v238
	v_mfma_f32_32x32x16_bf16 v[34:49], v[142:145], v[114:117], v[34:49]
	v_exp_f32_e32 v166, v166
	v_exp_f32_e32 v167, v167
	v_exp_f32_e32 v168, v168
	v_add_f32_e32 v27, v27, v166
	v_exp_f32_e32 v169, v169
	ds_read_b128 v[218:221], v2
	ds_read_b128 v[214:217], v2 offset:512
	ds_read_b128 v[210:213], v2 offset:2048
	v_mfma_f32_32x32x16_bf16 v[50:65], v[142:145], v[240:243], v[50:65]
	v_add_f32_e32 v27, v27, v167
	v_exp_f32_e32 v170, v170
	v_add_f32_e32 v27, v27, v168
	v_exp_f32_e32 v171, v171
	v_add_f32_e32 v27, v27, v169
	ds_read_b128 v[206:209], v2 offset:2560
	ds_read_b128 v[202:205], v2 offset:4096
	ds_read_b128 v[198:201], v2 offset:4608
	v_mfma_f32_32x32x16_bf16 v[34:49], v[150:153], v[118:121], v[34:49]
	v_exp_f32_e32 v172, v172
	v_add_f32_e32 v27, v27, v170
	v_exp_f32_e32 v173, v173
	v_add_f32_e32 v27, v27, v171
	v_add_f32_e32 v27, v27, v172
	ds_read_b128 v[194:197], v2 offset:6144
	ds_read_b128 v[190:193], v2 offset:6656
	ds_read_b128 v[186:189], v2 offset:8192
	v_mfma_f32_32x32x16_bf16 v[50:65], v[150:153], v[244:247], v[50:65]
	v_add_f32_e32 v27, v27, v173
	v_cvt_pk_bf16_f32 v166, v166, v167
	v_cvt_pk_bf16_f32 v167, v168, v169
	v_cvt_pk_bf16_f32 v168, v170, v171
	v_cvt_pk_bf16_f32 v169, v172, v173
	v_add_f32_e32 v236, v236, v27
	ds_read_b128 v[182:185], v2 offset:8704
	ds_read_b128 v[178:181], v2 offset:10240
	ds_read_b128 v[174:177], v2 offset:10752
	v_mfma_f32_32x32x16_bf16 v[34:49], v[158:161], v[122:125], v[34:49]
	v_max3_f32 v19, v82, v83, v84
	v_max3_f32 v26, v85, v86, v87
	v_max3_f32 v19, v19, v88, v89
	v_max3_f32 v26, v26, v90, v91
	v_mfma_f32_32x32x16_bf16 v[50:65], v[158:161], v[248:251], v[50:65]
	v_max3_f32 v19, v19, v92, v93
	v_max3_f32 v26, v26, v94, v95
	v_max3_f32 v19, v19, v96, v97
	v_max3_f32 v26, v26, v98, v99
	v_mfma_f32_32x32x16_bf16 v[34:49], v[166:169], v[126:129], v[34:49]
	v_max3_f32 v19, v19, v100, v101
	v_max3_f32 v26, v26, v102, v103
	v_max3_f32 v19, v19, v104, v105
	v_max3_f32 v26, v26, v106, v107
	v_mfma_f32_32x32x16_bf16 v[50:65], v[166:169], v[20:23], v[50:65]
	v_max3_f32 v19, v19, v108, v109
	v_max3_f32 v26, v26, v110, v111
	v_max3_f32 v19, v19, v112, v113
	v_max_f32_e32 v19, v19, v26
	v_cmp_lt_f32_e32 vcc, s41, v19
	s_cbranch_vccz .Lmy_nors_35
	s_nop 15
	s_nop 15
	v_mov_b32_e32 v26, v19
	s_nop 1
	v_permlane32_swap_b32_e32 v19, v26
	v_max_f32_e32 v19, v19, v26
	v_max_f32_e32 v19, v19, v19
	v_max_f32_e32 v150, 0, v19
	v_exp_f32_e64 v151, -v150
	v_add_f32_e32 v239, v239, v150
	v_xor_b32_e32 v66, 0x80000000, v239
	v_mov_b32_e32 v67, v66
	v_mov_b32_e32 v68, v66
	v_mov_b32_e32 v69, v66
	v_mov_b32_e32 v70, v66
	v_mov_b32_e32 v71, v66
	v_mov_b32_e32 v72, v66
	v_mov_b32_e32 v73, v66
	v_mov_b32_e32 v74, v66
	v_mov_b32_e32 v75, v66
	v_mov_b32_e32 v76, v66
	v_mov_b32_e32 v77, v66
	v_mov_b32_e32 v78, v66
	v_mov_b32_e32 v79, v66
	v_mov_b32_e32 v80, v66
	v_mov_b32_e32 v81, v66
	v_sub_f32_e32 v82, v82, v150
	v_sub_f32_e32 v83, v83, v150
	v_sub_f32_e32 v84, v84, v150
	v_sub_f32_e32 v85, v85, v150
	v_sub_f32_e32 v86, v86, v150
	v_sub_f32_e32 v87, v87, v150
	v_sub_f32_e32 v88, v88, v150
	v_sub_f32_e32 v89, v89, v150
	v_sub_f32_e32 v90, v90, v150
	v_sub_f32_e32 v91, v91, v150
	v_sub_f32_e32 v92, v92, v150
	v_sub_f32_e32 v93, v93, v150
	v_sub_f32_e32 v94, v94, v150
	v_sub_f32_e32 v95, v95, v150
	v_sub_f32_e32 v96, v96, v150
	v_sub_f32_e32 v97, v97, v150
	v_sub_f32_e32 v98, v98, v150
	v_sub_f32_e32 v99, v99, v150
	v_sub_f32_e32 v100, v100, v150
	v_sub_f32_e32 v101, v101, v150
	v_sub_f32_e32 v102, v102, v150
	v_sub_f32_e32 v103, v103, v150
	v_sub_f32_e32 v104, v104, v150
	v_sub_f32_e32 v105, v105, v150
	v_sub_f32_e32 v106, v106, v150
	v_sub_f32_e32 v107, v107, v150
	v_sub_f32_e32 v108, v108, v150
	v_sub_f32_e32 v109, v109, v150
	v_sub_f32_e32 v110, v110, v150
	v_sub_f32_e32 v111, v111, v150
	v_sub_f32_e32 v112, v112, v150
	v_sub_f32_e32 v113, v113, v150
	v_mul_f32_e32 v236, v236, v151
	s_mov_b64 s[96:97], exec
	s_and_b64 exec, exec, s[8:9]
	ds_write_b32 v235, v151
	s_mov_b64 exec, s[96:97]
	v_lshl_add_u32 v2, v228, 4, s47
	ds_read_b128 v[154:157], v2 offset:0
	s_waitcnt lgkmcnt(0)
	v_mul_f32_e32 v34, v34, v154
	v_mul_f32_e32 v50, v50, v154
	v_mul_f32_e32 v35, v35, v155
	v_mul_f32_e32 v51, v51, v155
	v_mul_f32_e32 v36, v36, v156
	v_mul_f32_e32 v52, v52, v156
	v_mul_f32_e32 v37, v37, v157
	v_mul_f32_e32 v53, v53, v157
	ds_read_b128 v[154:157], v2 offset:32
	s_waitcnt lgkmcnt(0)
	v_mul_f32_e32 v38, v38, v154
	v_mul_f32_e32 v54, v54, v154
	v_mul_f32_e32 v39, v39, v155
	v_mul_f32_e32 v55, v55, v155
	v_mul_f32_e32 v40, v40, v156
	v_mul_f32_e32 v56, v56, v156
	v_mul_f32_e32 v41, v41, v157
	v_mul_f32_e32 v57, v57, v157
	ds_read_b128 v[154:157], v2 offset:64
	s_waitcnt lgkmcnt(0)
	v_mul_f32_e32 v42, v42, v154
	v_mul_f32_e32 v58, v58, v154
	v_mul_f32_e32 v43, v43, v155
	v_mul_f32_e32 v59, v59, v155
	v_mul_f32_e32 v44, v44, v156
	v_mul_f32_e32 v60, v60, v156
	v_mul_f32_e32 v45, v45, v157
	v_mul_f32_e32 v61, v61, v157
	ds_read_b128 v[154:157], v2 offset:96
	s_waitcnt lgkmcnt(0)
	v_mul_f32_e32 v46, v46, v154
	v_mul_f32_e32 v62, v62, v154
	v_mul_f32_e32 v47, v47, v155
	v_mul_f32_e32 v63, v63, v155
	v_mul_f32_e32 v48, v48, v156
	v_mul_f32_e32 v64, v64, v156
	v_mul_f32_e32 v49, v49, v157
	v_mul_f32_e32 v65, v65, v157

.Lmy_B_loop:
	s_waitcnt lgkmcnt(0)
	v_mov_b32_e32 v2, v237
	v_mfma_f32_32x32x16_bf16 v[142:157], v[218:221], v[4:7], v[66:81]
	v_exp_f32_e32 v82, v82
	v_exp_f32_e32 v83, v83
	v_exp_f32_e32 v84, v84
	v_add_f32_e32 v27, v82, v83
	v_exp_f32_e32 v85, v85
	v_mfma_f32_32x32x16_bf16 v[158:173], v[214:217], v[4:7], v[66:81]
	v_exp_f32_e32 v86, v86
	v_add_f32_e32 v27, v27, v84
	v_exp_f32_e32 v87, v87
	v_add_f32_e32 v27, v27, v85
	v_exp_f32_e32 v88, v88
	v_mfma_f32_32x32x16_bf16 v[142:157], v[210:213], v[8:11], v[142:157]
	v_add_f32_e32 v27, v27, v86
	v_exp_f32_e32 v89, v89
	v_add_f32_e32 v27, v27, v87
	v_add_f32_e32 v27, v27, v88
	v_add_f32_e32 v27, v27, v89
	v_mfma_f32_32x32x16_bf16 v[158:173], v[206:209], v[8:11], v[158:173]
	v_cvt_pk_bf16_f32 v82, v82, v83
	v_cvt_pk_bf16_f32 v83, v84, v85
	v_cvt_pk_bf16_f32 v84, v86, v87
	v_cvt_pk_bf16_f32 v85, v88, v89
	v_mfma_f32_32x32x16_bf16 v[142:157], v[202:205], v[12:15], v[142:157]
	v_exp_f32_e32 v90, v90
	v_exp_f32_e32 v91, v91
	v_exp_f32_e32 v92, v92
	v_add_f32_e32 v27, v27, v90
	v_exp_f32_e32 v93, v93
	v_mfma_f32_32x32x16_bf16 v[158:173], v[198:201], v[12:15], v[158:173]
	v_add_f32_e32 v27, v27, v91
	v_exp_f32_e32 v94, v94
	v_add_f32_e32 v27, v27, v92
	v_exp_f32_e32 v95, v95
	v_add_f32_e32 v27, v27, v93
	s_waitcnt vmcnt(4)
	s_barrier
	v_mfma_f32_32x32x16_bf16 v[142:157], v[194:197], v[130:133], v[142:157]
	s_add_u32 m0, s57, 0x6000
	v_exp_f32_e32 v96, v96
	v_add_f32_e32 v27, v27, v94
	global_load_lds_dwordx4 v[28:29], off
	v_lshl_add_u64 v[28:29], v[28:29], 0, s[30:31]
	v_exp_f32_e32 v97, v97
	v_add_f32_e32 v27, v27, v95
	v_add_f32_e32 v27, v27, v96
	ds_read_b64_tr_b16 v[114:115], v2 offset:49152
	ds_read_b64_tr_b16 v[116:117], v2 offset:49664
	ds_read_b64_tr_b16 v[118:119], v2 offset:50176
	ds_read_b64_tr_b16 v[120:121], v2 offset:50688
	v_mfma_f32_32x32x16_bf16 v[158:173], v[190:193], v[130:133], v[158:173]
	s_add_u32 m0, s40, 0x3000
	v_add_f32_e32 v27, v27, v97
	v_cvt_pk_bf16_f32 v90, v90, v91
	global_load_lds_dwordx4 v[24:25], off
	v_lshl_add_u64 v[24:25], v[24:25], 0, s[30:31]
	v_cvt_pk_bf16_f32 v91, v92, v93
	v_cvt_pk_bf16_f32 v92, v94, v95
	v_cvt_pk_bf16_f32 v93, v96, v97
	ds_read_b64_tr_b16 v[122:123], v2 offset:51200
	ds_read_b64_tr_b16 v[124:125], v2 offset:51712
	ds_read_b64_tr_b16 v[126:127], v2 offset:52224
	ds_read_b64_tr_b16 v[128:129], v2 offset:52736
	v_mfma_f32_32x32x16_bf16 v[142:157], v[186:189], v[134:137], v[142:157]
	v_exp_f32_e32 v98, v98
	v_exp_f32_e32 v99, v99
	v_exp_f32_e32 v100, v100
	v_add_f32_e32 v27, v27, v98
	v_exp_f32_e32 v101, v101
	ds_read_b64_tr_b16 v[240:241], v2 offset:53248
	ds_read_b64_tr_b16 v[242:243], v2 offset:53760
	ds_read_b64_tr_b16 v[244:245], v2 offset:54272
	ds_read_b64_tr_b16 v[246:247], v2 offset:54784
	v_mfma_f32_32x32x16_bf16 v[158:173], v[182:185], v[134:137], v[158:173]
	v_add_f32_e32 v27, v27, v99
	v_exp_f32_e32 v102, v102
	v_add_f32_e32 v27, v27, v100
	v_exp_f32_e32 v103, v103
	v_add_f32_e32 v27, v27, v101
	ds_read_b64_tr_b16 v[248:249], v2 offset:55296
	ds_read_b64_tr_b16 v[250:251], v2 offset:55808
	ds_read_b64_tr_b16 v[20:21], v2 offset:56320
	ds_read_b64_tr_b16 v[22:23], v2 offset:56832
	v_mfma_f32_32x32x16_bf16 v[142:157], v[178:181], v[138:141], v[142:157]
	v_exp_f32_e32 v104, v104
	v_add_f32_e32 v27, v27, v102
	v_exp_f32_e32 v105, v105
	v_add_f32_e32 v27, v27, v103
	v_add_f32_e32 v27, v27, v104
	v_mfma_f32_32x32x16_bf16 v[158:173], v[174:177], v[138:141], v[158:173]
	v_add_f32_e32 v27, v27, v105
	v_cvt_pk_bf16_f32 v98, v98, v99
	v_cvt_pk_bf16_f32 v99, v100, v101
	v_cvt_pk_bf16_f32 v100, v102, v103
	v_cvt_pk_bf16_f32 v101, v104, v105
	s_waitcnt lgkmcnt(0)
	v_add_u32_e32 v2, 0x6000, v238
	v_mfma_f32_32x32x16_bf16 v[34:49], v[82:85], v[114:117], v[34:49]
	v_exp_f32_e32 v106, v106
	v_exp_f32_e32 v107, v107
	v_exp_f32_e32 v108, v108
	v_add_f32_e32 v27, v27, v106
	v_exp_f32_e32 v109, v109
	ds_read_b128 v[218:221], v2
	ds_read_b128 v[214:217], v2 offset:512
	ds_read_b128 v[210:213], v2 offset:2048
	v_mfma_f32_32x32x16_bf16 v[50:65], v[82:85], v[240:243], v[50:65]
	v_add_f32_e32 v27, v27, v107
	v_exp_f32_e32 v110, v110
	v_add_f32_e32 v27, v27, v108
	v_exp_f32_e32 v111, v111
	v_add_f32_e32 v27, v27, v109
	ds_read_b128 v[206:209], v2 offset:2560
	ds_read_b128 v[202:205], v2 offset:4096
	ds_read_b128 v[198:201], v2 offset:4608
	v_mfma_f32_32x32x16_bf16 v[34:49], v[90:93], v[118:121], v[34:49]
	v_exp_f32_e32 v112, v112
	v_add_f32_e32 v27, v27, v110
	v_exp_f32_e32 v113, v113
	v_add_f32_e32 v27, v27, v111
	v_add_f32_e32 v27, v27, v112
	ds_read_b128 v[194:197], v2 offset:6144
	ds_read_b128 v[190:193], v2 offset:6656
	ds_read_b128 v[186:189], v2 offset:8192
	v_mfma_f32_32x32x16_bf16 v[50:65], v[90:93], v[244:247], v[50:65]
	v_add_f32_e32 v27, v27, v113
	v_cvt_pk_bf16_f32 v106, v106, v107
	v_cvt_pk_bf16_f32 v107, v108, v109
	v_cvt_pk_bf16_f32 v108, v110, v111
	v_cvt_pk_bf16_f32 v109, v112, v113
	v_add_f32_e32 v236, v236, v27
	ds_read_b128 v[182:185], v2 offset:8704
	ds_read_b128 v[178:181], v2 offset:10240
	ds_read_b128 v[174:177], v2 offset:10752
	v_mfma_f32_32x32x16_bf16 v[34:49], v[98:101], v[122:125], v[34:49]
	v_max3_f32 v19, v142, v143, v144
	v_max3_f32 v26, v145, v146, v147
	v_max3_f32 v19, v19, v148, v149
	v_max3_f32 v26, v26, v150, v151
	v_mfma_f32_32x32x16_bf16 v[50:65], v[98:101], v[248:251], v[50:65]
	v_max3_f32 v19, v19, v152, v153
	v_max3_f32 v26, v26, v154, v155
	v_max3_f32 v19, v19, v156, v157
	v_max3_f32 v26, v26, v158, v159
	v_mfma_f32_32x32x16_bf16 v[34:49], v[106:109], v[126:129], v[34:49]
	v_max3_f32 v19, v19, v160, v161
	v_max3_f32 v26, v26, v162, v163
	v_max3_f32 v19, v19, v164, v165
	v_max3_f32 v26, v26, v166, v167
	v_mfma_f32_32x32x16_bf16 v[50:65], v[106:109], v[20:23], v[50:65]
	v_max3_f32 v19, v19, v168, v169
	v_max3_f32 v26, v26, v170, v171
	v_max3_f32 v19, v19, v172, v173
	v_max_f32_e32 v19, v19, v26
	v_cmp_lt_f32_e32 vcc, s41, v19
	s_cbranch_vccz .Lmy_nors_36
	s_nop 15
	s_nop 15
	v_mov_b32_e32 v26, v19
	s_nop 1
	v_permlane32_swap_b32_e32 v19, v26
	v_max_f32_e32 v19, v19, v26
	v_max_f32_e32 v19, v19, v19
	v_max_f32_e32 v90, 0, v19
	v_exp_f32_e64 v91, -v90
	v_add_f32_e32 v239, v239, v90
	v_xor_b32_e32 v66, 0x80000000, v239
	v_mov_b32_e32 v67, v66
	v_mov_b32_e32 v68, v66
	v_mov_b32_e32 v69, v66
	v_mov_b32_e32 v70, v66
	v_mov_b32_e32 v71, v66
	v_mov_b32_e32 v72, v66
	v_mov_b32_e32 v73, v66
	v_mov_b32_e32 v74, v66
	v_mov_b32_e32 v75, v66
	v_mov_b32_e32 v76, v66
	v_mov_b32_e32 v77, v66
	v_mov_b32_e32 v78, v66
	v_mov_b32_e32 v79, v66
	v_mov_b32_e32 v80, v66
	v_mov_b32_e32 v81, v66
	v_sub_f32_e32 v142, v142, v90
	v_sub_f32_e32 v143, v143, v90
	v_sub_f32_e32 v144, v144, v90
	v_sub_f32_e32 v145, v145, v90
	v_sub_f32_e32 v146, v146, v90
	v_sub_f32_e32 v147, v147, v90
	v_sub_f32_e32 v148, v148, v90
	v_sub_f32_e32 v149, v149, v90
	v_sub_f32_e32 v150, v150, v90
	v_sub_f32_e32 v151, v151, v90
	v_sub_f32_e32 v152, v152, v90
	v_sub_f32_e32 v153, v153, v90
	v_sub_f32_e32 v154, v154, v90
	v_sub_f32_e32 v155, v155, v90
	v_sub_f32_e32 v156, v156, v90
	v_sub_f32_e32 v157, v157, v90
	v_sub_f32_e32 v158, v158, v90
	v_sub_f32_e32 v159, v159, v90
	v_sub_f32_e32 v160, v160, v90
	v_sub_f32_e32 v161, v161, v90
	v_sub_f32_e32 v162, v162, v90
	v_sub_f32_e32 v163, v163, v90
	v_sub_f32_e32 v164, v164, v90
	v_sub_f32_e32 v165, v165, v90
	v_sub_f32_e32 v166, v166, v90
	v_sub_f32_e32 v167, v167, v90
	v_sub_f32_e32 v168, v168, v90
	v_sub_f32_e32 v169, v169, v90
	v_sub_f32_e32 v170, v170, v90
	v_sub_f32_e32 v171, v171, v90
	v_sub_f32_e32 v172, v172, v90
	v_sub_f32_e32 v173, v173, v90
	v_mul_f32_e32 v236, v236, v91
	s_mov_b64 s[96:97], exec
	s_and_b64 exec, exec, s[8:9]
	ds_write_b32 v235, v91
	s_mov_b64 exec, s[96:97]
	v_lshl_add_u32 v2, v228, 4, s47
	ds_read_b128 v[94:97], v2 offset:0
	s_waitcnt lgkmcnt(0)
	v_mul_f32_e32 v34, v34, v94
	v_mul_f32_e32 v50, v50, v94
	v_mul_f32_e32 v35, v35, v95
	v_mul_f32_e32 v51, v51, v95
	v_mul_f32_e32 v36, v36, v96
	v_mul_f32_e32 v52, v52, v96
	v_mul_f32_e32 v37, v37, v97
	v_mul_f32_e32 v53, v53, v97
	ds_read_b128 v[94:97], v2 offset:32
	s_waitcnt lgkmcnt(0)
	v_mul_f32_e32 v38, v38, v94
	v_mul_f32_e32 v54, v54, v94
	v_mul_f32_e32 v39, v39, v95
	v_mul_f32_e32 v55, v55, v95
	v_mul_f32_e32 v40, v40, v96
	v_mul_f32_e32 v56, v56, v96
	v_mul_f32_e32 v41, v41, v97
	v_mul_f32_e32 v57, v57, v97
	ds_read_b128 v[94:97], v2 offset:64
	s_waitcnt lgkmcnt(0)
	v_mul_f32_e32 v42, v42, v94
	v_mul_f32_e32 v58, v58, v94
	v_mul_f32_e32 v43, v43, v95
	v_mul_f32_e32 v59, v59, v95
	v_mul_f32_e32 v44, v44, v96
	v_mul_f32_e32 v60, v60, v96
	v_mul_f32_e32 v45, v45, v97
	v_mul_f32_e32 v61, v61, v97
	ds_read_b128 v[94:97], v2 offset:96
	s_waitcnt lgkmcnt(0)
	v_mul_f32_e32 v46, v46, v94
	v_mul_f32_e32 v62, v62, v94
	v_mul_f32_e32 v47, v47, v95
	v_mul_f32_e32 v63, v63, v95
	v_mul_f32_e32 v48, v48, v96
	v_mul_f32_e32 v64, v64, v96
	v_mul_f32_e32 v49, v49, v97
	v_mul_f32_e32 v65, v65, v97
.Lmy_nors_36:
	s_waitcnt lgkmcnt(0)
	v_add_u32_e32 v2, 0x2000, v237
	v_mfma_f32_32x32x16_bf16 v[82:97], v[218:221], v[4:7], v[66:81]
	v_exp_f32_e32 v142, v142
	v_exp_f32_e32 v143, v143
	v_exp_f32_e32 v144, v144
	v_add_f32_e32 v27, v142, v143
	v_exp_f32_e32 v145, v145
	v_mfma_f32_32x32x16_bf16 v[98:113], v[214:217], v[4:7], v[66:81]
	v_exp_f32_e32 v146, v146
	v_add_f32_e32 v27, v27, v144
	v_exp_f32_e32 v147, v147
	v_add_f32_e32 v27, v27, v145
	v_exp_f32_e32 v148, v148
	v_mfma_f32_32x32x16_bf16 v[82:97], v[210:213], v[8:11], v[82:97]
	v_add_f32_e32 v27, v27, v146
	v_exp_f32_e32 v149, v149
	v_add_f32_e32 v27, v27, v147
	v_add_f32_e32 v27, v27, v148
	v_add_f32_e32 v27, v27, v149
	v_mfma_f32_32x32x16_bf16 v[98:113], v[206:209], v[8:11], v[98:113]
	v_cvt_pk_bf16_f32 v142, v142, v143
	v_cvt_pk_bf16_f32 v143, v144, v145
	v_cvt_pk_bf16_f32 v144, v146, v147
	v_cvt_pk_bf16_f32 v145, v148, v149
	v_mfma_f32_32x32x16_bf16 v[82:97], v[202:205], v[12:15], v[82:97]
	v_exp_f32_e32 v150, v150
	v_exp_f32_e32 v151, v151
	v_exp_f32_e32 v152, v152
	v_add_f32_e32 v27, v27, v150
	v_exp_f32_e32 v153, v153
	v_mfma_f32_32x32x16_bf16 v[98:113], v[198:201], v[12:15], v[98:113]
	v_add_f32_e32 v27, v27, v151
	v_exp_f32_e32 v154, v154
	v_add_f32_e32 v27, v27, v152
	v_exp_f32_e32 v155, v155
	v_add_f32_e32 v27, v27, v153
	s_waitcnt vmcnt(4)
	s_barrier
	v_mfma_f32_32x32x16_bf16 v[82:97], v[194:197], v[130:133], v[82:97]
	s_add_u32 m0, s57, 0x0
	v_exp_f32_e32 v156, v156
	v_add_f32_e32 v27, v27, v154
	global_load_lds_dwordx4 v[28:29], off
	v_lshl_add_u64 v[28:29], v[28:29], 0, s[30:31]
	v_exp_f32_e32 v157, v157
	v_add_f32_e32 v27, v27, v155
	v_add_f32_e32 v27, v27, v156
	ds_read_b64_tr_b16 v[114:115], v2 offset:49152
	ds_read_b64_tr_b16 v[116:117], v2 offset:49664
	ds_read_b64_tr_b16 v[118:119], v2 offset:50176
	ds_read_b64_tr_b16 v[120:121], v2 offset:50688
	v_mfma_f32_32x32x16_bf16 v[98:113], v[190:193], v[130:133], v[98:113]
	s_add_u32 m0, s40, 0x6000
	v_add_f32_e32 v27, v27, v157
	v_cvt_pk_bf16_f32 v150, v150, v151
	global_load_lds_dwordx4 v[24:25], off
	v_lshl_add_u64 v[24:25], v[24:25], 0, s[30:31]
	v_cvt_pk_bf16_f32 v151, v152, v153
	v_cvt_pk_bf16_f32 v152, v154, v155
	v_cvt_pk_bf16_f32 v153, v156, v157
	ds_read_b64_tr_b16 v[122:123], v2 offset:51200
	ds_read_b64_tr_b16 v[124:125], v2 offset:51712
	ds_read_b64_tr_b16 v[126:127], v2 offset:52224
	ds_read_b64_tr_b16 v[128:129], v2 offset:52736
	v_mfma_f32_32x32x16_bf16 v[82:97], v[186:189], v[134:137], v[82:97]
	v_exp_f32_e32 v158, v158
	v_exp_f32_e32 v159, v159
	v_exp_f32_e32 v160, v160
	v_add_f32_e32 v27, v27, v158
	v_exp_f32_e32 v161, v161
	ds_read_b64_tr_b16 v[240:241], v2 offset:53248
	ds_read_b64_tr_b16 v[242:243], v2 offset:53760
	ds_read_b64_tr_b16 v[244:245], v2 offset:54272
	ds_read_b64_tr_b16 v[246:247], v2 offset:54784
	v_mfma_f32_32x32x16_bf16 v[98:113], v[182:185], v[134:137], v[98:113]
	v_add_f32_e32 v27, v27, v159
	v_exp_f32_e32 v162, v162
	v_add_f32_e32 v27, v27, v160
	v_exp_f32_e32 v163, v163
	v_add_f32_e32 v27, v27, v161
	ds_read_b64_tr_b16 v[248:249], v2 offset:55296
	ds_read_b64_tr_b16 v[250:251], v2 offset:55808
	ds_read_b64_tr_b16 v[20:21], v2 offset:56320
	ds_read_b64_tr_b16 v[22:23], v2 offset:56832
	v_mfma_f32_32x32x16_bf16 v[82:97], v[178:181], v[138:141], v[82:97]
	v_exp_f32_e32 v164, v164
	v_add_f32_e32 v27, v27, v162
	v_exp_f32_e32 v165, v165
	v_add_f32_e32 v27, v27, v163
	v_add_f32_e32 v27, v27, v164
	v_mfma_f32_32x32x16_bf16 v[98:113], v[174:177], v[138:141], v[98:113]
	v_add_f32_e32 v27, v27, v165
	v_cvt_pk_bf16_f32 v158, v158, v159
	v_cvt_pk_bf16_f32 v159, v160, v161
	v_cvt_pk_bf16_f32 v160, v162, v163
	v_cvt_pk_bf16_f32 v161, v164, v165
	s_waitcnt lgkmcnt(0)
	v_add_u32_e32 v2, 0x9000, v238
	v_mfma_f32_32x32x16_bf16 v[34:49], v[142:145], v[114:117], v[34:49]
	v_exp_f32_e32 v166, v166
	v_exp_f32_e32 v167, v167
	v_exp_f32_e32 v168, v168
	v_add_f32_e32 v27, v27, v166
	v_exp_f32_e32 v169, v169
	ds_read_b128 v[218:221], v2
	ds_read_b128 v[214:217], v2 offset:512
	ds_read_b128 v[210:213], v2 offset:2048
	v_mfma_f32_32x32x16_bf16 v[50:65], v[142:145], v[240:243], v[50:65]
	v_add_f32_e32 v27, v27, v167
	v_exp_f32_e32 v170, v170
	v_add_f32_e32 v27, v27, v168
	v_exp_f32_e32 v171, v171
	v_add_f32_e32 v27, v27, v169
	ds_read_b128 v[206:209], v2 offset:2560
	ds_read_b128 v[202:205], v2 offset:4096
	ds_read_b128 v[198:201], v2 offset:4608
	v_mfma_f32_32x32x16_bf16 v[34:49], v[150:153], v[118:121], v[34:49]
	v_exp_f32_e32 v172, v172
	v_add_f32_e32 v27, v27, v170
	v_exp_f32_e32 v173, v173
	v_add_f32_e32 v27, v27, v171
	v_add_f32_e32 v27, v27, v172
	ds_read_b128 v[194:197], v2 offset:6144
	ds_read_b128 v[190:193], v2 offset:6656
	ds_read_b128 v[186:189], v2 offset:8192
	v_mfma_f32_32x32x16_bf16 v[50:65], v[150:153], v[244:247], v[50:65]
	v_add_f32_e32 v27, v27, v173
	v_cvt_pk_bf16_f32 v166, v166, v167
	v_cvt_pk_bf16_f32 v167, v168, v169
	v_cvt_pk_bf16_f32 v168, v170, v171
	v_cvt_pk_bf16_f32 v169, v172, v173
	v_add_f32_e32 v236, v236, v27
	ds_read_b128 v[182:185], v2 offset:8704
	ds_read_b128 v[178:181], v2 offset:10240
	ds_read_b128 v[174:177], v2 offset:10752
	v_mfma_f32_32x32x16_bf16 v[34:49], v[158:161], v[122:125], v[34:49]
	v_max3_f32 v19, v82, v83, v84
	v_max3_f32 v26, v85, v86, v87
	v_max3_f32 v19, v19, v88, v89
	v_max3_f32 v26, v26, v90, v91
	v_mfma_f32_32x32x16_bf16 v[50:65], v[158:161], v[248:251], v[50:65]
	v_max3_f32 v19, v19, v92, v93
	v_max3_f32 v26, v26, v94, v95
	v_max3_f32 v19, v19, v96, v97
	v_max3_f32 v26, v26, v98, v99
	v_mfma_f32_32x32x16_bf16 v[34:49], v[166:169], v[126:129], v[34:49]
	v_max3_f32 v19, v19, v100, v101
	v_max3_f32 v26, v26, v102, v103
	v_max3_f32 v19, v19, v104, v105
	v_max3_f32 v26, v26, v106, v107
	v_mfma_f32_32x32x16_bf16 v[50:65], v[166:169], v[20:23], v[50:65]
	v_max3_f32 v19, v19, v108, v109
	v_max3_f32 v26, v26, v110, v111
	v_max3_f32 v19, v19, v112, v113
	v_max_f32_e32 v19, v19, v26
	v_cmp_lt_f32_e32 vcc, s41, v19
	s_cbranch_vccz .Lmy_nors_37
	s_nop 15
	s_nop 15
	v_mov_b32_e32 v26, v19
	s_nop 1
	v_permlane32_swap_b32_e32 v19, v26
	v_max_f32_e32 v19, v19, v26
	v_max_f32_e32 v19, v19, v19
	v_max_f32_e32 v150, 0, v19
	v_exp_f32_e64 v151, -v150
	v_add_f32_e32 v239, v239, v150
	v_xor_b32_e32 v66, 0x80000000, v239
	v_mov_b32_e32 v67, v66
	v_mov_b32_e32 v68, v66
	v_mov_b32_e32 v69, v66
	v_mov_b32_e32 v70, v66
	v_mov_b32_e32 v71, v66
	v_mov_b32_e32 v72, v66
	v_mov_b32_e32 v73, v66
	v_mov_b32_e32 v74, v66
	v_mov_b32_e32 v75, v66
	v_mov_b32_e32 v76, v66
	v_mov_b32_e32 v77, v66
	v_mov_b32_e32 v78, v66
	v_mov_b32_e32 v79, v66
	v_mov_b32_e32 v80, v66
	v_mov_b32_e32 v81, v66
	v_sub_f32_e32 v82, v82, v150
	v_sub_f32_e32 v83, v83, v150
	v_sub_f32_e32 v84, v84, v150
	v_sub_f32_e32 v85, v85, v150
	v_sub_f32_e32 v86, v86, v150
	v_sub_f32_e32 v87, v87, v150
	v_sub_f32_e32 v88, v88, v150
	v_sub_f32_e32 v89, v89, v150
	v_sub_f32_e32 v90, v90, v150
	v_sub_f32_e32 v91, v91, v150
	v_sub_f32_e32 v92, v92, v150
	v_sub_f32_e32 v93, v93, v150
	v_sub_f32_e32 v94, v94, v150
	v_sub_f32_e32 v95, v95, v150
	v_sub_f32_e32 v96, v96, v150
	v_sub_f32_e32 v97, v97, v150
	v_sub_f32_e32 v98, v98, v150
	v_sub_f32_e32 v99, v99, v150
	v_sub_f32_e32 v100, v100, v150
	v_sub_f32_e32 v101, v101, v150
	v_sub_f32_e32 v102, v102, v150
	v_sub_f32_e32 v103, v103, v150
	v_sub_f32_e32 v104, v104, v150
	v_sub_f32_e32 v105, v105, v150
	v_sub_f32_e32 v106, v106, v150
	v_sub_f32_e32 v107, v107, v150
	v_sub_f32_e32 v108, v108, v150
	v_sub_f32_e32 v109, v109, v150
	v_sub_f32_e32 v110, v110, v150
	v_sub_f32_e32 v111, v111, v150
	v_sub_f32_e32 v112, v112, v150
	v_sub_f32_e32 v113, v113, v150
	v_mul_f32_e32 v236, v236, v151
	s_mov_b64 s[96:97], exec
	s_and_b64 exec, exec, s[8:9]
	ds_write_b32 v235, v151
	s_mov_b64 exec, s[96:97]
	v_lshl_add_u32 v2, v228, 4, s47
	ds_read_b128 v[154:157], v2 offset:0
	s_waitcnt lgkmcnt(0)
	v_mul_f32_e32 v34, v34, v154
	v_mul_f32_e32 v50, v50, v154
	v_mul_f32_e32 v35, v35, v155
	v_mul_f32_e32 v51, v51, v155
	v_mul_f32_e32 v36, v36, v156
	v_mul_f32_e32 v52, v52, v156
	v_mul_f32_e32 v37, v37, v157
	v_mul_f32_e32 v53, v53, v157
	ds_read_b128 v[154:157], v2 offset:32
	s_waitcnt lgkmcnt(0)
	v_mul_f32_e32 v38, v38, v154
	v_mul_f32_e32 v54, v54, v154
	v_mul_f32_e32 v39, v39, v155
	v_mul_f32_e32 v55, v55, v155
	v_mul_f32_e32 v40, v40, v156
	v_mul_f32_e32 v56, v56, v156
	v_mul_f32_e32 v41, v41, v157
	v_mul_f32_e32 v57, v57, v157
	ds_read_b128 v[154:157], v2 offset:64
	s_waitcnt lgkmcnt(0)
	v_mul_f32_e32 v42, v42, v154
	v_mul_f32_e32 v58, v58, v154
	v_mul_f32_e32 v43, v43, v155
	v_mul_f32_e32 v59, v59, v155
	v_mul_f32_e32 v44, v44, v156
	v_mul_f32_e32 v60, v60, v156
	v_mul_f32_e32 v45, v45, v157
	v_mul_f32_e32 v61, v61, v157
	ds_read_b128 v[154:157], v2 offset:96
	s_waitcnt lgkmcnt(0)
	v_mul_f32_e32 v46, v46, v154
	v_mul_f32_e32 v62, v62, v154
	v_mul_f32_e32 v47, v47, v155
	v_mul_f32_e32 v63, v63, v155
	v_mul_f32_e32 v48, v48, v156
	v_mul_f32_e32 v64, v64, v156
	v_mul_f32_e32 v49, v49, v157
	v_mul_f32_e32 v65, v65, v157
.Lmy_nors_37:
	s_waitcnt lgkmcnt(0)
	v_add_u32_e32 v2, 0x4000, v237
	v_mfma_f32_32x32x16_bf16 v[142:157], v[218:221], v[4:7], v[66:81]
	v_exp_f32_e32 v82, v82
	v_exp_f32_e32 v83, v83
	v_exp_f32_e32 v84, v84
	v_add_f32_e32 v27, v82, v83
	v_exp_f32_e32 v85, v85
	v_mfma_f32_32x32x16_bf16 v[158:173], v[214:217], v[4:7], v[66:81]
	v_exp_f32_e32 v86, v86
	v_add_f32_e32 v27, v27, v84
	v_exp_f32_e32 v87, v87
	v_add_f32_e32 v27, v27, v85
	v_exp_f32_e32 v88, v88
	v_mfma_f32_32x32x16_bf16 v[142:157], v[210:213], v[8:11], v[142:157]
	v_add_f32_e32 v27, v27, v86
	v_exp_f32_e32 v89, v89
	v_add_f32_e32 v27, v27, v87
	v_add_f32_e32 v27, v27, v88
	v_add_f32_e32 v27, v27, v89
	v_mfma_f32_32x32x16_bf16 v[158:173], v[206:209], v[8:11], v[158:173]
	v_cvt_pk_bf16_f32 v82, v82, v83
	v_cvt_pk_bf16_f32 v83, v84, v85
	v_cvt_pk_bf16_f32 v84, v86, v87
	v_cvt_pk_bf16_f32 v85, v88, v89
	v_mfma_f32_32x32x16_bf16 v[142:157], v[202:205], v[12:15], v[142:157]
	v_exp_f32_e32 v90, v90
	v_exp_f32_e32 v91, v91
	v_exp_f32_e32 v92, v92
	v_add_f32_e32 v27, v27, v90
	v_exp_f32_e32 v93, v93
	v_mfma_f32_32x32x16_bf16 v[158:173], v[198:201], v[12:15], v[158:173]
	v_add_f32_e32 v27, v27, v91
	v_exp_f32_e32 v94, v94
	v_add_f32_e32 v27, v27, v92
	v_exp_f32_e32 v95, v95
	v_add_f32_e32 v27, v27, v93
	s_waitcnt vmcnt(4)
	s_barrier
	v_mfma_f32_32x32x16_bf16 v[142:157], v[194:197], v[130:133], v[142:157]
	s_add_u32 m0, s57, 0x2000
	v_exp_f32_e32 v96, v96
	v_add_f32_e32 v27, v27, v94
	global_load_lds_dwordx4 v[28:29], off
	v_lshl_add_u64 v[28:29], v[28:29], 0, s[30:31]
	v_exp_f32_e32 v97, v97
	v_add_f32_e32 v27, v27, v95
	v_add_f32_e32 v27, v27, v96
	ds_read_b64_tr_b16 v[114:115], v2 offset:49152
	ds_read_b64_tr_b16 v[116:117], v2 offset:49664
	ds_read_b64_tr_b16 v[118:119], v2 offset:50176
	ds_read_b64_tr_b16 v[120:121], v2 offset:50688
	v_mfma_f32_32x32x16_bf16 v[158:173], v[190:193], v[130:133], v[158:173]
	s_add_u32 m0, s40, 0x9000
	v_add_f32_e32 v27, v27, v97
	v_cvt_pk_bf16_f32 v90, v90, v91
	global_load_lds_dwordx4 v[24:25], off
	v_lshl_add_u64 v[24:25], v[24:25], 0, s[30:31]
	v_cvt_pk_bf16_f32 v91, v92, v93
	v_cvt_pk_bf16_f32 v92, v94, v95
	v_cvt_pk_bf16_f32 v93, v96, v97
	ds_read_b64_tr_b16 v[122:123], v2 offset:51200
	ds_read_b64_tr_b16 v[124:125], v2 offset:51712
	ds_read_b64_tr_b16 v[126:127], v2 offset:52224
	ds_read_b64_tr_b16 v[128:129], v2 offset:52736
	v_mfma_f32_32x32x16_bf16 v[142:157], v[186:189], v[134:137], v[142:157]
	v_exp_f32_e32 v98, v98
	v_exp_f32_e32 v99, v99
	v_exp_f32_e32 v100, v100
	v_add_f32_e32 v27, v27, v98
	v_exp_f32_e32 v101, v101
	ds_read_b64_tr_b16 v[240:241], v2 offset:53248
	ds_read_b64_tr_b16 v[242:243], v2 offset:53760
	ds_read_b64_tr_b16 v[244:245], v2 offset:54272
	ds_read_b64_tr_b16 v[246:247], v2 offset:54784
	v_mfma_f32_32x32x16_bf16 v[158:173], v[182:185], v[134:137], v[158:173]
	v_add_f32_e32 v27, v27, v99
	v_exp_f32_e32 v102, v102
	v_add_f32_e32 v27, v27, v100
	v_exp_f32_e32 v103, v103
	v_add_f32_e32 v27, v27, v101
	ds_read_b64_tr_b16 v[248:249], v2 offset:55296
	ds_read_b64_tr_b16 v[250:251], v2 offset:55808
	ds_read_b64_tr_b16 v[20:21], v2 offset:56320
	ds_read_b64_tr_b16 v[22:23], v2 offset:56832
	v_mfma_f32_32x32x16_bf16 v[142:157], v[178:181], v[138:141], v[142:157]
	v_exp_f32_e32 v104, v104
	v_add_f32_e32 v27, v27, v102
	v_exp_f32_e32 v105, v105
	v_add_f32_e32 v27, v27, v103
	v_add_f32_e32 v27, v27, v104
	v_mfma_f32_32x32x16_bf16 v[158:173], v[174:177], v[138:141], v[158:173]
	v_add_f32_e32 v27, v27, v105
	v_cvt_pk_bf16_f32 v98, v98, v99
	v_cvt_pk_bf16_f32 v99, v100, v101
	v_cvt_pk_bf16_f32 v100, v102, v103
	v_cvt_pk_bf16_f32 v101, v104, v105
	s_waitcnt lgkmcnt(0)
	v_mov_b32_e32 v2, v238
	v_mfma_f32_32x32x16_bf16 v[34:49], v[82:85], v[114:117], v[34:49]
	v_exp_f32_e32 v106, v106
	v_exp_f32_e32 v107, v107
	v_exp_f32_e32 v108, v108
	v_add_f32_e32 v27, v27, v106
	v_exp_f32_e32 v109, v109
	ds_read_b128 v[218:221], v2
	ds_read_b128 v[214:217], v2 offset:512
	ds_read_b128 v[210:213], v2 offset:2048
	v_mfma_f32_32x32x16_bf16 v[50:65], v[82:85], v[240:243], v[50:65]
	v_add_f32_e32 v27, v27, v107
	v_exp_f32_e32 v110, v110
	v_add_f32_e32 v27, v27, v108
	v_exp_f32_e32 v111, v111
	v_add_f32_e32 v27, v27, v109
	ds_read_b128 v[206:209], v2 offset:2560
	ds_read_b128 v[202:205], v2 offset:4096
	ds_read_b128 v[198:201], v2 offset:4608
	v_mfma_f32_32x32x16_bf16 v[34:49], v[90:93], v[118:121], v[34:49]
	v_exp_f32_e32 v112, v112
	v_add_f32_e32 v27, v27, v110
	v_exp_f32_e32 v113, v113
	v_add_f32_e32 v27, v27, v111
	v_add_f32_e32 v27, v27, v112
	ds_read_b128 v[194:197], v2 offset:6144
	ds_read_b128 v[190:193], v2 offset:6656
	ds_read_b128 v[186:189], v2 offset:8192
	v_mfma_f32_32x32x16_bf16 v[50:65], v[90:93], v[244:247], v[50:65]
	v_add_f32_e32 v27, v27, v113
	v_cvt_pk_bf16_f32 v106, v106, v107
	v_cvt_pk_bf16_f32 v107, v108, v109
	v_cvt_pk_bf16_f32 v108, v110, v111
	v_cvt_pk_bf16_f32 v109, v112, v113
	v_add_f32_e32 v236, v236, v27
	ds_read_b128 v[182:185], v2 offset:8704
	ds_read_b128 v[178:181], v2 offset:10240
	ds_read_b128 v[174:177], v2 offset:10752
	v_mfma_f32_32x32x16_bf16 v[34:49], v[98:101], v[122:125], v[34:49]
	v_max3_f32 v19, v142, v143, v144
	v_max3_f32 v26, v145, v146, v147
	v_max3_f32 v19, v19, v148, v149
	v_max3_f32 v26, v26, v150, v151
	v_mfma_f32_32x32x16_bf16 v[50:65], v[98:101], v[248:251], v[50:65]
	v_max3_f32 v19, v19, v152, v153
	v_max3_f32 v26, v26, v154, v155
	v_max3_f32 v19, v19, v156, v157
	v_max3_f32 v26, v26, v158, v159
	v_mfma_f32_32x32x16_bf16 v[34:49], v[106:109], v[126:129], v[34:49]
	v_max3_f32 v19, v19, v160, v161
	v_max3_f32 v26, v26, v162, v163
	v_max3_f32 v19, v19, v164, v165
	v_max3_f32 v26, v26, v166, v167
	v_mfma_f32_32x32x16_bf16 v[50:65], v[106:109], v[20:23], v[50:65]
	v_max3_f32 v19, v19, v168, v169
	v_max3_f32 v26, v26, v170, v171
	v_max3_f32 v19, v19, v172, v173
	v_max_f32_e32 v19, v19, v26
	v_cmp_lt_f32_e32 vcc, s41, v19
	s_cbranch_vccz .Lmy_nors_38
	s_nop 15
	s_nop 15
	v_mov_b32_e32 v26, v19
	s_nop 1
	v_permlane32_swap_b32_e32 v19, v26
	v_max_f32_e32 v19, v19, v26
	v_max_f32_e32 v19, v19, v19
	v_max_f32_e32 v90, 0, v19
	v_exp_f32_e64 v91, -v90
	v_add_f32_e32 v239, v239, v90
	v_xor_b32_e32 v66, 0x80000000, v239
	v_mov_b32_e32 v67, v66
	v_mov_b32_e32 v68, v66
	v_mov_b32_e32 v69, v66
	v_mov_b32_e32 v70, v66
	v_mov_b32_e32 v71, v66
	v_mov_b32_e32 v72, v66
	v_mov_b32_e32 v73, v66
	v_mov_b32_e32 v74, v66
	v_mov_b32_e32 v75, v66
	v_mov_b32_e32 v76, v66
	v_mov_b32_e32 v77, v66
	v_mov_b32_e32 v78, v66
	v_mov_b32_e32 v79, v66
	v_mov_b32_e32 v80, v66
	v_mov_b32_e32 v81, v66
	v_sub_f32_e32 v142, v142, v90
	v_sub_f32_e32 v143, v143, v90
	v_sub_f32_e32 v144, v144, v90
	v_sub_f32_e32 v145, v145, v90
	v_sub_f32_e32 v146, v146, v90
	v_sub_f32_e32 v147, v147, v90
	v_sub_f32_e32 v148, v148, v90
	v_sub_f32_e32 v149, v149, v90
	v_sub_f32_e32 v150, v150, v90
	v_sub_f32_e32 v151, v151, v90
	v_sub_f32_e32 v152, v152, v90
	v_sub_f32_e32 v153, v153, v90
	v_sub_f32_e32 v154, v154, v90
	v_sub_f32_e32 v155, v155, v90
	v_sub_f32_e32 v156, v156, v90
	v_sub_f32_e32 v157, v157, v90
	v_sub_f32_e32 v158, v158, v90
	v_sub_f32_e32 v159, v159, v90
	v_sub_f32_e32 v160, v160, v90
	v_sub_f32_e32 v161, v161, v90
	v_sub_f32_e32 v162, v162, v90
	v_sub_f32_e32 v163, v163, v90
	v_sub_f32_e32 v164, v164, v90
	v_sub_f32_e32 v165, v165, v90
	v_sub_f32_e32 v166, v166, v90
	v_sub_f32_e32 v167, v167, v90
	v_sub_f32_e32 v168, v168, v90
	v_sub_f32_e32 v169, v169, v90
	v_sub_f32_e32 v170, v170, v90
	v_sub_f32_e32 v171, v171, v90
	v_sub_f32_e32 v172, v172, v90
	v_sub_f32_e32 v173, v173, v90
	v_mul_f32_e32 v236, v236, v91
	s_mov_b64 s[96:97], exec
	s_and_b64 exec, exec, s[8:9]
	ds_write_b32 v235, v91
	s_mov_b64 exec, s[96:97]
	v_lshl_add_u32 v2, v228, 4, s47
	ds_read_b128 v[94:97], v2 offset:0
	s_waitcnt lgkmcnt(0)
	v_mul_f32_e32 v34, v34, v94
	v_mul_f32_e32 v50, v50, v94
	v_mul_f32_e32 v35, v35, v95
	v_mul_f32_e32 v51, v51, v95
	v_mul_f32_e32 v36, v36, v96
	v_mul_f32_e32 v52, v52, v96
	v_mul_f32_e32 v37, v37, v97
	v_mul_f32_e32 v53, v53, v97
	ds_read_b128 v[94:97], v2 offset:32
	s_waitcnt lgkmcnt(0)
	v_mul_f32_e32 v38, v38, v94
	v_mul_f32_e32 v54, v54, v94
	v_mul_f32_e32 v39, v39, v95
	v_mul_f32_e32 v55, v55, v95
	v_mul_f32_e32 v40, v40, v96
	v_mul_f32_e32 v56, v56, v96
	v_mul_f32_e32 v41, v41, v97
	v_mul_f32_e32 v57, v57, v97
	ds_read_b128 v[94:97], v2 offset:64
	s_waitcnt lgkmcnt(0)
	v_mul_f32_e32 v42, v42, v94
	v_mul_f32_e32 v58, v58, v94
	v_mul_f32_e32 v43, v43, v95
	v_mul_f32_e32 v59, v59, v95
	v_mul_f32_e32 v44, v44, v96
	v_mul_f32_e32 v60, v60, v96
	v_mul_f32_e32 v45, v45, v97
	v_mul_f32_e32 v61, v61, v97
	ds_read_b128 v[94:97], v2 offset:96
	s_waitcnt lgkmcnt(0)
	v_mul_f32_e32 v46, v46, v94
	v_mul_f32_e32 v62, v62, v94
	v_mul_f32_e32 v47, v47, v95
	v_mul_f32_e32 v63, v63, v95
	v_mul_f32_e32 v48, v48, v96
	v_mul_f32_e32 v64, v64, v96
	v_mul_f32_e32 v49, v49, v97
	v_mul_f32_e32 v65, v65, v97

.Lmy_ts_42:
	s_waitcnt lgkmcnt(0)
	s_waitcnt vmcnt(2)
	s_barrier
	s_add_u32 m0, s57, 0x6000
	s_nop 0
	global_load_lds_dwordx4 v[28:29], off
	v_lshl_add_u64 v[28:29], v[28:29], 0, s[30:31]
	v_mov_b32_e32 v2, v237
	ds_read_b64_tr_b16 v[114:115], v2 offset:49152
	ds_read_b64_tr_b16 v[116:117], v2 offset:49664
	ds_read_b64_tr_b16 v[118:119], v2 offset:50176
	ds_read_b64_tr_b16 v[120:121], v2 offset:50688
	ds_read_b64_tr_b16 v[122:123], v2 offset:51200
	ds_read_b64_tr_b16 v[124:125], v2 offset:51712
	ds_read_b64_tr_b16 v[126:127], v2 offset:52224
	ds_read_b64_tr_b16 v[128:129], v2 offset:52736
	ds_read_b64_tr_b16 v[240:241], v2 offset:53248
	ds_read_b64_tr_b16 v[242:243], v2 offset:53760
	ds_read_b64_tr_b16 v[244:245], v2 offset:54272
	ds_read_b64_tr_b16 v[246:247], v2 offset:54784
	ds_read_b64_tr_b16 v[248:249], v2 offset:55296
	ds_read_b64_tr_b16 v[250:251], v2 offset:55808
	ds_read_b64_tr_b16 v[20:21], v2 offset:56320
	ds_read_b64_tr_b16 v[22:23], v2 offset:56832
	v_exp_f32_e32 v82, v82
	v_exp_f32_e32 v83, v83
	v_exp_f32_e32 v84, v84
	v_add_f32_e32 v27, v82, v83
	v_exp_f32_e32 v85, v85
	v_exp_f32_e32 v86, v86
	v_add_f32_e32 v27, v27, v84
	v_exp_f32_e32 v87, v87
	v_add_f32_e32 v27, v27, v85
	v_exp_f32_e32 v88, v88
	v_add_f32_e32 v27, v27, v86
	v_exp_f32_e32 v89, v89
	v_add_f32_e32 v27, v27, v87
	v_add_f32_e32 v27, v27, v88
	v_add_f32_e32 v27, v27, v89
	v_cvt_pk_bf16_f32 v82, v82, v83
	v_cvt_pk_bf16_f32 v83, v84, v85
	v_cvt_pk_bf16_f32 v84, v86, v87
	v_cvt_pk_bf16_f32 v85, v88, v89
	v_exp_f32_e32 v90, v90
	v_exp_f32_e32 v91, v91
	v_exp_f32_e32 v92, v92
	v_add_f32_e32 v27, v27, v90
	v_exp_f32_e32 v93, v93
	v_add_f32_e32 v27, v27, v91
	v_exp_f32_e32 v94, v94
	v_add_f32_e32 v27, v27, v92
	v_exp_f32_e32 v95, v95
	v_add_f32_e32 v27, v27, v93
	v_exp_f32_e32 v96, v96
	v_add_f32_e32 v27, v27, v94
	v_exp_f32_e32 v97, v97
	v_add_f32_e32 v27, v27, v95
	v_add_f32_e32 v27, v27, v96
	v_add_f32_e32 v27, v27, v97
	v_cvt_pk_bf16_f32 v90, v90, v91
	v_cvt_pk_bf16_f32 v91, v92, v93
	v_cvt_pk_bf16_f32 v92, v94, v95
	v_cvt_pk_bf16_f32 v93, v96, v97
	s_waitcnt lgkmcnt(0)
	v_mfma_f32_32x32x16_bf16 v[34:49], v[82:85], v[114:117], v[34:49]
	v_mfma_f32_32x32x16_bf16 v[50:65], v[82:85], v[240:243], v[50:65]
	v_exp_f32_e32 v98, v98
	v_exp_f32_e32 v99, v99
	v_exp_f32_e32 v100, v100
	v_add_f32_e32 v27, v27, v98
	v_exp_f32_e32 v101, v101
	v_add_f32_e32 v27, v27, v99
	v_exp_f32_e32 v102, v102
	v_add_f32_e32 v27, v27, v100
	v_exp_f32_e32 v103, v103
	v_add_f32_e32 v27, v27, v101
	v_exp_f32_e32 v104, v104
	v_add_f32_e32 v27, v27, v102
	v_exp_f32_e32 v105, v105
	v_add_f32_e32 v27, v27, v103
	v_add_f32_e32 v27, v27, v104
	v_add_f32_e32 v27, v27, v105
	v_cvt_pk_bf16_f32 v98, v98, v99
	v_cvt_pk_bf16_f32 v99, v100, v101
	v_cvt_pk_bf16_f32 v100, v102, v103
	v_cvt_pk_bf16_f32 v101, v104, v105
	v_mfma_f32_32x32x16_bf16 v[34:49], v[90:93], v[118:121], v[34:49]
	v_mfma_f32_32x32x16_bf16 v[50:65], v[90:93], v[244:247], v[50:65]
	v_exp_f32_e32 v106, v106
	v_exp_f32_e32 v107, v107
	v_exp_f32_e32 v108, v108
	v_add_f32_e32 v27, v27, v106
	v_exp_f32_e32 v109, v109
	v_add_f32_e32 v27, v27, v107
	v_exp_f32_e32 v110, v110
	v_add_f32_e32 v27, v27, v108
	v_exp_f32_e32 v111, v111
	v_add_f32_e32 v27, v27, v109
	v_exp_f32_e32 v112, v112
	v_add_f32_e32 v27, v27, v110
	v_exp_f32_e32 v113, v113
	v_add_f32_e32 v27, v27, v111
	v_add_f32_e32 v27, v27, v112
	v_add_f32_e32 v27, v27, v113
	v_cvt_pk_bf16_f32 v106, v106, v107
	v_cvt_pk_bf16_f32 v107, v108, v109
	v_cvt_pk_bf16_f32 v108, v110, v111
	v_cvt_pk_bf16_f32 v109, v112, v113
	v_add_f32_e32 v236, v236, v27
	s_nop 1
	v_mfma_f32_32x32x16_bf16 v[34:49], v[98:101], v[122:125], v[34:49]
	v_mfma_f32_32x32x16_bf16 v[50:65], v[98:101], v[248:251], v[50:65]
	v_mfma_f32_32x32x16_bf16 v[34:49], v[106:109], v[126:129], v[34:49]
	v_mfma_f32_32x32x16_bf16 v[50:65], v[106:109], v[20:23], v[50:65]
	s_branch .Lmy_te_43
.Lmy_tf_41:
	s_waitcnt lgkmcnt(0)
	v_mov_b32_e32 v2, v237
	v_mfma_f32_32x32x16_bf16 v[142:157], v[218:221], v[4:7], v[66:81]
	v_exp_f32_e32 v82, v82
	v_exp_f32_e32 v83, v83
	v_exp_f32_e32 v84, v84
	v_add_f32_e32 v27, v82, v83
	v_exp_f32_e32 v85, v85
	v_mfma_f32_32x32x16_bf16 v[158:173], v[214:217], v[4:7], v[66:81]
	v_exp_f32_e32 v86, v86
	v_add_f32_e32 v27, v27, v84
	v_exp_f32_e32 v87, v87
	v_add_f32_e32 v27, v27, v85
	v_exp_f32_e32 v88, v88
	v_mfma_f32_32x32x16_bf16 v[142:157], v[210:213], v[8:11], v[142:157]
	v_add_f32_e32 v27, v27, v86
	v_exp_f32_e32 v89, v89
	v_add_f32_e32 v27, v27, v87
	v_add_f32_e32 v27, v27, v88
	v_add_f32_e32 v27, v27, v89
	v_mfma_f32_32x32x16_bf16 v[158:173], v[206:209], v[8:11], v[158:173]
	v_cvt_pk_bf16_f32 v82, v82, v83
	v_cvt_pk_bf16_f32 v83, v84, v85
	v_cvt_pk_bf16_f32 v84, v86, v87
	v_cvt_pk_bf16_f32 v85, v88, v89
	v_mfma_f32_32x32x16_bf16 v[142:157], v[202:205], v[12:15], v[142:157]
	v_exp_f32_e32 v90, v90
	v_exp_f32_e32 v91, v91
	v_exp_f32_e32 v92, v92
	v_add_f32_e32 v27, v27, v90
	v_exp_f32_e32 v93, v93
	v_mfma_f32_32x32x16_bf16 v[158:173], v[198:201], v[12:15], v[158:173]
	v_add_f32_e32 v27, v27, v91
	v_exp_f32_e32 v94, v94
	v_add_f32_e32 v27, v27, v92
	v_exp_f32_e32 v95, v95
	v_add_f32_e32 v27, v27, v93
	s_waitcnt vmcnt(2)
	s_barrier
	v_mfma_f32_32x32x16_bf16 v[142:157], v[194:197], v[130:133], v[142:157]
	s_add_u32 m0, s57, 0x6000
	v_exp_f32_e32 v96, v96
	v_add_f32_e32 v27, v27, v94
	global_load_lds_dwordx4 v[28:29], off
	v_lshl_add_u64 v[28:29], v[28:29], 0, s[30:31]
	v_exp_f32_e32 v97, v97
	v_add_f32_e32 v27, v27, v95
	v_add_f32_e32 v27, v27, v96
	ds_read_b64_tr_b16 v[114:115], v2 offset:49152
	ds_read_b64_tr_b16 v[116:117], v2 offset:49664
	ds_read_b64_tr_b16 v[118:119], v2 offset:50176
	ds_read_b64_tr_b16 v[120:121], v2 offset:50688
	v_mfma_f32_32x32x16_bf16 v[158:173], v[190:193], v[130:133], v[158:173]
	v_add_f32_e32 v27, v27, v97
	v_cvt_pk_bf16_f32 v90, v90, v91
	v_cvt_pk_bf16_f32 v91, v92, v93
	v_cvt_pk_bf16_f32 v92, v94, v95
	v_cvt_pk_bf16_f32 v93, v96, v97
	ds_read_b64_tr_b16 v[122:123], v2 offset:51200
	ds_read_b64_tr_b16 v[124:125], v2 offset:51712
	ds_read_b64_tr_b16 v[126:127], v2 offset:52224
	ds_read_b64_tr_b16 v[128:129], v2 offset:52736
	v_mfma_f32_32x32x16_bf16 v[142:157], v[186:189], v[134:137], v[142:157]
	v_exp_f32_e32 v98, v98
	v_exp_f32_e32 v99, v99
	v_exp_f32_e32 v100, v100
	v_add_f32_e32 v27, v27, v98
	v_exp_f32_e32 v101, v101
	ds_read_b64_tr_b16 v[240:241], v2 offset:53248
	ds_read_b64_tr_b16 v[242:243], v2 offset:53760
	ds_read_b64_tr_b16 v[244:245], v2 offset:54272
	ds_read_b64_tr_b16 v[246:247], v2 offset:54784
	v_mfma_f32_32x32x16_bf16 v[158:173], v[182:185], v[134:137], v[158:173]
	v_add_f32_e32 v27, v27, v99
	v_exp_f32_e32 v102, v102
	v_add_f32_e32 v27, v27, v100
	v_exp_f32_e32 v103, v103
	v_add_f32_e32 v27, v27, v101
	ds_read_b64_tr_b16 v[248:249], v2 offset:55296
	ds_read_b64_tr_b16 v[250:251], v2 offset:55808
	ds_read_b64_tr_b16 v[20:21], v2 offset:56320
	ds_read_b64_tr_b16 v[22:23], v2 offset:56832
	v_mfma_f32_32x32x16_bf16 v[142:157], v[178:181], v[138:141], v[142:157]
	v_exp_f32_e32 v104, v104
	v_add_f32_e32 v27, v27, v102
	v_exp_f32_e32 v105, v105
	v_add_f32_e32 v27, v27, v103
	v_add_f32_e32 v27, v27, v104
	v_mfma_f32_32x32x16_bf16 v[158:173], v[174:177], v[138:141], v[158:173]
	v_add_f32_e32 v27, v27, v105
	v_cvt_pk_bf16_f32 v98, v98, v99
	v_cvt_pk_bf16_f32 v99, v100, v101
	v_cvt_pk_bf16_f32 v100, v102, v103
	v_cvt_pk_bf16_f32 v101, v104, v105
	s_waitcnt lgkmcnt(0)
	v_add_u32_e32 v2, 0x6000, v238
	v_mfma_f32_32x32x16_bf16 v[34:49], v[82:85], v[114:117], v[34:49]
	v_exp_f32_e32 v106, v106
	v_exp_f32_e32 v107, v107
	v_exp_f32_e32 v108, v108
	v_add_f32_e32 v27, v27, v106
	v_exp_f32_e32 v109, v109
	s_cmp_gt_u32 s71, 1
	s_cbranch_scc0 .Lmy_nok_44
	ds_read_b128 v[218:221], v2
	ds_read_b128 v[214:217], v2 offset:512
	ds_read_b128 v[210:213], v2 offset:2048
	ds_read_b128 v[206:209], v2 offset:2560
	ds_read_b128 v[202:205], v2 offset:4096
	ds_read_b128 v[198:201], v2 offset:4608
	ds_read_b128 v[194:197], v2 offset:6144
	ds_read_b128 v[190:193], v2 offset:6656
	ds_read_b128 v[186:189], v2 offset:8192
	ds_read_b128 v[182:185], v2 offset:8704
	ds_read_b128 v[178:181], v2 offset:10240
	ds_read_b128 v[174:177], v2 offset:10752
